# RES epilogues: round-1 residual/gate loads issued together with round 0 into dead fragment registers (one store-bound wait less per tile)
# speedup vs baseline: 1.0088x; 1.0011x over previous
.LBB0_707:
	s_add_i32 s58, s64, 0xffffe000
	s_lshr_b32 s58, s58, 12
	s_mulk_i32 s58, 0x1800
	s_addk_i32 s58, 0x1800
	s_cmp_gt_i32 s6, 63
	s_cselect_b32 s6, s58, 0
	s_lshl_b64 s[58:59], s[6:7], 2
	v_mov_b32_e32 v70, s68
	s_add_u32 s6, s14, s58
	ds_read_b64 v[70:71], v70
	s_addc_u32 s63, s15, s59
	s_lshl_b32 s58, s69, 14
	s_add_i32 s58, s58, 0x20000
	s_ashr_i32 s59, s58, 31
	s_lshl_b64 s[58:59], s[58:59], 2
	s_add_u32 s58, s10, s58
	s_waitcnt lgkmcnt(0)
	v_readfirstlane_b32 s70, v70
	s_addc_u32 s59, s11, s59
	v_add_u32_e32 v70, s64, v141
	s_add_u32 s60, s6, 0x5ba2000
	v_lshlrev_b32_e32 v190, 10, v70
	s_addc_u32 s61, s63, 0
	v_or_b32_e32 v102, s66, v140
	v_or_b32_e32 v188, 0x400, v190
	v_or_b32_e32 v187, 0x4400, v190
	v_or_b32_e32 v191, 0x4c00, v190
	v_or_b32_e32 v195, 0x6c00, v190
	v_readfirstlane_b32 s71, v71
	s_add_u32 s62, s6, 0x5ba4000
	v_ashrrev_i32_e32 v103, 31, v102
	v_add_u32_e32 v134, v190, v102
	v_add_u32_e32 v136, v188, v102
	v_or_b32_e32 v186, 0x800, v190
	v_or_b32_e32 v185, 0xc00, v190
	v_or_b32_e32 v183, 0x2000, v190
	v_or_b32_e32 v181, 0x2400, v190
	v_or_b32_e32 v71, 0x2800, v190
	v_or_b32_e32 v182, 0x2c00, v190
	v_or_b32_e32 v184, 0x4000, v190
	v_add_u32_e32 v114, v187, v102
	v_or_b32_e32 v189, 0x4800, v190
	v_add_u32_e32 v120, v191, v102
	v_or_b32_e32 v192, 0x6000, v190
	v_or_b32_e32 v193, 0x6400, v190
	v_or_b32_e32 v194, 0x6800, v190
	v_add_u32_e32 v130, v195, v102
	s_addc_u32 s63, s63, 0
	v_lshlrev_b64 v[72:73], 2, v[102:103]
	v_ashrrev_i32_e32 v137, 31, v136
	v_add_u32_e32 v138, v186, v102
	v_add_u32_e32 v132, v185, v102
	v_add_u32_e32 v124, v183, v102
	v_add_u32_e32 v116, v181, v102
	v_add_u32_e32 v108, v71, v102
	v_add_u32_e32 v110, v182, v102
	v_add_u32_e32 v112, v184, v102
	v_ashrrev_i32_e32 v115, 31, v114
	v_add_u32_e32 v118, v189, v102
	v_ashrrev_i32_e32 v121, 31, v120
	v_add_u32_e32 v122, v192, v102
	v_add_u32_e32 v126, v193, v102
	v_add_u32_e32 v128, v194, v102
	v_ashrrev_i32_e32 v131, 31, v130
	v_ashrrev_i32_e32 v135, 31, v134
	v_lshl_add_u64 v[74:75], s[60:61], 0, v[72:73]
	v_lshl_add_u64 v[104:105], s[70:71], 0, v[72:73]
	v_lshl_add_u64 v[72:73], s[62:63], 0, v[72:73]
	v_lshl_add_u64 v[88:89], v[136:137], 2, s[12:13]
	v_ashrrev_i32_e32 v139, 31, v138
	v_ashrrev_i32_e32 v133, 31, v132
	v_ashrrev_i32_e32 v125, 31, v124
	v_ashrrev_i32_e32 v117, 31, v116
	v_ashrrev_i32_e32 v109, 31, v108
	v_ashrrev_i32_e32 v111, 31, v110
	v_ashrrev_i32_e32 v113, 31, v112
	v_lshl_add_u64 v[86:87], v[114:115], 2, s[12:13]
	v_ashrrev_i32_e32 v119, 31, v118
	v_lshl_add_u64 v[92:93], v[120:121], 2, s[12:13]
	v_ashrrev_i32_e32 v123, 31, v122
	v_ashrrev_i32_e32 v127, 31, v126
	v_ashrrev_i32_e32 v129, 31, v128
	v_lshl_add_u64 v[100:101], v[130:131], 2, s[12:13]
	v_lshl_add_u64 v[106:107], v[134:135], 2, s[12:13]
	global_load_dword v196, v[74:75], off
	global_load_dword v207, v[74:75], off offset:128
	global_load_dword v198, v[72:73], off
	global_load_dword v208, v[72:73], off offset:128
	global_load_dword v197, v[104:105], off
	v_lshl_add_u64 v[84:85], v[138:139], 2, s[12:13]
	v_lshl_add_u64 v[82:83], v[132:133], 2, s[12:13]
	v_lshl_add_u64 v[78:79], v[124:125], 2, s[12:13]
	v_lshl_add_u64 v[72:73], v[116:117], 2, s[12:13]
	v_lshl_add_u64 v[74:75], v[108:109], 2, s[12:13]
	v_lshl_add_u64 v[76:77], v[110:111], 2, s[12:13]
	v_lshl_add_u64 v[80:81], v[112:113], 2, s[12:13]
	global_load_dword v180, v[88:89], off
	global_load_dword v179, v[84:85], off
	global_load_dword v178, v[82:83], off
	global_load_dword v177, v[78:79], off
	global_load_dword v176, v[72:73], off
	global_load_dword v175, v[74:75], off
	global_load_dword v174, v[76:77], off
	global_load_dword v173, v[80:81], off
	v_lshl_add_u64 v[90:91], v[118:119], 2, s[12:13]
	global_load_dword v172, v[86:87], off
	global_load_dword v170, v[90:91], off
	v_lshl_add_u64 v[94:95], v[122:123], 2, s[12:13]
	v_lshl_add_u64 v[96:97], v[126:127], 2, s[12:13]
	v_lshl_add_u64 v[98:99], v[128:129], 2, s[12:13]
	global_load_dword v171, v[92:93], off
	global_load_dword v169, v[94:95], off
	global_load_dword v168, v[96:97], off
	global_load_dword v167, v[98:99], off
	global_load_dword v103, v[100:101], off
	global_load_dword v202, v[106:107], off
	v_lshl_add_u64 v[108:109], v[108:109], 1, s[8:9]
	global_load_dword v206, v[106:107], off offset:128
	global_load_dword v209, v[104:105], off offset:128
	global_load_dword v210, v[84:85], off offset:128
	global_load_dword v211, v[78:79], off offset:128
	global_load_dword v212, v[72:73], off offset:128
	global_load_dword v213, v[74:75], off offset:128
	global_load_dword v214, v[80:81], off offset:128
	global_load_dword v215, v[76:77], off offset:128
	global_load_dword v216, v[86:87], off offset:128
	global_load_dword v217, v[82:83], off offset:128
	global_load_dword v218, v[90:91], off offset:128
	global_load_dword v219, v[92:93], off offset:128
	global_load_dword v220, v[94:95], off offset:128
	global_load_dword v221, v[96:97], off offset:128
	global_load_dword v222, v[98:99], off offset:128
	global_load_dword v223, v[100:101], off offset:128
	global_load_dword v224, v[88:89], off offset:128
	s_waitcnt vmcnt(0)
	v_add_f32_e32 v198, 1.0, v198
	v_mul_f32_e32 v197, v197, v198
	v_fmac_f32_e32 v180, v49, v196
	v_fmac_f32_e32 v179, v50, v196
	v_fmac_f32_e32 v178, v51, v196
	v_fmac_f32_e32 v177, v52, v196
	v_fmac_f32_e32 v176, v53, v196
	v_fmac_f32_e32 v175, v54, v196
	v_fmac_f32_e32 v174, v55, v196
	v_fmac_f32_e32 v173, v56, v196
	v_fmac_f32_e32 v172, v57, v196
	v_fmac_f32_e32 v170, v58, v196
	v_fmac_f32_e32 v171, v59, v196
	v_fmac_f32_e32 v169, v60, v196
	v_fmac_f32_e32 v168, v61, v196
	v_fmac_f32_e32 v167, v62, v196
	v_fmac_f32_e32 v103, v63, v196
	v_fmac_f32_e32 v202, v48, v196
	v_or_b32_e32 v48, 32, v102
	v_ashrrev_i32_e32 v49, 31, v48
	v_lshlrev_b64 v[50:51], 2, v[48:49]
	global_store_dword v[88:89], v180, off sc1
	global_store_dword v[84:85], v179, off sc1
	global_store_dword v[82:83], v178, off sc1
	global_store_dword v[78:79], v177, off sc1
	global_store_dword v[72:73], v176, off sc1
	global_store_dword v[74:75], v175, off sc1
	global_store_dword v[76:77], v174, off sc1
	global_store_dword v[80:81], v173, off sc1
	global_store_dword v[86:87], v172, off sc1
	global_store_dword v[90:91], v170, off sc1
	global_store_dword v[92:93], v171, off sc1
	global_store_dword v[94:95], v169, off sc1
	global_store_dword v[96:97], v168, off sc1
	global_store_dword v[98:99], v167, off sc1
	global_store_dword v[100:101], v103, off sc1
	global_store_dword v[106:107], v202, off sc1
	v_mul_f32_e32 v54, v197, v202
	v_lshl_add_u64 v[52:53], s[60:61], 0, v[50:51]
	v_lshl_add_u64 v[50:51], s[62:63], 0, v[50:51]
	v_mov_b32_e32 v198, v206
	v_mov_b32_e32 v196, v207
	v_mov_b32_e32 v203, v208
	v_mov_b32_e32 v204, v209
	v_cvt_pk_bf16_f32 v49, v54, s0
	v_lshl_add_u64 v[50:51], v[134:135], 1, s[8:9]
	global_store_short v[50:51], v49, off sc1
	v_mul_f32_e32 v49, v197, v180
	v_cvt_pk_bf16_f32 v49, v49, s0
	v_lshl_add_u64 v[50:51], v[136:137], 1, s[8:9]
	global_store_short v[50:51], v49, off sc1
	v_mul_f32_e32 v49, v197, v179
	v_cvt_pk_bf16_f32 v49, v49, s0
	v_lshl_add_u64 v[50:51], v[138:139], 1, s[8:9]
	global_store_short v[50:51], v49, off sc1
	v_mul_f32_e32 v49, v197, v178
	v_cvt_pk_bf16_f32 v49, v49, s0
	v_lshl_add_u64 v[50:51], v[132:133], 1, s[8:9]
	global_store_short v[50:51], v49, off sc1
	v_mul_f32_e32 v49, v197, v177
	v_cvt_pk_bf16_f32 v49, v49, s0
	v_lshl_add_u64 v[50:51], v[124:125], 1, s[8:9]
	global_store_short v[50:51], v49, off sc1
	v_mul_f32_e32 v49, v197, v176
	v_cvt_pk_bf16_f32 v49, v49, s0
	v_lshl_add_u64 v[50:51], v[116:117], 1, s[8:9]
	global_store_short v[50:51], v49, off sc1
	v_mul_f32_e32 v49, v197, v175
	v_mov_b32_e32 v62, v210
	v_mov_b32_e32 v60, v211
	v_mov_b32_e32 v59, v212
	v_mov_b32_e32 v58, v213
	v_mov_b32_e32 v56, v214
	v_mov_b32_e32 v57, v215
	v_mov_b32_e32 v55, v216
	v_mov_b32_e32 v61, v217
	v_mov_b32_e32 v54, v218
	v_mov_b32_e32 v53, v219
	v_mov_b32_e32 v52, v220
	v_mov_b32_e32 v51, v221
	v_mov_b32_e32 v50, v222
	v_cvt_pk_bf16_f32 v63, v49, s0
	v_mov_b32_e32 v49, v223
	v_fmac_f32_e32 v198, v32, v196
	global_store_short v[108:109], v63, off sc1
	v_mov_b32_e32 v63, v224
	v_mul_f32_e32 v108, v197, v174
	v_cvt_pk_bf16_f32 v116, v108, s0
	v_lshl_add_u64 v[108:109], v[110:111], 1, s[8:9]
	global_store_short v[108:109], v116, off sc1
	v_mul_f32_e32 v108, v197, v173
	v_cvt_pk_bf16_f32 v110, v108, s0
	v_lshl_add_u64 v[108:109], v[112:113], 1, s[8:9]
	global_store_short v[108:109], v110, off sc1
	v_mul_f32_e32 v108, v197, v172
	v_cvt_pk_bf16_f32 v110, v108, s0
	v_lshl_add_u64 v[108:109], v[114:115], 1, s[8:9]
	global_store_short v[108:109], v110, off sc1
	v_mul_f32_e32 v108, v197, v170
	v_cvt_pk_bf16_f32 v110, v108, s0
	v_lshl_add_u64 v[108:109], v[118:119], 1, s[8:9]
	global_store_short v[108:109], v110, off sc1
	v_mul_f32_e32 v108, v197, v171
	v_cvt_pk_bf16_f32 v110, v108, s0
	v_lshl_add_u64 v[108:109], v[120:121], 1, s[8:9]
	global_store_short v[108:109], v110, off sc1
	v_mul_f32_e32 v108, v197, v169
	v_cvt_pk_bf16_f32 v110, v108, s0
	v_lshl_add_u64 v[108:109], v[122:123], 1, s[8:9]
	global_store_short v[108:109], v110, off sc1
	v_mul_f32_e32 v108, v197, v168
	v_cvt_pk_bf16_f32 v110, v108, s0
	v_lshl_add_u64 v[108:109], v[126:127], 1, s[8:9]
	global_store_short v[108:109], v110, off sc1
	v_mul_f32_e32 v108, v197, v167
	v_cvt_pk_bf16_f32 v110, v108, s0
	v_lshl_add_u64 v[108:109], v[128:129], 1, s[8:9]
	global_store_short v[108:109], v110, off sc1
	v_mul_f32_e32 v108, v197, v103
	v_cvt_pk_bf16_f32 v110, v108, s0
	v_lshl_add_u64 v[108:109], v[130:131], 1, s[8:9]
	global_store_short v[108:109], v110, off sc1
	v_add_f32_e32 v108, 1.0, v203
	v_mul_f32_e32 v112, v204, v108
	v_add_u32_e32 v108, v190, v48
	v_fmac_f32_e32 v62, v34, v196
	v_fmac_f32_e32 v61, v35, v196
	v_fmac_f32_e32 v60, v36, v196
	v_fmac_f32_e32 v59, v37, v196
	v_fmac_f32_e32 v58, v38, v196
	v_fmac_f32_e32 v57, v39, v196
	v_fmac_f32_e32 v56, v40, v196
	v_fmac_f32_e32 v55, v41, v196
	v_fmac_f32_e32 v54, v42, v196
	v_fmac_f32_e32 v53, v43, v196
	v_fmac_f32_e32 v52, v44, v196
	v_fmac_f32_e32 v51, v45, v196
	v_fmac_f32_e32 v50, v46, v196
	v_fmac_f32_e32 v49, v47, v196
	v_ashrrev_i32_e32 v109, 31, v108
	global_store_dword v[106:107], v198, off offset:128 sc1
	v_mul_f32_e32 v32, v112, v198
	global_store_dword v[84:85], v62, off offset:128 sc1
	global_store_dword v[82:83], v61, off offset:128 sc1
	global_store_dword v[78:79], v60, off offset:128 sc1
	global_store_dword v[72:73], v59, off offset:128 sc1
	global_store_dword v[74:75], v58, off offset:128 sc1
	global_store_dword v[76:77], v57, off offset:128 sc1
	global_store_dword v[80:81], v56, off offset:128 sc1
	global_store_dword v[86:87], v55, off offset:128 sc1
	global_store_dword v[90:91], v54, off offset:128 sc1
	global_store_dword v[92:93], v53, off offset:128 sc1
	global_store_dword v[94:95], v52, off offset:128 sc1
	global_store_dword v[96:97], v51, off offset:128 sc1
	global_store_dword v[98:99], v50, off offset:128 sc1
	global_store_dword v[100:101], v49, off offset:128 sc1
	v_cvt_pk_bf16_f32 v32, v32, s0
	v_lshl_add_u64 v[108:109], v[108:109], 1, s[8:9]
	v_add_u32_e32 v110, v188, v48
	global_load_dword v45, v[88:89], off offset:256
	v_ashrrev_i32_e32 v111, 31, v110
	global_store_short v[108:109], v32, off sc1
	v_mul_f32_e32 v40, v112, v59
	v_mul_f32_e32 v115, v112, v56
	v_cvt_pk_bf16_f32 v115, v115, s0
	s_waitcnt vmcnt(26)
	v_fmac_f32_e32 v63, v33, v196
	v_mul_f32_e32 v32, v112, v63
	v_cvt_pk_bf16_f32 v34, v32, s0
	v_lshl_add_u64 v[32:33], v[110:111], 1, s[8:9]
	global_store_short v[32:33], v34, off sc1
	v_add_u32_e32 v32, v186, v48
	v_ashrrev_i32_e32 v33, 31, v32
	v_mul_f32_e32 v34, v112, v62
	v_cvt_pk_bf16_f32 v34, v34, s0
	v_lshl_add_u64 v[32:33], v[32:33], 1, s[8:9]
	global_store_short v[32:33], v34, off sc1
	v_add_u32_e32 v32, v185, v48
	v_ashrrev_i32_e32 v33, 31, v32
	v_mul_f32_e32 v34, v112, v61
	v_cvt_pk_bf16_f32 v34, v34, s0
	v_lshl_add_u64 v[32:33], v[32:33], 1, s[8:9]
	global_store_short v[32:33], v34, off sc1
	v_add_u32_e32 v32, v183, v48
	v_ashrrev_i32_e32 v33, 31, v32
	v_mul_f32_e32 v34, v112, v60
	v_cvt_pk_bf16_f32 v34, v34, s0
	v_lshl_add_u64 v[32:33], v[32:33], 1, s[8:9]
	global_store_short v[32:33], v34, off sc1
	v_or_b32_e32 v32, 64, v102
	v_add_u32_e32 v34, v181, v48
	v_ashrrev_i32_e32 v33, 31, v32
	v_ashrrev_i32_e32 v35, 31, v34
	v_lshlrev_b64 v[36:37], 2, v[32:33]
	global_store_dword v[88:89], v63, off offset:128 sc1
	v_lshl_add_u64 v[38:39], s[60:61], 0, v[36:37]
	v_cvt_pk_bf16_f32 v33, v40, s0
	v_lshl_add_u64 v[34:35], v[34:35], 1, s[8:9]
	v_lshl_add_u64 v[36:37], s[62:63], 0, v[36:37]
	global_load_dword v109, v[38:39], off
	global_load_dword v113, v[36:37], off
	global_load_dword v114, v[104:105], off offset:256
	global_load_dword v116, v[106:107], off offset:256
	global_load_dword v47, v[84:85], off offset:256
	global_load_dword v44, v[78:79], off offset:256
	global_load_dword v39, v[86:87], off offset:256
	global_load_dword v46, v[82:83], off offset:256
	global_load_dword v43, v[72:73], off offset:256
	global_load_dword v42, v[74:75], off offset:256
	global_load_dword v40, v[80:81], off offset:256
	global_load_dword v41, v[76:77], off offset:256
	global_load_dword v38, v[90:91], off offset:256
	global_load_dword v37, v[92:93], off offset:256
	global_load_dword v36, v[94:95], off offset:256
	v_add_u32_e32 v110, v184, v48
	global_store_short v[34:35], v33, off sc1
	v_add_u32_e32 v34, v71, v48
	v_ashrrev_i32_e32 v35, 31, v34
	v_mul_f32_e32 v33, v112, v58
	v_cvt_pk_bf16_f32 v33, v33, s0
	v_lshl_add_u64 v[34:35], v[34:35], 1, s[8:9]
	global_store_short v[34:35], v33, off sc1
	v_add_u32_e32 v34, v182, v48
	v_ashrrev_i32_e32 v35, 31, v34
	v_mul_f32_e32 v33, v112, v57
	v_cvt_pk_bf16_f32 v33, v33, s0
	v_lshl_add_u64 v[34:35], v[34:35], 1, s[8:9]
	global_store_short v[34:35], v33, off sc1
	global_load_dword v35, v[96:97], off offset:256
	v_ashrrev_i32_e32 v111, 31, v110
	global_load_dword v34, v[98:99], off offset:256
	global_load_dword v33, v[100:101], off offset:256
	v_lshl_add_u64 v[110:111], v[110:111], 1, s[8:9]
	global_store_short v[110:111], v115, off sc1
	v_add_u32_e32 v110, v187, v48
	v_ashrrev_i32_e32 v111, 31, v110
	v_mul_f32_e32 v115, v112, v55
	v_cvt_pk_bf16_f32 v115, v115, s0
	v_lshl_add_u64 v[110:111], v[110:111], 1, s[8:9]
	global_store_short v[110:111], v115, off sc1
	v_add_u32_e32 v110, v189, v48
	v_ashrrev_i32_e32 v111, 31, v110
	v_mul_f32_e32 v115, v112, v54
	v_cvt_pk_bf16_f32 v115, v115, s0
	v_lshl_add_u64 v[110:111], v[110:111], 1, s[8:9]
	global_store_short v[110:111], v115, off sc1
	v_add_u32_e32 v110, v191, v48
	v_ashrrev_i32_e32 v111, 31, v110
	v_mul_f32_e32 v115, v112, v53
	v_cvt_pk_bf16_f32 v115, v115, s0
	v_lshl_add_u64 v[110:111], v[110:111], 1, s[8:9]
	global_store_short v[110:111], v115, off sc1
	v_add_u32_e32 v110, v192, v48
	v_ashrrev_i32_e32 v111, 31, v110
	v_mul_f32_e32 v115, v112, v52
	v_cvt_pk_bf16_f32 v115, v115, s0
	v_lshl_add_u64 v[110:111], v[110:111], 1, s[8:9]
	global_store_short v[110:111], v115, off sc1
	v_add_u32_e32 v110, v193, v48
	v_ashrrev_i32_e32 v111, 31, v110
	v_mul_f32_e32 v115, v112, v51
	v_cvt_pk_bf16_f32 v115, v115, s0
	v_lshl_add_u64 v[110:111], v[110:111], 1, s[8:9]
	global_store_short v[110:111], v115, off sc1
	v_add_u32_e32 v110, v194, v48
	v_ashrrev_i32_e32 v111, 31, v110
	v_mul_f32_e32 v115, v112, v50
	v_cvt_pk_bf16_f32 v115, v115, s0
	v_lshl_add_u64 v[110:111], v[110:111], 1, s[8:9]
	global_store_short v[110:111], v115, off sc1
	v_add_u32_e32 v110, v195, v48
	v_ashrrev_i32_e32 v111, 31, v110
	v_mul_f32_e32 v48, v112, v49
	v_cvt_pk_bf16_f32 v48, v48, s0
	v_lshl_add_u64 v[110:111], v[110:111], 1, s[8:9]
	global_store_short v[110:111], v48, off sc1
	v_add_u32_e32 v110, v190, v32
	v_ashrrev_i32_e32 v111, 31, v110
	v_mul_f32_e32 v108, v198, v198
	s_waitcnt vmcnt(28)
	v_fmac_f32_e32 v45, v17, v109
	s_waitcnt vmcnt(27)
	v_add_f32_e32 v48, 1.0, v113
	s_waitcnt vmcnt(26)
	v_mul_f32_e32 v48, v114, v48
	s_waitcnt vmcnt(25)
	v_fmac_f32_e32 v116, v16, v109
	v_mul_f32_e32 v16, v48, v116
	s_waitcnt vmcnt(24)
	v_fmac_f32_e32 v47, v18, v109
	v_cvt_pk_bf16_f32 v18, v16, s0
	v_lshl_add_u64 v[16:17], v[110:111], 1, s[8:9]
	global_store_short v[16:17], v18, off sc1
	v_add_u32_e32 v16, v188, v32
	v_ashrrev_i32_e32 v17, 31, v16
	v_mul_f32_e32 v18, v48, v45
	v_cvt_pk_bf16_f32 v18, v18, s0
	v_lshl_add_u64 v[16:17], v[16:17], 1, s[8:9]
	global_store_short v[16:17], v18, off sc1
	v_add_u32_e32 v16, v186, v32
	v_ashrrev_i32_e32 v17, 31, v16
	v_mul_f32_e32 v18, v48, v47
	v_cvt_pk_bf16_f32 v18, v18, s0
	v_lshl_add_u64 v[16:17], v[16:17], 1, s[8:9]
	s_waitcnt vmcnt(23)
	v_fmac_f32_e32 v46, v19, v109
	global_store_short v[16:17], v18, off sc1
	v_add_u32_e32 v16, v185, v32
	v_ashrrev_i32_e32 v17, 31, v16
	v_mul_f32_e32 v18, v48, v46
	v_cvt_pk_bf16_f32 v18, v18, s0
	v_lshl_add_u64 v[16:17], v[16:17], 1, s[8:9]
	global_store_short v[16:17], v18, off sc1
	v_or_b32_e32 v16, 0x60, v102
	v_ashrrev_i32_e32 v17, 31, v16
	v_fmac_f32_e32 v44, v20, v109
	s_waitcnt vmcnt(24)
	v_fmac_f32_e32 v43, v21, v109
	s_waitcnt vmcnt(23)
	v_fmac_f32_e32 v42, v22, v109
	s_waitcnt vmcnt(21)
	v_fmac_f32_e32 v41, v23, v109
	v_fmac_f32_e32 v40, v24, v109
	v_fmac_f32_e32 v39, v25, v109
	s_waitcnt vmcnt(20)
	v_fmac_f32_e32 v38, v26, v109
	s_waitcnt vmcnt(19)
	v_fmac_f32_e32 v37, v27, v109
	s_waitcnt vmcnt(18)
	v_fmac_f32_e32 v36, v28, v109
	s_waitcnt vmcnt(14)
	v_fmac_f32_e32 v35, v29, v109
	s_waitcnt vmcnt(13)
	v_fmac_f32_e32 v34, v30, v109
	s_waitcnt vmcnt(12)
	v_fmac_f32_e32 v33, v31, v109
	v_lshlrev_b64 v[20:21], 2, v[16:17]
	global_store_dword v[88:89], v45, off offset:256 sc1
	global_store_dword v[84:85], v47, off offset:256 sc1
	global_store_dword v[82:83], v46, off offset:256 sc1
	global_store_dword v[78:79], v44, off offset:256 sc1
	global_store_dword v[72:73], v43, off offset:256 sc1
	global_store_dword v[74:75], v42, off offset:256 sc1
	global_store_dword v[76:77], v41, off offset:256 sc1
	global_store_dword v[80:81], v40, off offset:256 sc1
	global_store_dword v[86:87], v39, off offset:256 sc1
	global_store_dword v[90:91], v38, off offset:256 sc1
	global_store_dword v[92:93], v37, off offset:256 sc1
	global_store_dword v[94:95], v36, off offset:256 sc1
	global_store_dword v[96:97], v35, off offset:256 sc1
	global_store_dword v[98:99], v34, off offset:256 sc1
	global_store_dword v[100:101], v33, off offset:256 sc1
	global_store_dword v[106:107], v116, off offset:256 sc1
	v_lshl_add_u64 v[22:23], s[60:61], 0, v[20:21]
	v_lshl_add_u64 v[20:21], s[62:63], 0, v[20:21]
	global_load_dword v29, v[106:107], off offset:384
	global_load_dword v102, v[22:23], off
	global_load_dword v17, v[20:21], off
	s_nop 0
	global_load_dword v20, v[104:105], off offset:384
	v_add_u32_e32 v18, v183, v32
	v_ashrrev_i32_e32 v19, 31, v18
	v_mul_f32_e32 v21, v48, v44
	v_cvt_pk_bf16_f32 v21, v21, s0
	v_lshl_add_u64 v[18:19], v[18:19], 1, s[8:9]
	global_store_short v[18:19], v21, off sc1
	v_add_u32_e32 v18, v181, v32
	v_ashrrev_i32_e32 v19, 31, v18
	v_mul_f32_e32 v21, v48, v43
	v_cvt_pk_bf16_f32 v21, v21, s0
	v_lshl_add_u64 v[18:19], v[18:19], 1, s[8:9]
	global_store_short v[18:19], v21, off sc1
	v_add_u32_e32 v18, v71, v32
	v_ashrrev_i32_e32 v19, 31, v18
	v_mul_f32_e32 v21, v48, v42
	v_cvt_pk_bf16_f32 v21, v21, s0
	v_lshl_add_u64 v[18:19], v[18:19], 1, s[8:9]
	global_store_short v[18:19], v21, off sc1
	v_add_u32_e32 v18, v182, v32
	v_ashrrev_i32_e32 v19, 31, v18
	v_mul_f32_e32 v21, v48, v41
	v_cvt_pk_bf16_f32 v21, v21, s0
	v_lshl_add_u64 v[18:19], v[18:19], 1, s[8:9]
	global_store_short v[18:19], v21, off sc1
	v_add_u32_e32 v18, v184, v32
	v_ashrrev_i32_e32 v19, 31, v18
	v_mul_f32_e32 v21, v48, v40
	v_cvt_pk_bf16_f32 v21, v21, s0
	v_lshl_add_u64 v[18:19], v[18:19], 1, s[8:9]
	global_store_short v[18:19], v21, off sc1
	v_add_u32_e32 v18, v187, v32
	v_ashrrev_i32_e32 v19, 31, v18
	v_mul_f32_e32 v21, v48, v39
	v_cvt_pk_bf16_f32 v21, v21, s0
	v_lshl_add_u64 v[18:19], v[18:19], 1, s[8:9]
	global_store_short v[18:19], v21, off sc1
	v_add_u32_e32 v18, v189, v32
	v_ashrrev_i32_e32 v19, 31, v18
	v_mul_f32_e32 v21, v48, v38
	v_cvt_pk_bf16_f32 v21, v21, s0
	v_lshl_add_u64 v[18:19], v[18:19], 1, s[8:9]
	global_store_short v[18:19], v21, off sc1
	v_add_u32_e32 v18, v191, v32
	v_ashrrev_i32_e32 v19, 31, v18
	v_mul_f32_e32 v21, v48, v37
	v_cvt_pk_bf16_f32 v21, v21, s0
	v_lshl_add_u64 v[18:19], v[18:19], 1, s[8:9]
	global_store_short v[18:19], v21, off sc1
	v_add_u32_e32 v18, v192, v32
	v_ashrrev_i32_e32 v19, 31, v18
	v_mul_f32_e32 v21, v48, v36
	v_cvt_pk_bf16_f32 v21, v21, s0
	v_lshl_add_u64 v[18:19], v[18:19], 1, s[8:9]
	global_load_dword v28, v[88:89], off offset:384
	global_load_dword v27, v[84:85], off offset:384
	global_load_dword v25, v[78:79], off offset:384
	global_load_dword v24, v[72:73], off offset:384
	global_load_dword v23, v[74:75], off offset:384
	v_mul_f32_e32 v30, v48, v33
	global_store_short v[18:19], v21, off sc1
	v_add_u32_e32 v18, v193, v32
	v_ashrrev_i32_e32 v19, 31, v18
	v_mul_f32_e32 v21, v48, v35
	v_cvt_pk_bf16_f32 v21, v21, s0
	v_lshl_add_u64 v[18:19], v[18:19], 1, s[8:9]
	global_store_short v[18:19], v21, off sc1
	v_add_u32_e32 v18, v194, v32
	v_ashrrev_i32_e32 v19, 31, v18
	v_mul_f32_e32 v21, v48, v34
	v_cvt_pk_bf16_f32 v21, v21, s0
	v_lshl_add_u64 v[18:19], v[18:19], 1, s[8:9]
	global_store_short v[18:19], v21, off sc1
	v_add_u32_e32 v18, v195, v32
	global_load_dword v21, v[80:81], off offset:384
	global_load_dword v22, v[76:77], off offset:384
	v_ashrrev_i32_e32 v19, 31, v18
	v_cvt_pk_bf16_f32 v30, v30, s0
	v_lshl_add_u64 v[18:19], v[18:19], 1, s[8:9]
	s_waitcnt vmcnt(19)
	v_add_f32_e32 v17, 1.0, v17
	s_waitcnt vmcnt(18)
	v_mul_f32_e32 v32, v20, v17
	global_load_dword v20, v[86:87], off offset:384
	global_load_dword v26, v[82:83], off offset:384
	v_fmac_f32_e32 v29, v0, v102
	global_store_short v[18:19], v30, off sc1
	v_add_u32_e32 v18, v190, v16
	v_ashrrev_i32_e32 v19, 31, v18
	v_mul_f32_e32 v0, v32, v29
	v_cvt_pk_bf16_f32 v0, v0, s0
	v_lshl_add_u64 v[18:19], v[18:19], 1, s[8:9]
	global_store_short v[18:19], v0, off sc1
	global_load_dword v19, v[90:91], off offset:384
	v_add_u32_e32 v30, v188, v16
	global_load_dword v18, v[92:93], off offset:384
	v_ashrrev_i32_e32 v31, 31, v30
	v_fmac_f32_e32 v108, v202, v202
	v_fmac_f32_e32 v108, v116, v116
	v_fmac_f32_e32 v108, v29, v29
	global_store_dword v[106:107], v29, off offset:384 sc1
	s_waitcnt vmcnt(16)
	v_fmac_f32_e32 v28, v1, v102
	v_mul_f32_e32 v0, v32, v28
	v_cvt_pk_bf16_f32 v17, v0, s0
	v_lshl_add_u64 v[0:1], v[30:31], 1, s[8:9]
	global_store_short v[0:1], v17, off sc1
	v_add_u32_e32 v0, v186, v16
	s_waitcnt vmcnt(16)
	v_fmac_f32_e32 v27, v2, v102
	global_load_dword v17, v[94:95], off offset:384
	v_ashrrev_i32_e32 v1, 31, v0
	v_mul_f32_e32 v2, v32, v27
	v_cvt_pk_bf16_f32 v2, v2, s0
	v_lshl_add_u64 v[0:1], v[0:1], 1, s[8:9]
	global_store_short v[0:1], v2, off sc1
	v_add_u32_e32 v0, v185, v16
	global_load_dword v2, v[96:97], off offset:384
	v_ashrrev_i32_e32 v1, 31, v0
	v_lshl_add_u64 v[0:1], v[0:1], 1, s[8:9]
	v_add_u32_e32 v30, v183, v16
	s_waitcnt vmcnt(18)
	v_fmac_f32_e32 v25, v4, v102
	v_ashrrev_i32_e32 v31, 31, v30
	v_lshl_add_u64 v[30:31], v[30:31], 1, s[8:9]
	s_waitcnt vmcnt(17)
	v_fmac_f32_e32 v24, v5, v102
	s_waitcnt vmcnt(16)
	v_fmac_f32_e32 v23, v6, v102
	s_waitcnt vmcnt(11)
	v_fmac_f32_e32 v22, v7, v102
	v_fmac_f32_e32 v21, v8, v102
	global_store_dword v[88:89], v28, off offset:384 sc1
	global_store_dword v[84:85], v27, off offset:384 sc1
	s_waitcnt vmcnt(12)
	v_fmac_f32_e32 v20, v9, v102
	s_waitcnt vmcnt(11)
	v_fmac_f32_e32 v26, v3, v102
	v_mul_f32_e32 v3, v32, v26
	v_cvt_pk_bf16_f32 v3, v3, s0
	global_store_short v[0:1], v3, off sc1
	global_load_dword v1, v[98:99], off offset:384
	v_mul_f32_e32 v0, v32, v25
	v_cvt_pk_bf16_f32 v0, v0, s0
	global_store_short v[30:31], v0, off sc1
	global_load_dword v0, v[100:101], off offset:384
	v_add_u32_e32 v30, v181, v16
	v_ashrrev_i32_e32 v31, 31, v30
	v_mul_f32_e32 v3, v32, v24
	v_cvt_pk_bf16_f32 v3, v3, s0
	v_lshl_add_u64 v[4:5], v[30:31], 1, s[8:9]
	global_store_short v[4:5], v3, off sc1
	v_add_u32_e32 v4, v71, v16
	v_ashrrev_i32_e32 v5, 31, v4
	v_mul_f32_e32 v3, v32, v23
	v_cvt_pk_bf16_f32 v3, v3, s0
	v_lshl_add_u64 v[4:5], v[4:5], 1, s[8:9]
	global_store_short v[4:5], v3, off sc1
	v_add_u32_e32 v4, v182, v16
	v_ashrrev_i32_e32 v5, 31, v4
	v_mul_f32_e32 v3, v32, v22
	v_cvt_pk_bf16_f32 v3, v3, s0
	v_lshl_add_u64 v[4:5], v[4:5], 1, s[8:9]
	global_store_short v[4:5], v3, off sc1
	v_add_u32_e32 v4, v184, v16
	v_ashrrev_i32_e32 v5, 31, v4
	v_mul_f32_e32 v3, v32, v21
	v_cvt_pk_bf16_f32 v3, v3, s0
	v_lshl_add_u64 v[4:5], v[4:5], 1, s[8:9]
	global_store_short v[4:5], v3, off sc1
	v_add_u32_e32 v4, v187, v16
	v_ashrrev_i32_e32 v5, 31, v4
	v_mul_f32_e32 v3, v32, v20
	v_cvt_pk_bf16_f32 v3, v3, s0
	v_lshl_add_u64 v[4:5], v[4:5], 1, s[8:9]
	global_store_short v[4:5], v3, off sc1
	v_add_u32_e32 v4, v189, v16
	s_waitcnt vmcnt(17)
	v_fmac_f32_e32 v19, v10, v102
	v_ashrrev_i32_e32 v5, 31, v4
	v_mul_f32_e32 v3, v32, v19
	v_cvt_pk_bf16_f32 v3, v3, s0
	v_lshl_add_u64 v[4:5], v[4:5], 1, s[8:9]
	global_store_short v[4:5], v3, off sc1
	v_add_u32_e32 v4, v191, v16
	s_waitcnt vmcnt(17)
	v_fmac_f32_e32 v18, v11, v102
	v_ashrrev_i32_e32 v5, 31, v4
	v_mul_f32_e32 v3, v32, v18
	v_cvt_pk_bf16_f32 v3, v3, s0
	v_lshl_add_u64 v[4:5], v[4:5], 1, s[8:9]
	global_store_short v[4:5], v3, off sc1
	v_add_u32_e32 v4, v192, v16
	v_ashrrev_i32_e32 v5, 31, v4
	v_lshl_add_u64 v[4:5], v[4:5], 1, s[8:9]
	v_add_u32_e32 v10, v195, v16
	v_ashrrev_i32_e32 v11, 31, v10
	v_lshl_add_u64 v[10:11], v[10:11], 1, s[8:9]
	s_waitcnt vmcnt(15)
	v_fmac_f32_e32 v17, v12, v102
	v_mul_f32_e32 v3, v32, v17
	v_cvt_pk_bf16_f32 v3, v3, s0
	global_store_short v[4:5], v3, off sc1
	v_add_u32_e32 v4, v193, v16
	v_ashrrev_i32_e32 v5, 31, v4
	v_lshl_add_u64 v[4:5], v[4:5], 1, s[8:9]
	s_waitcnt vmcnt(14)
	v_fmac_f32_e32 v2, v13, v102
	v_mul_f32_e32 v3, v32, v2
	v_cvt_pk_bf16_f32 v3, v3, s0
	global_store_short v[4:5], v3, off sc1
	v_add_u32_e32 v4, v194, v16
	v_ashrrev_i32_e32 v5, 31, v4
	v_lshl_add_u64 v[4:5], v[4:5], 1, s[8:9]
	v_xor_b32_e32 v13, 16, v166
	v_ashrrev_i32_e32 v71, 31, v70
	global_store_dword v[82:83], v26, off offset:384 sc1
	global_store_dword v[78:79], v25, off offset:384 sc1
	global_store_dword v[72:73], v24, off offset:384 sc1
	global_store_dword v[74:75], v23, off offset:384 sc1
	global_store_dword v[76:77], v22, off offset:384 sc1
	global_store_dword v[80:81], v21, off offset:384 sc1
	global_store_dword v[86:87], v20, off offset:384 sc1
	global_store_dword v[90:91], v19, off offset:384 sc1
	global_store_dword v[92:93], v18, off offset:384 sc1
	s_waitcnt vmcnt(20)
	v_fmac_f32_e32 v1, v14, v102
	v_mul_f32_e32 v3, v32, v1
	v_cvt_pk_bf16_f32 v3, v3, s0
	global_store_short v[4:5], v3, off sc1
	v_and_b32_e32 v4, 64, v166
	v_xor_b32_e32 v3, 1, v166
	v_add_u32_e32 v7, 64, v4
	v_cmp_lt_i32_e32 vcc, v3, v7
	v_xor_b32_e32 v4, 2, v166
	s_waitcnt vmcnt(19)
	v_fmac_f32_e32 v0, v15, v102
	v_cndmask_b32_e32 v3, v166, v3, vcc
	v_lshlrev_b32_e32 v3, 2, v3
	ds_bpermute_b32 v5, v3, v108
	v_cmp_lt_i32_e32 vcc, v4, v7
	v_mul_f32_e32 v12, v32, v0
	v_cvt_pk_bf16_f32 v12, v12, s0
	v_cndmask_b32_e32 v4, v166, v4, vcc
	v_lshlrev_b32_e32 v4, 2, v4
	s_waitcnt lgkmcnt(0)
	v_add_f32_e32 v6, v108, v5
	ds_bpermute_b32 v8, v4, v6
	v_xor_b32_e32 v5, 4, v166
	v_cmp_lt_i32_e32 vcc, v5, v7
	global_store_dword v[94:95], v17, off offset:384 sc1
	global_store_dword v[96:97], v2, off offset:384 sc1
	v_cndmask_b32_e32 v5, v166, v5, vcc
	v_lshlrev_b32_e32 v5, 2, v5
	s_waitcnt lgkmcnt(0)
	v_add_f32_e32 v8, v6, v8
	ds_bpermute_b32 v9, v5, v8
	v_xor_b32_e32 v6, 8, v166
	v_cmp_lt_i32_e32 vcc, v6, v7
	global_store_dword v[98:99], v1, off offset:384 sc1
	global_store_dword v[100:101], v0, off offset:384 sc1
	v_cndmask_b32_e32 v6, v166, v6, vcc
	v_lshlrev_b32_e32 v6, 2, v6
	s_waitcnt lgkmcnt(0)
	v_add_f32_e32 v8, v8, v9
	ds_bpermute_b32 v9, v6, v8
	v_cmp_lt_i32_e32 vcc, v13, v7
	global_store_short v[10:11], v12, off sc1
	s_waitcnt lgkmcnt(0)
	v_add_f32_e32 v8, v8, v9
	v_cndmask_b32_e32 v7, v166, v13, vcc
	v_lshlrev_b32_e32 v7, 2, v7
	ds_bpermute_b32 v9, v7, v8
	s_and_saveexec_b64 s[60:61], s[0:1]
	s_cbranch_execz .LBB0_709
	s_waitcnt lgkmcnt(0)
	v_add_f32_e32 v10, v8, v9
	v_lshl_add_u64 v[8:9], v[70:71], 2, s[58:59]
	global_store_dword v[8:9], v10, off sc1

.LBB0_779:
	s_add_i32 s58, s67, 0xffffe000
	s_lshr_b32 s58, s58, 12
	s_mulk_i32 s58, 0x1800
	s_addk_i32 s58, 0x1800
	s_cmp_gt_i32 s6, 63
	s_cselect_b32 s6, s58, 0
	s_lshl_b64 s[58:59], s[6:7], 2
	s_add_u32 s58, s14, s58
	s_addc_u32 s59, s15, s59
	s_add_u32 s60, s58, 0x5ba5000
	s_addc_u32 s61, s59, 0
	s_addk_i32 s6, 0x4800
	s_lshl_b64 s[58:59], s[6:7], 2
	v_mov_b32_e32 v70, s66
	s_add_u32 s6, s14, s58
	ds_read_b64 v[70:71], v70
	s_addc_u32 s65, s15, s59
	s_lshl_b32 s58, s64, 14
	s_add_i32 s58, s58, 0x40000
	s_ashr_i32 s59, s58, 31
	s_lshl_b64 s[58:59], s[58:59], 2
	s_add_u32 s58, s10, s58
	s_waitcnt lgkmcnt(0)
	v_readfirstlane_b32 s62, v70
	s_addc_u32 s59, s11, s59
	v_or_b32_e32 v102, s68, v138
	v_add_u32_e32 v70, s67, v139
	v_readfirstlane_b32 s63, v71
	s_add_u32 s62, s62, 0x1000
	v_ashrrev_i32_e32 v103, 31, v102
	v_lshlrev_b32_e32 v191, 10, v70
	s_addc_u32 s63, s63, 0
	v_lshlrev_b64 v[72:73], 2, v[102:103]
	v_or_b32_e32 v187, 0x400, v191
	v_or_b32_e32 v186, 0x4400, v191
	v_or_b32_e32 v189, 0x4c00, v191
	v_or_b32_e32 v194, 0x6c00, v191
	s_add_u32 s64, s6, 0x5ba1000
	v_lshl_add_u64 v[74:75], s[60:61], 0, v[72:73]
	v_add_u32_e32 v130, v191, v102
	v_add_u32_e32 v132, v187, v102
	v_or_b32_e32 v185, 0x800, v191
	v_or_b32_e32 v184, 0xc00, v191
	v_or_b32_e32 v182, 0x2000, v191
	v_or_b32_e32 v180, 0x2400, v191
	v_or_b32_e32 v71, 0x2800, v191
	v_or_b32_e32 v181, 0x2c00, v191
	v_or_b32_e32 v183, 0x4000, v191
	v_add_u32_e32 v112, v186, v102
	v_or_b32_e32 v188, 0x4800, v191
	v_add_u32_e32 v116, v189, v102
	v_or_b32_e32 v190, 0x6000, v191
	v_or_b32_e32 v192, 0x6400, v191
	v_or_b32_e32 v193, 0x6800, v191
	v_add_u32_e32 v128, v194, v102
	s_addc_u32 s65, s65, 0
	global_load_dword v195, v[74:75], off
	global_load_dword v205, v[74:75], off offset:128
	v_lshl_add_u64 v[74:75], s[62:63], 0, v[72:73]
	v_ashrrev_i32_e32 v133, 31, v132
	v_add_u32_e32 v134, v185, v102
	v_add_u32_e32 v136, v184, v102
	v_add_u32_e32 v126, v182, v102
	v_add_u32_e32 v118, v180, v102
	v_add_u32_e32 v110, v71, v102
	v_add_u32_e32 v106, v181, v102
	v_add_u32_e32 v108, v183, v102
	v_ashrrev_i32_e32 v113, 31, v112
	v_add_u32_e32 v114, v188, v102
	v_ashrrev_i32_e32 v117, 31, v116
	v_add_u32_e32 v120, v190, v102
	v_add_u32_e32 v122, v192, v102
	v_add_u32_e32 v124, v193, v102
	v_ashrrev_i32_e32 v129, 31, v128
	v_ashrrev_i32_e32 v131, 31, v130
	v_lshl_add_u64 v[72:73], s[64:65], 0, v[72:73]
	global_load_dword v196, v[74:75], off
	global_load_dword v204, v[74:75], off offset:128
	global_load_dword v197, v[72:73], off
	global_load_dword v203, v[72:73], off offset:128
	v_lshl_add_u64 v[88:89], v[132:133], 2, s[12:13]
	v_ashrrev_i32_e32 v135, 31, v134
	v_ashrrev_i32_e32 v137, 31, v136
	v_ashrrev_i32_e32 v127, 31, v126
	v_ashrrev_i32_e32 v119, 31, v118
	v_ashrrev_i32_e32 v111, 31, v110
	v_ashrrev_i32_e32 v107, 31, v106
	v_ashrrev_i32_e32 v109, 31, v108
	v_lshl_add_u64 v[86:87], v[112:113], 2, s[12:13]
	v_ashrrev_i32_e32 v115, 31, v114
	v_lshl_add_u64 v[92:93], v[116:117], 2, s[12:13]
	v_ashrrev_i32_e32 v121, 31, v120
	v_ashrrev_i32_e32 v123, 31, v122
	v_ashrrev_i32_e32 v125, 31, v124
	v_lshl_add_u64 v[100:101], v[128:129], 2, s[12:13]
	v_lshl_add_u64 v[104:105], v[130:131], 2, s[12:13]
	v_lshl_add_u64 v[84:85], v[134:135], 2, s[12:13]
	v_lshl_add_u64 v[82:83], v[136:137], 2, s[12:13]
	v_lshl_add_u64 v[78:79], v[126:127], 2, s[12:13]
	v_lshl_add_u64 v[72:73], v[118:119], 2, s[12:13]
	v_lshl_add_u64 v[74:75], v[110:111], 2, s[12:13]
	v_lshl_add_u64 v[76:77], v[106:107], 2, s[12:13]
	v_lshl_add_u64 v[80:81], v[108:109], 2, s[12:13]
	global_load_dword v179, v[88:89], off
	global_load_dword v178, v[84:85], off
	global_load_dword v177, v[82:83], off
	global_load_dword v176, v[78:79], off
	global_load_dword v175, v[72:73], off
	global_load_dword v174, v[74:75], off
	global_load_dword v173, v[76:77], off
	global_load_dword v172, v[80:81], off
	v_lshl_add_u64 v[90:91], v[114:115], 2, s[12:13]
	global_load_dword v171, v[86:87], off
	global_load_dword v169, v[90:91], off
	v_lshl_add_u64 v[94:95], v[120:121], 2, s[12:13]
	v_lshl_add_u64 v[96:97], v[122:123], 2, s[12:13]
	v_lshl_add_u64 v[98:99], v[124:125], 2, s[12:13]
	global_load_dword v170, v[92:93], off
	global_load_dword v168, v[94:95], off
	global_load_dword v167, v[96:97], off
	global_load_dword v166, v[98:99], off
	global_load_dword v103, v[100:101], off
	global_load_dword v198, v[104:105], off
	v_lshl_add_u64 v[110:111], v[110:111], 1, s[8:9]
	v_lshl_add_u64 v[106:107], v[106:107], 1, s[8:9]
	global_load_dword v202, v[104:105], off offset:128
	global_load_dword v206, v[84:85], off offset:128
	global_load_dword v207, v[78:79], off offset:128
	global_load_dword v208, v[72:73], off offset:128
	global_load_dword v209, v[74:75], off offset:128
	global_load_dword v210, v[80:81], off offset:128
	global_load_dword v211, v[76:77], off offset:128
	global_load_dword v212, v[86:87], off offset:128
	global_load_dword v213, v[82:83], off offset:128
	global_load_dword v214, v[90:91], off offset:128
	global_load_dword v215, v[92:93], off offset:128
	global_load_dword v216, v[94:95], off offset:128
	global_load_dword v217, v[96:97], off offset:128
	global_load_dword v218, v[98:99], off offset:128
	global_load_dword v219, v[100:101], off offset:128
	global_load_dword v220, v[88:89], off offset:128
	s_waitcnt vmcnt(0)
	v_add_f32_e32 v197, 1.0, v197
	v_mul_f32_e32 v196, v196, v197
	v_fmac_f32_e32 v179, v49, v195
	v_fmac_f32_e32 v178, v50, v195
	v_fmac_f32_e32 v177, v51, v195
	v_fmac_f32_e32 v176, v52, v195
	v_fmac_f32_e32 v175, v53, v195
	v_fmac_f32_e32 v174, v54, v195
	v_fmac_f32_e32 v173, v55, v195
	v_fmac_f32_e32 v172, v56, v195
	v_fmac_f32_e32 v171, v57, v195
	v_fmac_f32_e32 v169, v58, v195
	v_fmac_f32_e32 v170, v59, v195
	v_fmac_f32_e32 v168, v60, v195
	v_fmac_f32_e32 v167, v61, v195
	v_fmac_f32_e32 v166, v62, v195
	v_fmac_f32_e32 v103, v63, v195
	v_fmac_f32_e32 v198, v48, v195
	v_mul_f32_e32 v48, v196, v198
	v_cvt_pk_bf16_f32 v58, v48, s0
	v_or_b32_e32 v48, 32, v102
	v_ashrrev_i32_e32 v49, 31, v48
	v_lshlrev_b64 v[52:53], 2, v[48:49]
	global_store_dword v[88:89], v179, off sc1
	global_store_dword v[84:85], v178, off sc1
	global_store_dword v[82:83], v177, off sc1
	global_store_dword v[78:79], v176, off sc1
	global_store_dword v[72:73], v175, off sc1
	global_store_dword v[74:75], v174, off sc1
	global_store_dword v[76:77], v173, off sc1
	global_store_dword v[80:81], v172, off sc1
	global_store_dword v[86:87], v171, off sc1
	global_store_dword v[90:91], v169, off sc1
	global_store_dword v[92:93], v170, off sc1
	global_store_dword v[94:95], v168, off sc1
	global_store_dword v[96:97], v167, off sc1
	global_store_dword v[98:99], v166, off sc1
	global_store_dword v[100:101], v103, off sc1
	global_store_dword v[104:105], v198, off sc1
	v_lshl_add_u64 v[50:51], v[130:131], 1, s[8:9]
	v_lshl_add_u64 v[56:57], s[64:65], 0, v[52:53]
	v_mov_b32_e32 v197, v202
	v_lshl_add_u64 v[54:55], s[62:63], 0, v[52:53]
	v_mov_b32_e32 v130, v203
	v_mov_b32_e32 v131, v204
	v_mul_f32_e32 v49, v196, v179
	global_store_short v[50:51], v58, off sc1
	v_lshl_add_u64 v[50:51], s[60:61], 0, v[52:53]
	v_mov_b32_e32 v195, v205
	v_lshl_add_u64 v[50:51], v[132:133], 1, s[8:9]
	v_cvt_pk_bf16_f32 v49, v49, s0
	global_store_short v[50:51], v49, off sc1
	v_mul_f32_e32 v49, v196, v178
	v_lshl_add_u64 v[50:51], v[134:135], 1, s[8:9]
	v_cvt_pk_bf16_f32 v49, v49, s0
	global_store_short v[50:51], v49, off sc1
	v_mul_f32_e32 v49, v196, v177
	v_lshl_add_u64 v[50:51], v[136:137], 1, s[8:9]
	v_cvt_pk_bf16_f32 v49, v49, s0
	global_store_short v[50:51], v49, off sc1
	v_mul_f32_e32 v49, v196, v176
	v_lshl_add_u64 v[50:51], v[126:127], 1, s[8:9]
	v_cvt_pk_bf16_f32 v49, v49, s0
	global_store_short v[50:51], v49, off sc1
	v_mul_f32_e32 v49, v196, v175
	v_lshl_add_u64 v[50:51], v[118:119], 1, s[8:9]
	v_cvt_pk_bf16_f32 v49, v49, s0
	v_mov_b32_e32 v62, v206
	v_mov_b32_e32 v60, v207
	v_mov_b32_e32 v59, v208
	v_mov_b32_e32 v58, v209
	v_mov_b32_e32 v56, v210
	v_mov_b32_e32 v57, v211
	v_mov_b32_e32 v55, v212
	v_mov_b32_e32 v61, v213
	v_mov_b32_e32 v54, v214
	v_mov_b32_e32 v53, v215
	v_mov_b32_e32 v52, v216
	v_mul_f32_e32 v63, v196, v174
	global_store_short v[50:51], v49, off sc1
	v_mov_b32_e32 v51, v217
	v_cvt_pk_bf16_f32 v63, v63, s0
	v_mov_b32_e32 v50, v218
	v_mov_b32_e32 v49, v219
	v_fmac_f32_e32 v197, v32, v195
	global_store_short v[110:111], v63, off sc1
	v_mov_b32_e32 v63, v220
	v_mul_f32_e32 v110, v196, v173
	v_cvt_pk_bf16_f32 v110, v110, s0
	global_store_short v[106:107], v110, off sc1
	v_lshl_add_u64 v[106:107], v[108:109], 1, s[8:9]
	v_mul_f32_e32 v108, v196, v172
	v_cvt_pk_bf16_f32 v108, v108, s0
	global_store_short v[106:107], v108, off sc1
	v_mul_f32_e32 v108, v196, v171
	v_lshl_add_u64 v[106:107], v[112:113], 1, s[8:9]
	v_cvt_pk_bf16_f32 v108, v108, s0
	global_store_short v[106:107], v108, off sc1
	v_mul_f32_e32 v108, v196, v169
	v_lshl_add_u64 v[106:107], v[114:115], 1, s[8:9]
	v_cvt_pk_bf16_f32 v108, v108, s0
	global_store_short v[106:107], v108, off sc1
	v_mul_f32_e32 v108, v196, v170
	v_lshl_add_u64 v[106:107], v[116:117], 1, s[8:9]
	v_cvt_pk_bf16_f32 v108, v108, s0
	global_store_short v[106:107], v108, off sc1
	v_mul_f32_e32 v108, v196, v168
	v_lshl_add_u64 v[106:107], v[120:121], 1, s[8:9]
	v_cvt_pk_bf16_f32 v108, v108, s0
	global_store_short v[106:107], v108, off sc1
	v_mul_f32_e32 v108, v196, v167
	v_lshl_add_u64 v[106:107], v[122:123], 1, s[8:9]
	v_cvt_pk_bf16_f32 v108, v108, s0
	global_store_short v[106:107], v108, off sc1
	v_mul_f32_e32 v108, v196, v166
	v_lshl_add_u64 v[106:107], v[124:125], 1, s[8:9]
	v_cvt_pk_bf16_f32 v108, v108, s0
	global_store_short v[106:107], v108, off sc1
	v_mul_f32_e32 v108, v196, v103
	v_lshl_add_u64 v[106:107], v[128:129], 1, s[8:9]
	v_cvt_pk_bf16_f32 v108, v108, s0
	global_store_short v[106:107], v108, off sc1
	v_add_f32_e32 v106, 1.0, v130
	v_mul_f32_e32 v107, v131, v106
	v_add_u32_e32 v108, v191, v48
	v_ashrrev_i32_e32 v109, 31, v108
	v_mul_f32_e32 v32, v107, v197
	v_fmac_f32_e32 v62, v34, v195
	v_fmac_f32_e32 v61, v35, v195
	v_fmac_f32_e32 v60, v36, v195
	v_fmac_f32_e32 v59, v37, v195
	v_fmac_f32_e32 v58, v38, v195
	v_fmac_f32_e32 v57, v39, v195
	v_fmac_f32_e32 v56, v40, v195
	v_fmac_f32_e32 v55, v41, v195
	v_fmac_f32_e32 v54, v42, v195
	v_fmac_f32_e32 v53, v43, v195
	v_fmac_f32_e32 v52, v44, v195
	v_fmac_f32_e32 v51, v45, v195
	v_fmac_f32_e32 v50, v46, v195
	v_fmac_f32_e32 v49, v47, v195
	global_store_dword v[104:105], v197, off offset:128 sc1
	v_lshl_add_u64 v[108:109], v[108:109], 1, s[8:9]
	v_cvt_pk_bf16_f32 v32, v32, s0
	global_store_dword v[84:85], v62, off offset:128 sc1
	global_store_dword v[82:83], v61, off offset:128 sc1
	global_store_dword v[78:79], v60, off offset:128 sc1
	global_store_dword v[72:73], v59, off offset:128 sc1
	global_store_dword v[74:75], v58, off offset:128 sc1
	global_store_dword v[76:77], v57, off offset:128 sc1
	global_store_dword v[80:81], v56, off offset:128 sc1
	global_store_dword v[86:87], v55, off offset:128 sc1
	global_store_dword v[90:91], v54, off offset:128 sc1
	global_store_dword v[92:93], v53, off offset:128 sc1
	global_store_dword v[94:95], v52, off offset:128 sc1
	global_store_dword v[96:97], v51, off offset:128 sc1
	global_store_dword v[98:99], v50, off offset:128 sc1
	global_store_dword v[100:101], v49, off offset:128 sc1
	global_store_short v[108:109], v32, off sc1
	v_add_u32_e32 v108, v187, v48
	global_load_dword v45, v[88:89], off offset:256
	v_ashrrev_i32_e32 v109, 31, v108
	v_mul_f32_e32 v113, v107, v56
	v_cvt_pk_bf16_f32 v113, v113, s0
	v_mul_f32_e32 v106, v197, v197
	v_fmac_f32_e32 v106, v198, v198
	s_waitcnt vmcnt(26)
	v_fmac_f32_e32 v63, v33, v195
	v_mul_f32_e32 v34, v107, v63
	v_lshl_add_u64 v[32:33], v[108:109], 1, s[8:9]
	v_cvt_pk_bf16_f32 v34, v34, s0
	global_store_short v[32:33], v34, off sc1
	v_add_u32_e32 v32, v185, v48
	v_ashrrev_i32_e32 v33, 31, v32
	v_mul_f32_e32 v34, v107, v62
	v_lshl_add_u64 v[32:33], v[32:33], 1, s[8:9]
	v_cvt_pk_bf16_f32 v34, v34, s0
	global_store_short v[32:33], v34, off sc1
	v_add_u32_e32 v32, v184, v48
	v_ashrrev_i32_e32 v33, 31, v32
	v_mul_f32_e32 v34, v107, v61
	v_lshl_add_u64 v[32:33], v[32:33], 1, s[8:9]
	v_cvt_pk_bf16_f32 v34, v34, s0
	global_store_short v[32:33], v34, off sc1
	v_add_u32_e32 v32, v182, v48
	v_ashrrev_i32_e32 v33, 31, v32
	v_mul_f32_e32 v34, v107, v60
	v_lshl_add_u64 v[32:33], v[32:33], 1, s[8:9]
	v_cvt_pk_bf16_f32 v34, v34, s0
	global_store_short v[32:33], v34, off sc1
	v_add_u32_e32 v32, v180, v48
	v_ashrrev_i32_e32 v33, 31, v32
	v_lshl_add_u64 v[34:35], v[32:33], 1, s[8:9]
	v_mul_f32_e32 v32, v107, v59
	v_cvt_pk_bf16_f32 v42, v32, s0
	v_or_b32_e32 v32, 64, v102
	v_ashrrev_i32_e32 v33, 31, v32
	v_lshlrev_b64 v[36:37], 2, v[32:33]
	global_store_dword v[88:89], v63, off offset:128 sc1
	v_lshl_add_u64 v[40:41], s[64:65], 0, v[36:37]
	v_lshl_add_u64 v[38:39], s[62:63], 0, v[36:37]
	global_load_dword v110, v[40:41], off
	global_load_dword v111, v[38:39], off
	v_mul_f32_e32 v33, v107, v58
	global_store_short v[34:35], v42, off sc1
	v_lshl_add_u64 v[34:35], s[60:61], 0, v[36:37]
	global_load_dword v112, v[34:35], off
	v_add_u32_e32 v34, v71, v48
	v_ashrrev_i32_e32 v35, 31, v34
	v_lshl_add_u64 v[34:35], v[34:35], 1, s[8:9]
	v_cvt_pk_bf16_f32 v33, v33, s0
	global_store_short v[34:35], v33, off sc1
	v_add_u32_e32 v34, v181, v48
	v_ashrrev_i32_e32 v35, 31, v34
	v_mul_f32_e32 v33, v107, v57
	v_lshl_add_u64 v[34:35], v[34:35], 1, s[8:9]
	v_cvt_pk_bf16_f32 v33, v33, s0
	global_load_dword v38, v[90:91], off offset:256
	global_load_dword v37, v[92:93], off offset:256
	global_load_dword v36, v[94:95], off offset:256
	global_load_dword v114, v[104:105], off offset:256
	global_load_dword v47, v[84:85], off offset:256
	global_load_dword v39, v[86:87], off offset:256
	global_load_dword v46, v[82:83], off offset:256
	global_load_dword v44, v[78:79], off offset:256
	global_load_dword v43, v[72:73], off offset:256
	global_load_dword v42, v[74:75], off offset:256
	global_load_dword v40, v[80:81], off offset:256
	global_load_dword v41, v[76:77], off offset:256
	v_add_u32_e32 v108, v183, v48
	global_store_short v[34:35], v33, off sc1
	global_load_dword v35, v[96:97], off offset:256
	v_ashrrev_i32_e32 v109, 31, v108
	global_load_dword v34, v[98:99], off offset:256
	global_load_dword v33, v[100:101], off offset:256
	v_lshl_add_u64 v[108:109], v[108:109], 1, s[8:9]
	global_store_short v[108:109], v113, off sc1
	v_add_u32_e32 v108, v186, v48
	v_ashrrev_i32_e32 v109, 31, v108
	v_mul_f32_e32 v113, v107, v55
	v_lshl_add_u64 v[108:109], v[108:109], 1, s[8:9]
	v_cvt_pk_bf16_f32 v113, v113, s0
	global_store_short v[108:109], v113, off sc1
	v_add_u32_e32 v108, v188, v48
	v_ashrrev_i32_e32 v109, 31, v108
	v_mul_f32_e32 v113, v107, v54
	v_lshl_add_u64 v[108:109], v[108:109], 1, s[8:9]
	v_cvt_pk_bf16_f32 v113, v113, s0
	global_store_short v[108:109], v113, off sc1
	v_add_u32_e32 v108, v189, v48
	v_ashrrev_i32_e32 v109, 31, v108
	v_mul_f32_e32 v113, v107, v53
	v_lshl_add_u64 v[108:109], v[108:109], 1, s[8:9]
	v_cvt_pk_bf16_f32 v113, v113, s0
	global_store_short v[108:109], v113, off sc1
	v_add_u32_e32 v108, v190, v48
	v_ashrrev_i32_e32 v109, 31, v108
	v_mul_f32_e32 v113, v107, v52
	v_lshl_add_u64 v[108:109], v[108:109], 1, s[8:9]
	v_cvt_pk_bf16_f32 v113, v113, s0
	global_store_short v[108:109], v113, off sc1
	v_add_u32_e32 v108, v192, v48
	v_ashrrev_i32_e32 v109, 31, v108
	v_mul_f32_e32 v113, v107, v51
	v_lshl_add_u64 v[108:109], v[108:109], 1, s[8:9]
	v_cvt_pk_bf16_f32 v113, v113, s0
	global_store_short v[108:109], v113, off sc1
	v_add_u32_e32 v108, v193, v48
	v_ashrrev_i32_e32 v109, 31, v108
	v_mul_f32_e32 v113, v107, v50
	v_lshl_add_u64 v[108:109], v[108:109], 1, s[8:9]
	v_cvt_pk_bf16_f32 v113, v113, s0
	global_store_short v[108:109], v113, off sc1
	v_add_u32_e32 v108, v194, v48
	v_ashrrev_i32_e32 v109, 31, v108
	v_mul_f32_e32 v48, v107, v49
	v_lshl_add_u64 v[108:109], v[108:109], 1, s[8:9]
	v_cvt_pk_bf16_f32 v48, v48, s0
	global_store_short v[108:109], v48, off sc1
	v_add_u32_e32 v108, v191, v32
	v_ashrrev_i32_e32 v109, 31, v108
	s_waitcnt vmcnt(28)
	v_add_f32_e32 v48, 1.0, v110
	s_waitcnt vmcnt(27)
	v_mul_f32_e32 v48, v111, v48
	s_waitcnt vmcnt(25)
	v_fmac_f32_e32 v45, v17, v112
	global_store_dword v[88:89], v45, off offset:256 sc1
	s_waitcnt vmcnt(24)
	v_fmac_f32_e32 v38, v26, v112
	s_waitcnt vmcnt(23)
	v_fmac_f32_e32 v37, v27, v112
	s_waitcnt vmcnt(22)
	v_fmac_f32_e32 v36, v28, v112
	s_waitcnt vmcnt(21)
	v_fmac_f32_e32 v114, v16, v112
	s_waitcnt vmcnt(20)
	v_fmac_f32_e32 v47, v18, v112
	v_mul_f32_e32 v18, v48, v114
	v_lshl_add_u64 v[16:17], v[108:109], 1, s[8:9]
	v_cvt_pk_bf16_f32 v18, v18, s0
	global_store_short v[16:17], v18, off sc1
	v_add_u32_e32 v16, v187, v32
	v_ashrrev_i32_e32 v17, 31, v16
	v_mul_f32_e32 v18, v48, v45
	v_lshl_add_u64 v[16:17], v[16:17], 1, s[8:9]
	v_cvt_pk_bf16_f32 v18, v18, s0
	global_store_short v[16:17], v18, off sc1
	v_add_u32_e32 v16, v185, v32
	v_ashrrev_i32_e32 v17, 31, v16
	v_mul_f32_e32 v18, v48, v47
	v_lshl_add_u64 v[16:17], v[16:17], 1, s[8:9]
	v_cvt_pk_bf16_f32 v18, v18, s0
	s_waitcnt vmcnt(20)
	v_fmac_f32_e32 v46, v19, v112
	global_store_short v[16:17], v18, off sc1
	v_add_u32_e32 v16, v184, v32
	v_ashrrev_i32_e32 v17, 31, v16
	v_mul_f32_e32 v18, v48, v46
	v_lshl_add_u64 v[16:17], v[16:17], 1, s[8:9]
	v_cvt_pk_bf16_f32 v18, v18, s0
	global_store_short v[16:17], v18, off sc1
	v_add_u32_e32 v16, v182, v32
	v_ashrrev_i32_e32 v17, 31, v16
	v_lshl_add_u64 v[18:19], v[16:17], 1, s[8:9]
	v_or_b32_e32 v16, 0x60, v102
	v_ashrrev_i32_e32 v17, 31, v16
	s_waitcnt vmcnt(21)
	v_fmac_f32_e32 v44, v20, v112
	s_waitcnt vmcnt(20)
	v_fmac_f32_e32 v43, v21, v112
	s_waitcnt vmcnt(19)
	v_fmac_f32_e32 v42, v22, v112
	s_waitcnt vmcnt(17)
	v_fmac_f32_e32 v41, v23, v112
	v_fmac_f32_e32 v40, v24, v112
	v_fmac_f32_e32 v39, v25, v112
	s_waitcnt vmcnt(15)
	v_fmac_f32_e32 v35, v29, v112
	s_waitcnt vmcnt(14)
	v_fmac_f32_e32 v34, v30, v112
	s_waitcnt vmcnt(13)
	v_fmac_f32_e32 v33, v31, v112
	v_lshlrev_b64 v[20:21], 2, v[16:17]
	global_store_dword v[84:85], v47, off offset:256 sc1
	global_store_dword v[82:83], v46, off offset:256 sc1
	global_store_dword v[78:79], v44, off offset:256 sc1
	global_store_dword v[72:73], v43, off offset:256 sc1
	global_store_dword v[74:75], v42, off offset:256 sc1
	global_store_dword v[76:77], v41, off offset:256 sc1
	global_store_dword v[80:81], v40, off offset:256 sc1
	global_store_dword v[86:87], v39, off offset:256 sc1
	global_store_dword v[90:91], v38, off offset:256 sc1
	global_store_dword v[92:93], v37, off offset:256 sc1
	global_store_dword v[94:95], v36, off offset:256 sc1
	global_store_dword v[96:97], v35, off offset:256 sc1
	global_store_dword v[98:99], v34, off offset:256 sc1
	global_store_dword v[100:101], v33, off offset:256 sc1
	global_store_dword v[104:105], v114, off offset:256 sc1
	v_mul_f32_e32 v26, v48, v44
	v_lshl_add_u64 v[22:23], s[62:63], 0, v[20:21]
	v_lshl_add_u64 v[24:25], s[64:65], 0, v[20:21]
	global_load_dword v29, v[104:105], off offset:384
	global_load_dword v17, v[24:25], off
	global_load_dword v30, v[22:23], off
	v_cvt_pk_bf16_f32 v22, v26, s0
	global_store_short v[18:19], v22, off sc1
	v_lshl_add_u64 v[18:19], s[60:61], 0, v[20:21]
	global_load_dword v102, v[18:19], off
	v_add_u32_e32 v18, v180, v32
	v_ashrrev_i32_e32 v19, 31, v18
	v_mul_f32_e32 v20, v48, v43
	v_lshl_add_u64 v[18:19], v[18:19], 1, s[8:9]
	v_cvt_pk_bf16_f32 v20, v20, s0
	global_store_short v[18:19], v20, off sc1
	v_add_u32_e32 v18, v71, v32
	v_ashrrev_i32_e32 v19, 31, v18
	v_mul_f32_e32 v20, v48, v42
	v_lshl_add_u64 v[18:19], v[18:19], 1, s[8:9]
	v_cvt_pk_bf16_f32 v20, v20, s0
	global_store_short v[18:19], v20, off sc1
	v_add_u32_e32 v18, v181, v32
	v_ashrrev_i32_e32 v19, 31, v18
	v_mul_f32_e32 v20, v48, v41
	v_lshl_add_u64 v[18:19], v[18:19], 1, s[8:9]
	v_cvt_pk_bf16_f32 v20, v20, s0
	global_store_short v[18:19], v20, off sc1
	v_add_u32_e32 v18, v183, v32
	v_ashrrev_i32_e32 v19, 31, v18
	v_mul_f32_e32 v20, v48, v40
	v_lshl_add_u64 v[18:19], v[18:19], 1, s[8:9]
	v_cvt_pk_bf16_f32 v20, v20, s0
	global_store_short v[18:19], v20, off sc1
	v_add_u32_e32 v18, v186, v32
	v_ashrrev_i32_e32 v19, 31, v18
	v_mul_f32_e32 v20, v48, v39
	v_lshl_add_u64 v[18:19], v[18:19], 1, s[8:9]
	v_cvt_pk_bf16_f32 v20, v20, s0
	global_store_short v[18:19], v20, off sc1
	v_add_u32_e32 v18, v188, v32
	v_ashrrev_i32_e32 v19, 31, v18
	v_mul_f32_e32 v20, v48, v38
	v_lshl_add_u64 v[18:19], v[18:19], 1, s[8:9]
	v_cvt_pk_bf16_f32 v20, v20, s0
	global_store_short v[18:19], v20, off sc1
	v_add_u32_e32 v18, v189, v32
	v_ashrrev_i32_e32 v19, 31, v18
	v_mul_f32_e32 v20, v48, v37
	v_lshl_add_u64 v[18:19], v[18:19], 1, s[8:9]
	v_cvt_pk_bf16_f32 v20, v20, s0
	global_store_short v[18:19], v20, off sc1
	v_add_u32_e32 v18, v190, v32
	v_ashrrev_i32_e32 v19, 31, v18
	v_mul_f32_e32 v20, v48, v36
	v_lshl_add_u64 v[18:19], v[18:19], 1, s[8:9]
	v_cvt_pk_bf16_f32 v20, v20, s0
	global_store_short v[18:19], v20, off sc1
	v_add_u32_e32 v18, v192, v32
	v_ashrrev_i32_e32 v19, 31, v18
	v_mul_f32_e32 v20, v48, v35
	v_lshl_add_u64 v[18:19], v[18:19], 1, s[8:9]
	v_cvt_pk_bf16_f32 v20, v20, s0
	global_load_dword v28, v[88:89], off offset:384
	global_load_dword v27, v[84:85], off offset:384
	global_load_dword v25, v[78:79], off offset:384
	global_load_dword v24, v[72:73], off offset:384
	global_load_dword v23, v[74:75], off offset:384
	global_load_dword v21, v[80:81], off offset:384
	global_load_dword v22, v[76:77], off offset:384
	v_fmac_f32_e32 v106, v114, v114
	global_store_short v[18:19], v20, off sc1
	v_add_u32_e32 v18, v193, v32
	v_ashrrev_i32_e32 v19, 31, v18
	v_mul_f32_e32 v20, v48, v34
	v_lshl_add_u64 v[18:19], v[18:19], 1, s[8:9]
	v_cvt_pk_bf16_f32 v20, v20, s0
	global_store_short v[18:19], v20, off sc1
	v_add_u32_e32 v18, v194, v32
	v_ashrrev_i32_e32 v19, 31, v18
	v_mul_f32_e32 v20, v48, v33
	v_lshl_add_u64 v[18:19], v[18:19], 1, s[8:9]
	v_cvt_pk_bf16_f32 v20, v20, s0
	global_store_short v[18:19], v20, off sc1
	global_load_dword v20, v[86:87], off offset:384
	s_waitcnt vmcnt(22)
	v_add_f32_e32 v17, 1.0, v17
	global_load_dword v26, v[82:83], off offset:384
	s_waitcnt vmcnt(22)
	v_mul_f32_e32 v32, v30, v17
	v_add_u32_e32 v18, v191, v16
	s_waitcnt vmcnt(20)
	v_fmac_f32_e32 v29, v0, v102
	v_ashrrev_i32_e32 v19, 31, v18
	v_mul_f32_e32 v0, v32, v29
	v_lshl_add_u64 v[18:19], v[18:19], 1, s[8:9]
	v_cvt_pk_bf16_f32 v0, v0, s0
	global_store_short v[18:19], v0, off sc1
	global_load_dword v19, v[90:91], off offset:384
	v_add_u32_e32 v30, v187, v16
	global_load_dword v18, v[92:93], off offset:384
	v_ashrrev_i32_e32 v31, 31, v30
	v_fmac_f32_e32 v106, v29, v29
	global_store_dword v[104:105], v29, off offset:384 sc1
	s_waitcnt vmcnt(15)
	v_fmac_f32_e32 v28, v1, v102
	v_mul_f32_e32 v17, v32, v28
	v_lshl_add_u64 v[0:1], v[30:31], 1, s[8:9]
	v_cvt_pk_bf16_f32 v17, v17, s0
	global_store_short v[0:1], v17, off sc1
	v_add_u32_e32 v0, v185, v16
	s_waitcnt vmcnt(15)
	v_fmac_f32_e32 v27, v2, v102
	global_load_dword v17, v[94:95], off offset:384
	v_ashrrev_i32_e32 v1, 31, v0
	v_mul_f32_e32 v2, v32, v27
	v_lshl_add_u64 v[0:1], v[0:1], 1, s[8:9]
	v_cvt_pk_bf16_f32 v2, v2, s0
	global_store_short v[0:1], v2, off sc1
	v_add_u32_e32 v0, v184, v16
	global_load_dword v2, v[96:97], off offset:384
	v_ashrrev_i32_e32 v1, 31, v0
	v_lshl_add_u64 v[0:1], v[0:1], 1, s[8:9]
	v_add_u32_e32 v30, v182, v16
	s_waitcnt vmcnt(17)
	v_fmac_f32_e32 v25, v4, v102
	v_ashrrev_i32_e32 v31, 31, v30
	v_lshl_add_u64 v[30:31], v[30:31], 1, s[8:9]
	s_waitcnt vmcnt(16)
	v_fmac_f32_e32 v24, v5, v102
	s_waitcnt vmcnt(15)
	v_fmac_f32_e32 v23, v6, v102
	s_waitcnt vmcnt(8)
	v_fmac_f32_e32 v26, v3, v102
	v_mul_f32_e32 v3, v32, v26
	v_cvt_pk_bf16_f32 v3, v3, s0
	global_store_short v[0:1], v3, off sc1
	global_load_dword v1, v[98:99], off offset:384
	v_mul_f32_e32 v0, v32, v25
	v_cvt_pk_bf16_f32 v0, v0, s0
	global_store_short v[30:31], v0, off sc1
	global_load_dword v0, v[100:101], off offset:384
	v_add_u32_e32 v30, v180, v16
	v_ashrrev_i32_e32 v31, 31, v30
	v_mul_f32_e32 v3, v32, v24
	v_lshl_add_u64 v[4:5], v[30:31], 1, s[8:9]
	v_cvt_pk_bf16_f32 v3, v3, s0
	global_store_short v[4:5], v3, off sc1
	v_add_u32_e32 v4, v71, v16
	v_ashrrev_i32_e32 v5, 31, v4
	v_mul_f32_e32 v3, v32, v23
	v_lshl_add_u64 v[4:5], v[4:5], 1, s[8:9]
	v_cvt_pk_bf16_f32 v3, v3, s0
	global_store_short v[4:5], v3, off sc1
	v_add_u32_e32 v4, v181, v16
	v_fmac_f32_e32 v22, v7, v102
	v_ashrrev_i32_e32 v5, 31, v4
	v_mul_f32_e32 v3, v32, v22
	v_lshl_add_u64 v[4:5], v[4:5], 1, s[8:9]
	v_cvt_pk_bf16_f32 v3, v3, s0
	global_store_short v[4:5], v3, off sc1
	v_add_u32_e32 v4, v183, v16
	v_fmac_f32_e32 v21, v8, v102
	v_ashrrev_i32_e32 v5, 31, v4
	v_mul_f32_e32 v3, v32, v21
	v_lshl_add_u64 v[4:5], v[4:5], 1, s[8:9]
	v_cvt_pk_bf16_f32 v3, v3, s0
	global_store_short v[4:5], v3, off sc1
	v_add_u32_e32 v4, v186, v16
	v_fmac_f32_e32 v20, v9, v102
	v_ashrrev_i32_e32 v5, 31, v4
	v_mul_f32_e32 v3, v32, v20
	v_lshl_add_u64 v[4:5], v[4:5], 1, s[8:9]
	v_cvt_pk_bf16_f32 v3, v3, s0
	global_store_short v[4:5], v3, off sc1
	v_add_u32_e32 v4, v188, v16
	s_waitcnt vmcnt(15)
	v_fmac_f32_e32 v19, v10, v102
	v_ashrrev_i32_e32 v5, 31, v4
	v_mul_f32_e32 v3, v32, v19
	v_lshl_add_u64 v[4:5], v[4:5], 1, s[8:9]
	v_cvt_pk_bf16_f32 v3, v3, s0
	global_store_short v[4:5], v3, off sc1
	v_add_u32_e32 v4, v189, v16
	s_waitcnt vmcnt(15)
	v_fmac_f32_e32 v18, v11, v102
	v_ashrrev_i32_e32 v5, 31, v4
	v_mul_f32_e32 v3, v32, v18
	v_lshl_add_u64 v[4:5], v[4:5], 1, s[8:9]
	v_cvt_pk_bf16_f32 v3, v3, s0
	global_store_short v[4:5], v3, off sc1
	v_add_u32_e32 v4, v190, v16
	v_ashrrev_i32_e32 v5, 31, v4
	v_lshl_add_u64 v[4:5], v[4:5], 1, s[8:9]
	v_ashrrev_i32_e32 v71, 31, v70
	global_store_dword v[88:89], v28, off offset:384 sc1
	global_store_dword v[84:85], v27, off offset:384 sc1
	global_store_dword v[82:83], v26, off offset:384 sc1
	global_store_dword v[78:79], v25, off offset:384 sc1
	s_waitcnt vmcnt(17)
	v_fmac_f32_e32 v17, v12, v102
	v_mul_f32_e32 v3, v32, v17
	v_cvt_pk_bf16_f32 v3, v3, s0
	global_store_short v[4:5], v3, off sc1
	v_add_u32_e32 v4, v192, v16
	v_ashrrev_i32_e32 v5, 31, v4
	v_lshl_add_u64 v[4:5], v[4:5], 1, s[8:9]
	s_waitcnt vmcnt(16)
	v_fmac_f32_e32 v2, v13, v102
	v_mul_f32_e32 v3, v32, v2
	v_cvt_pk_bf16_f32 v3, v3, s0
	global_store_short v[4:5], v3, off sc1
	v_add_u32_e32 v4, v193, v16
	v_ashrrev_i32_e32 v5, 31, v4
	v_lshl_add_u64 v[4:5], v[4:5], 1, s[8:9]
	v_xor_b32_e32 v12, 16, v165
	global_store_dword v[72:73], v24, off offset:384 sc1
	global_store_dword v[74:75], v23, off offset:384 sc1
	global_store_dword v[76:77], v22, off offset:384 sc1
	global_store_dword v[80:81], v21, off offset:384 sc1
	global_store_dword v[86:87], v20, off offset:384 sc1
	s_waitcnt vmcnt(20)
	v_fmac_f32_e32 v1, v14, v102
	v_mul_f32_e32 v3, v32, v1
	v_cvt_pk_bf16_f32 v3, v3, s0
	global_store_short v[4:5], v3, off sc1
	v_add_u32_e32 v4, v194, v16
	v_ashrrev_i32_e32 v5, 31, v4
	v_lshl_add_u64 v[10:11], v[4:5], 1, s[8:9]
	v_and_b32_e32 v4, 64, v165
	v_xor_b32_e32 v3, 1, v165
	v_add_u32_e32 v7, 64, v4
	v_cmp_lt_i32_e32 vcc, v3, v7
	v_xor_b32_e32 v4, 2, v165
	s_waitcnt vmcnt(19)
	v_fmac_f32_e32 v0, v15, v102
	v_cndmask_b32_e32 v3, v165, v3, vcc
	v_lshlrev_b32_e32 v3, 2, v3
	ds_bpermute_b32 v5, v3, v106
	v_cmp_lt_i32_e32 vcc, v4, v7
	global_store_dword v[90:91], v19, off offset:384 sc1
	global_store_dword v[92:93], v18, off offset:384 sc1
	v_cndmask_b32_e32 v4, v165, v4, vcc
	v_lshlrev_b32_e32 v4, 2, v4
	s_waitcnt lgkmcnt(0)
	v_add_f32_e32 v6, v106, v5
	ds_bpermute_b32 v8, v4, v6
	v_xor_b32_e32 v5, 4, v165
	v_cmp_lt_i32_e32 vcc, v5, v7
	global_store_dword v[94:95], v17, off offset:384 sc1
	global_store_dword v[96:97], v2, off offset:384 sc1
	v_cndmask_b32_e32 v5, v165, v5, vcc
	v_lshlrev_b32_e32 v5, 2, v5
	s_waitcnt lgkmcnt(0)
	v_add_f32_e32 v8, v6, v8
	ds_bpermute_b32 v9, v5, v8
	v_xor_b32_e32 v6, 8, v165
	v_cmp_lt_i32_e32 vcc, v6, v7
	global_store_dword v[98:99], v1, off offset:384 sc1
	global_store_dword v[100:101], v0, off offset:384 sc1
	v_cndmask_b32_e32 v6, v165, v6, vcc
	v_lshlrev_b32_e32 v6, 2, v6
	s_waitcnt lgkmcnt(0)
	v_add_f32_e32 v8, v8, v9
	ds_bpermute_b32 v9, v6, v8
	v_cmp_lt_i32_e32 vcc, v12, v7
	s_waitcnt lgkmcnt(0)
	v_add_f32_e32 v8, v8, v9
	v_cndmask_b32_e32 v7, v165, v12, vcc
	v_lshlrev_b32_e32 v7, 2, v7
	ds_bpermute_b32 v9, v7, v8
	v_mul_f32_e32 v12, v32, v0
	v_cvt_pk_bf16_f32 v12, v12, s0
	global_store_short v[10:11], v12, off sc1
	s_and_saveexec_b64 s[60:61], s[0:1]
	s_cbranch_execz .LBB0_781
	s_waitcnt lgkmcnt(0)
	v_add_f32_e32 v10, v8, v9
	v_lshl_add_u64 v[8:9], v[70:71], 2, s[58:59]
	global_store_dword v[8:9], v10, off sc1

.LBB0_1050:
	s_add_i32 s58, s66, 0xffffe000
	s_lshr_b32 s58, s58, 12
	s_mulk_i32 s58, 0x1800
	v_mov_b32_e32 v70, s70
	s_addk_i32 s58, 0x6000
	ds_read_b64 v[70:71], v70
	s_cmp_gt_i32 s6, 63
	s_cselect_b32 s6, s58, 0x4800
	s_lshl_b64 s[58:59], s[6:7], 2
	s_add_u32 s6, s14, s58
	s_addc_u32 s65, s15, s59
	s_waitcnt lgkmcnt(0)
	v_readfirstlane_b32 s58, v70
	v_readfirstlane_b32 s59, v71
	s_add_u32 s60, s58, 0x1000
	s_addc_u32 s61, s59, 0
	s_lshl_b32 s58, s64, 14
	s_add_i32 s58, s58, 0x60000
	s_ashr_i32 s59, s58, 31
	s_lshl_b64 s[58:59], s[58:59], 2
	s_add_u32 s58, s10, s58
	s_addc_u32 s59, s11, s59
	s_add_u32 s62, s6, 0x5ba2000
	v_or_b32_e32 v102, s68, v138
	v_add_u32_e32 v70, s66, v139
	s_addc_u32 s63, s65, 0
	v_lshlrev_b32_e32 v188, 10, v70
	v_ashrrev_i32_e32 v103, 31, v102
	s_add_u32 s64, s6, 0x5ba4000
	v_lshlrev_b64 v[72:73], 2, v[102:103]
	v_or_b32_e32 v186, 0x400, v188
	v_or_b32_e32 v185, 0x4400, v188
	v_or_b32_e32 v189, 0x4c00, v188
	v_or_b32_e32 v193, 0x6c00, v188
	s_addc_u32 s65, s65, 0
	v_lshl_add_u64 v[74:75], s[62:63], 0, v[72:73]
	v_add_u32_e32 v132, v188, v102
	v_add_u32_e32 v134, v186, v102
	v_or_b32_e32 v184, 0x800, v188
	v_or_b32_e32 v183, 0xc00, v188
	v_or_b32_e32 v181, 0x2000, v188
	v_or_b32_e32 v179, 0x2400, v188
	v_or_b32_e32 v71, 0x2800, v188
	v_or_b32_e32 v180, 0x2c00, v188
	v_or_b32_e32 v182, 0x4000, v188
	v_add_u32_e32 v112, v185, v102
	v_or_b32_e32 v187, 0x4800, v188
	v_add_u32_e32 v118, v189, v102
	v_or_b32_e32 v190, 0x6000, v188
	v_or_b32_e32 v191, 0x6400, v188
	v_or_b32_e32 v192, 0x6800, v188
	v_add_u32_e32 v128, v193, v102
	global_load_dword v194, v[74:75], off
	global_load_dword v205, v[74:75], off offset:128
	v_lshl_add_u64 v[74:75], s[60:61], 0, v[72:73]
	v_lshl_add_u64 v[72:73], s[64:65], 0, v[72:73]
	v_ashrrev_i32_e32 v135, 31, v134
	v_add_u32_e32 v136, v184, v102
	v_add_u32_e32 v130, v183, v102
	v_add_u32_e32 v122, v181, v102
	v_add_u32_e32 v114, v179, v102
	v_add_u32_e32 v106, v71, v102
	v_add_u32_e32 v108, v180, v102
	v_add_u32_e32 v110, v182, v102
	v_ashrrev_i32_e32 v113, 31, v112
	v_add_u32_e32 v116, v187, v102
	v_ashrrev_i32_e32 v119, 31, v118
	v_add_u32_e32 v120, v190, v102
	v_add_u32_e32 v124, v191, v102
	v_add_u32_e32 v126, v192, v102
	v_ashrrev_i32_e32 v129, 31, v128
	v_ashrrev_i32_e32 v133, 31, v132
	global_load_dword v196, v[72:73], off
	global_load_dword v203, v[72:73], off offset:128
	v_lshl_add_u64 v[88:89], v[134:135], 2, s[12:13]
	v_ashrrev_i32_e32 v137, 31, v136
	v_ashrrev_i32_e32 v131, 31, v130
	v_ashrrev_i32_e32 v123, 31, v122
	v_ashrrev_i32_e32 v115, 31, v114
	v_ashrrev_i32_e32 v107, 31, v106
	v_ashrrev_i32_e32 v109, 31, v108
	v_ashrrev_i32_e32 v111, 31, v110
	v_lshl_add_u64 v[86:87], v[112:113], 2, s[12:13]
	v_ashrrev_i32_e32 v117, 31, v116
	v_lshl_add_u64 v[92:93], v[118:119], 2, s[12:13]
	v_ashrrev_i32_e32 v121, 31, v120
	v_ashrrev_i32_e32 v125, 31, v124
	v_ashrrev_i32_e32 v127, 31, v126
	v_lshl_add_u64 v[100:101], v[128:129], 2, s[12:13]
	v_lshl_add_u64 v[104:105], v[132:133], 2, s[12:13]
	global_load_dword v195, v[74:75], off
	global_load_dword v204, v[74:75], off offset:128
	v_lshl_add_u64 v[84:85], v[136:137], 2, s[12:13]
	v_lshl_add_u64 v[82:83], v[130:131], 2, s[12:13]
	v_lshl_add_u64 v[78:79], v[122:123], 2, s[12:13]
	v_lshl_add_u64 v[72:73], v[114:115], 2, s[12:13]
	v_lshl_add_u64 v[74:75], v[106:107], 2, s[12:13]
	v_lshl_add_u64 v[76:77], v[108:109], 2, s[12:13]
	v_lshl_add_u64 v[80:81], v[110:111], 2, s[12:13]
	global_load_dword v178, v[88:89], off
	global_load_dword v177, v[84:85], off
	global_load_dword v176, v[82:83], off
	global_load_dword v175, v[78:79], off
	global_load_dword v174, v[72:73], off
	global_load_dword v173, v[74:75], off
	global_load_dword v172, v[76:77], off
	global_load_dword v171, v[80:81], off
	v_lshl_add_u64 v[90:91], v[116:117], 2, s[12:13]
	global_load_dword v170, v[86:87], off
	global_load_dword v168, v[90:91], off
	v_lshl_add_u64 v[94:95], v[120:121], 2, s[12:13]
	v_lshl_add_u64 v[96:97], v[124:125], 2, s[12:13]
	v_lshl_add_u64 v[98:99], v[126:127], 2, s[12:13]
	global_load_dword v169, v[92:93], off
	global_load_dword v167, v[94:95], off
	global_load_dword v166, v[96:97], off
	global_load_dword v165, v[98:99], off
	global_load_dword v103, v[100:101], off
	global_load_dword v197, v[104:105], off
	v_lshl_add_u64 v[106:107], v[106:107], 1, s[8:9]
	global_load_dword v202, v[104:105], off offset:128
	global_load_dword v206, v[84:85], off offset:128
	global_load_dword v207, v[78:79], off offset:128
	global_load_dword v208, v[72:73], off offset:128
	global_load_dword v209, v[74:75], off offset:128
	global_load_dword v210, v[80:81], off offset:128
	global_load_dword v211, v[76:77], off offset:128
	global_load_dword v212, v[86:87], off offset:128
	global_load_dword v213, v[82:83], off offset:128
	global_load_dword v214, v[90:91], off offset:128
	global_load_dword v215, v[92:93], off offset:128
	global_load_dword v216, v[94:95], off offset:128
	global_load_dword v217, v[96:97], off offset:128
	global_load_dword v218, v[98:99], off offset:128
	global_load_dword v219, v[100:101], off offset:128
	global_load_dword v220, v[88:89], off offset:128
	s_waitcnt vmcnt(0)
	v_add_f32_e32 v196, 1.0, v196
	v_mul_f32_e32 v195, v195, v196
	v_fmac_f32_e32 v178, v49, v194
	v_fmac_f32_e32 v177, v50, v194
	v_fmac_f32_e32 v176, v51, v194
	v_fmac_f32_e32 v175, v52, v194
	v_fmac_f32_e32 v174, v53, v194
	v_fmac_f32_e32 v173, v54, v194
	v_fmac_f32_e32 v172, v55, v194
	v_fmac_f32_e32 v171, v56, v194
	v_fmac_f32_e32 v170, v57, v194
	v_fmac_f32_e32 v168, v58, v194
	v_fmac_f32_e32 v169, v59, v194
	v_fmac_f32_e32 v167, v60, v194
	v_fmac_f32_e32 v166, v61, v194
	v_fmac_f32_e32 v165, v62, v194
	v_fmac_f32_e32 v103, v63, v194
	v_fmac_f32_e32 v197, v48, v194
	v_mul_f32_e32 v48, v195, v197
	v_cvt_pk_bf16_f32 v58, v48, s0
	v_or_b32_e32 v48, 32, v102
	v_ashrrev_i32_e32 v49, 31, v48
	v_lshlrev_b64 v[52:53], 2, v[48:49]
	global_store_dword v[88:89], v178, off sc1
	global_store_dword v[84:85], v177, off sc1
	global_store_dword v[82:83], v176, off sc1
	global_store_dword v[78:79], v175, off sc1
	global_store_dword v[72:73], v174, off sc1
	global_store_dword v[74:75], v173, off sc1
	global_store_dword v[76:77], v172, off sc1
	global_store_dword v[80:81], v171, off sc1
	global_store_dword v[86:87], v170, off sc1
	global_store_dword v[90:91], v168, off sc1
	global_store_dword v[92:93], v169, off sc1
	global_store_dword v[94:95], v167, off sc1
	global_store_dword v[96:97], v166, off sc1
	global_store_dword v[98:99], v165, off sc1
	global_store_dword v[100:101], v103, off sc1
	global_store_dword v[104:105], v197, off sc1
	v_lshl_add_u64 v[50:51], v[132:133], 1, s[8:9]
	v_lshl_add_u64 v[56:57], s[64:65], 0, v[52:53]
	v_mov_b32_e32 v196, v202
	v_lshl_add_u64 v[54:55], s[60:61], 0, v[52:53]
	v_mov_b32_e32 v132, v203
	v_mov_b32_e32 v133, v204
	v_mul_f32_e32 v49, v195, v178
	global_store_short v[50:51], v58, off sc1
	v_lshl_add_u64 v[50:51], s[62:63], 0, v[52:53]
	v_mov_b32_e32 v194, v205
	v_cvt_pk_bf16_f32 v49, v49, s0
	v_lshl_add_u64 v[50:51], v[134:135], 1, s[8:9]
	global_store_short v[50:51], v49, off sc1
	v_mul_f32_e32 v49, v195, v177
	v_cvt_pk_bf16_f32 v49, v49, s0
	v_lshl_add_u64 v[50:51], v[136:137], 1, s[8:9]
	global_store_short v[50:51], v49, off sc1
	v_mul_f32_e32 v49, v195, v176
	v_cvt_pk_bf16_f32 v49, v49, s0
	v_lshl_add_u64 v[50:51], v[130:131], 1, s[8:9]
	global_store_short v[50:51], v49, off sc1
	v_mul_f32_e32 v49, v195, v175
	v_cvt_pk_bf16_f32 v49, v49, s0
	v_lshl_add_u64 v[50:51], v[122:123], 1, s[8:9]
	global_store_short v[50:51], v49, off sc1
	v_mul_f32_e32 v49, v195, v174
	v_cvt_pk_bf16_f32 v49, v49, s0
	v_lshl_add_u64 v[50:51], v[114:115], 1, s[8:9]
	global_store_short v[50:51], v49, off sc1
	v_mul_f32_e32 v49, v195, v173
	v_mov_b32_e32 v62, v206
	v_mov_b32_e32 v60, v207
	v_mov_b32_e32 v59, v208
	v_mov_b32_e32 v58, v209
	v_mov_b32_e32 v56, v210
	v_mov_b32_e32 v57, v211
	v_mov_b32_e32 v55, v212
	v_mov_b32_e32 v61, v213
	v_mov_b32_e32 v54, v214
	v_mov_b32_e32 v53, v215
	v_mov_b32_e32 v52, v216
	v_mov_b32_e32 v51, v217
	v_mov_b32_e32 v50, v218
	v_cvt_pk_bf16_f32 v63, v49, s0
	v_mov_b32_e32 v49, v219
	v_fmac_f32_e32 v196, v32, v194
	global_store_short v[106:107], v63, off sc1
	v_mov_b32_e32 v63, v220
	v_mul_f32_e32 v106, v195, v172
	v_cvt_pk_bf16_f32 v114, v106, s0
	v_lshl_add_u64 v[106:107], v[108:109], 1, s[8:9]
	global_store_short v[106:107], v114, off sc1
	v_mul_f32_e32 v106, v195, v171
	v_cvt_pk_bf16_f32 v108, v106, s0
	v_lshl_add_u64 v[106:107], v[110:111], 1, s[8:9]
	global_store_short v[106:107], v108, off sc1
	v_mul_f32_e32 v106, v195, v170
	v_cvt_pk_bf16_f32 v108, v106, s0
	v_lshl_add_u64 v[106:107], v[112:113], 1, s[8:9]
	global_store_short v[106:107], v108, off sc1
	v_mul_f32_e32 v106, v195, v168
	v_cvt_pk_bf16_f32 v108, v106, s0
	v_lshl_add_u64 v[106:107], v[116:117], 1, s[8:9]
	global_store_short v[106:107], v108, off sc1
	v_mul_f32_e32 v106, v195, v169
	v_cvt_pk_bf16_f32 v108, v106, s0
	v_lshl_add_u64 v[106:107], v[118:119], 1, s[8:9]
	global_store_short v[106:107], v108, off sc1
	v_mul_f32_e32 v106, v195, v167
	v_cvt_pk_bf16_f32 v108, v106, s0
	v_lshl_add_u64 v[106:107], v[120:121], 1, s[8:9]
	global_store_short v[106:107], v108, off sc1
	v_mul_f32_e32 v106, v195, v166
	v_cvt_pk_bf16_f32 v108, v106, s0
	v_lshl_add_u64 v[106:107], v[124:125], 1, s[8:9]
	global_store_short v[106:107], v108, off sc1
	v_mul_f32_e32 v106, v195, v165
	v_cvt_pk_bf16_f32 v108, v106, s0
	v_lshl_add_u64 v[106:107], v[126:127], 1, s[8:9]
	global_store_short v[106:107], v108, off sc1
	v_mul_f32_e32 v106, v195, v103
	v_cvt_pk_bf16_f32 v108, v106, s0
	v_lshl_add_u64 v[106:107], v[128:129], 1, s[8:9]
	global_store_short v[106:107], v108, off sc1
	v_add_f32_e32 v106, 1.0, v132
	v_mul_f32_e32 v110, v133, v106
	v_add_u32_e32 v106, v188, v48
	v_fmac_f32_e32 v62, v34, v194
	v_fmac_f32_e32 v61, v35, v194
	v_fmac_f32_e32 v60, v36, v194
	v_fmac_f32_e32 v59, v37, v194
	v_fmac_f32_e32 v58, v38, v194
	v_fmac_f32_e32 v57, v39, v194
	v_fmac_f32_e32 v56, v40, v194
	v_fmac_f32_e32 v55, v41, v194
	v_fmac_f32_e32 v54, v42, v194
	v_fmac_f32_e32 v53, v43, v194
	v_fmac_f32_e32 v52, v44, v194
	v_fmac_f32_e32 v51, v45, v194
	v_fmac_f32_e32 v50, v46, v194
	v_fmac_f32_e32 v49, v47, v194
	v_ashrrev_i32_e32 v107, 31, v106
	global_store_dword v[104:105], v196, off offset:128 sc1
	v_mul_f32_e32 v32, v110, v196
	global_store_dword v[84:85], v62, off offset:128 sc1
	global_store_dword v[82:83], v61, off offset:128 sc1
	global_store_dword v[78:79], v60, off offset:128 sc1
	global_store_dword v[72:73], v59, off offset:128 sc1
	global_store_dword v[74:75], v58, off offset:128 sc1
	global_store_dword v[76:77], v57, off offset:128 sc1
	global_store_dword v[80:81], v56, off offset:128 sc1
	global_store_dword v[86:87], v55, off offset:128 sc1
	global_store_dword v[90:91], v54, off offset:128 sc1
	global_store_dword v[92:93], v53, off offset:128 sc1
	global_store_dword v[94:95], v52, off offset:128 sc1
	global_store_dword v[96:97], v51, off offset:128 sc1
	global_store_dword v[98:99], v50, off offset:128 sc1
	global_store_dword v[100:101], v49, off offset:128 sc1
	v_cvt_pk_bf16_f32 v32, v32, s0
	v_lshl_add_u64 v[106:107], v[106:107], 1, s[8:9]
	v_add_u32_e32 v108, v186, v48
	global_load_dword v45, v[88:89], off offset:256
	v_ashrrev_i32_e32 v109, 31, v108
	global_store_short v[106:107], v32, off sc1
	v_mul_f32_e32 v113, v110, v56
	v_cvt_pk_bf16_f32 v113, v113, s0
	v_mul_f32_e32 v106, v196, v196
	s_waitcnt vmcnt(26)
	v_fmac_f32_e32 v63, v33, v194
	v_mul_f32_e32 v32, v110, v63
	v_cvt_pk_bf16_f32 v34, v32, s0
	v_lshl_add_u64 v[32:33], v[108:109], 1, s[8:9]
	global_store_short v[32:33], v34, off sc1
	v_add_u32_e32 v32, v184, v48
	v_ashrrev_i32_e32 v33, 31, v32
	v_mul_f32_e32 v34, v110, v62
	v_cvt_pk_bf16_f32 v34, v34, s0
	v_lshl_add_u64 v[32:33], v[32:33], 1, s[8:9]
	global_store_short v[32:33], v34, off sc1
	v_add_u32_e32 v32, v183, v48
	v_ashrrev_i32_e32 v33, 31, v32
	v_mul_f32_e32 v34, v110, v61
	v_cvt_pk_bf16_f32 v34, v34, s0
	v_lshl_add_u64 v[32:33], v[32:33], 1, s[8:9]
	global_store_short v[32:33], v34, off sc1
	v_add_u32_e32 v32, v181, v48
	v_ashrrev_i32_e32 v33, 31, v32
	v_mul_f32_e32 v34, v110, v60
	v_cvt_pk_bf16_f32 v34, v34, s0
	v_lshl_add_u64 v[32:33], v[32:33], 1, s[8:9]
	global_store_short v[32:33], v34, off sc1
	v_add_u32_e32 v32, v179, v48
	v_ashrrev_i32_e32 v33, 31, v32
	v_mul_f32_e32 v34, v110, v59
	v_cvt_pk_bf16_f32 v42, v34, s0
	v_lshl_add_u64 v[34:35], v[32:33], 1, s[8:9]
	v_or_b32_e32 v32, 64, v102
	v_ashrrev_i32_e32 v33, 31, v32
	v_lshlrev_b64 v[36:37], 2, v[32:33]
	global_store_dword v[88:89], v63, off offset:128 sc1
	v_lshl_add_u64 v[40:41], s[64:65], 0, v[36:37]
	v_lshl_add_u64 v[38:39], s[60:61], 0, v[36:37]
	global_load_dword v107, v[40:41], off
	global_load_dword v111, v[38:39], off
	v_mul_f32_e32 v33, v110, v58
	global_store_short v[34:35], v42, off sc1
	v_lshl_add_u64 v[34:35], s[62:63], 0, v[36:37]
	global_load_dword v112, v[34:35], off
	v_add_u32_e32 v34, v71, v48
	v_ashrrev_i32_e32 v35, 31, v34
	v_cvt_pk_bf16_f32 v33, v33, s0
	v_lshl_add_u64 v[34:35], v[34:35], 1, s[8:9]
	global_store_short v[34:35], v33, off sc1
	v_add_u32_e32 v34, v180, v48
	v_ashrrev_i32_e32 v35, 31, v34
	v_mul_f32_e32 v33, v110, v57
	v_cvt_pk_bf16_f32 v33, v33, s0
	v_lshl_add_u64 v[34:35], v[34:35], 1, s[8:9]
	global_load_dword v38, v[90:91], off offset:256
	global_load_dword v37, v[92:93], off offset:256
	global_load_dword v36, v[94:95], off offset:256
	global_load_dword v114, v[104:105], off offset:256
	global_load_dword v47, v[84:85], off offset:256
	global_load_dword v39, v[86:87], off offset:256
	global_load_dword v46, v[82:83], off offset:256
	global_load_dword v44, v[78:79], off offset:256
	global_load_dword v43, v[72:73], off offset:256
	global_load_dword v42, v[74:75], off offset:256
	global_load_dword v40, v[80:81], off offset:256
	global_load_dword v41, v[76:77], off offset:256
	v_add_u32_e32 v108, v182, v48
	global_store_short v[34:35], v33, off sc1
	global_load_dword v35, v[96:97], off offset:256
	v_ashrrev_i32_e32 v109, 31, v108
	global_load_dword v34, v[98:99], off offset:256
	global_load_dword v33, v[100:101], off offset:256
	v_lshl_add_u64 v[108:109], v[108:109], 1, s[8:9]
	global_store_short v[108:109], v113, off sc1
	v_add_u32_e32 v108, v185, v48
	v_ashrrev_i32_e32 v109, 31, v108
	v_mul_f32_e32 v113, v110, v55
	v_cvt_pk_bf16_f32 v113, v113, s0
	v_lshl_add_u64 v[108:109], v[108:109], 1, s[8:9]
	global_store_short v[108:109], v113, off sc1
	v_add_u32_e32 v108, v187, v48
	v_ashrrev_i32_e32 v109, 31, v108
	v_mul_f32_e32 v113, v110, v54
	v_cvt_pk_bf16_f32 v113, v113, s0
	v_lshl_add_u64 v[108:109], v[108:109], 1, s[8:9]
	global_store_short v[108:109], v113, off sc1
	v_add_u32_e32 v108, v189, v48
	v_ashrrev_i32_e32 v109, 31, v108
	v_mul_f32_e32 v113, v110, v53
	v_cvt_pk_bf16_f32 v113, v113, s0
	v_lshl_add_u64 v[108:109], v[108:109], 1, s[8:9]
	global_store_short v[108:109], v113, off sc1
	v_add_u32_e32 v108, v190, v48
	v_ashrrev_i32_e32 v109, 31, v108
	v_mul_f32_e32 v113, v110, v52
	v_cvt_pk_bf16_f32 v113, v113, s0
	v_lshl_add_u64 v[108:109], v[108:109], 1, s[8:9]
	global_store_short v[108:109], v113, off sc1
	v_add_u32_e32 v108, v191, v48
	v_ashrrev_i32_e32 v109, 31, v108
	v_mul_f32_e32 v113, v110, v51
	v_cvt_pk_bf16_f32 v113, v113, s0
	v_lshl_add_u64 v[108:109], v[108:109], 1, s[8:9]
	global_store_short v[108:109], v113, off sc1
	v_add_u32_e32 v108, v192, v48
	v_ashrrev_i32_e32 v109, 31, v108
	v_mul_f32_e32 v113, v110, v50
	v_cvt_pk_bf16_f32 v113, v113, s0
	v_lshl_add_u64 v[108:109], v[108:109], 1, s[8:9]
	global_store_short v[108:109], v113, off sc1
	v_add_u32_e32 v108, v193, v48
	v_ashrrev_i32_e32 v109, 31, v108
	v_mul_f32_e32 v48, v110, v49
	v_cvt_pk_bf16_f32 v48, v48, s0
	v_lshl_add_u64 v[108:109], v[108:109], 1, s[8:9]
	global_store_short v[108:109], v48, off sc1
	v_add_u32_e32 v108, v188, v32
	v_ashrrev_i32_e32 v109, 31, v108
	s_waitcnt vmcnt(28)
	v_add_f32_e32 v48, 1.0, v107
	s_waitcnt vmcnt(27)
	v_mul_f32_e32 v48, v111, v48
	v_fmac_f32_e32 v106, v197, v197
	s_waitcnt vmcnt(25)
	v_fmac_f32_e32 v45, v17, v112
	global_store_dword v[88:89], v45, off offset:256 sc1
	s_waitcnt vmcnt(24)
	v_fmac_f32_e32 v38, v26, v112
	s_waitcnt vmcnt(23)
	v_fmac_f32_e32 v37, v27, v112
	s_waitcnt vmcnt(22)
	v_fmac_f32_e32 v36, v28, v112
	s_waitcnt vmcnt(21)
	v_fmac_f32_e32 v114, v16, v112
	v_mul_f32_e32 v16, v48, v114
	s_waitcnt vmcnt(20)
	v_fmac_f32_e32 v47, v18, v112
	v_cvt_pk_bf16_f32 v18, v16, s0
	v_lshl_add_u64 v[16:17], v[108:109], 1, s[8:9]
	global_store_short v[16:17], v18, off sc1
	v_add_u32_e32 v16, v186, v32
	v_ashrrev_i32_e32 v17, 31, v16
	v_mul_f32_e32 v18, v48, v45
	v_cvt_pk_bf16_f32 v18, v18, s0
	v_lshl_add_u64 v[16:17], v[16:17], 1, s[8:9]
	global_store_short v[16:17], v18, off sc1
	v_add_u32_e32 v16, v184, v32
	v_ashrrev_i32_e32 v17, 31, v16
	v_mul_f32_e32 v18, v48, v47
	v_cvt_pk_bf16_f32 v18, v18, s0
	v_lshl_add_u64 v[16:17], v[16:17], 1, s[8:9]
	s_waitcnt vmcnt(20)
	v_fmac_f32_e32 v46, v19, v112
	global_store_short v[16:17], v18, off sc1
	v_add_u32_e32 v16, v183, v32
	v_ashrrev_i32_e32 v17, 31, v16
	v_mul_f32_e32 v18, v48, v46
	s_waitcnt vmcnt(20)
	v_fmac_f32_e32 v44, v20, v112
	v_cvt_pk_bf16_f32 v18, v18, s0
	v_lshl_add_u64 v[16:17], v[16:17], 1, s[8:9]
	global_store_short v[16:17], v18, off sc1
	v_mul_f32_e32 v16, v48, v44
	v_cvt_pk_bf16_f32 v26, v16, s0
	v_or_b32_e32 v16, 0x60, v102
	v_add_u32_e32 v18, v181, v32
	v_ashrrev_i32_e32 v17, 31, v16
	s_waitcnt vmcnt(20)
	v_fmac_f32_e32 v43, v21, v112
	s_waitcnt vmcnt(19)
	v_fmac_f32_e32 v42, v22, v112
	s_waitcnt vmcnt(17)
	v_fmac_f32_e32 v41, v23, v112
	v_fmac_f32_e32 v40, v24, v112
	v_fmac_f32_e32 v39, v25, v112
	s_waitcnt vmcnt(15)
	v_fmac_f32_e32 v35, v29, v112
	s_waitcnt vmcnt(14)
	v_fmac_f32_e32 v34, v30, v112
	s_waitcnt vmcnt(13)
	v_fmac_f32_e32 v33, v31, v112
	v_ashrrev_i32_e32 v19, 31, v18
	v_lshlrev_b64 v[20:21], 2, v[16:17]
	global_store_dword v[84:85], v47, off offset:256 sc1
	global_store_dword v[82:83], v46, off offset:256 sc1
	global_store_dword v[78:79], v44, off offset:256 sc1
	global_store_dword v[72:73], v43, off offset:256 sc1
	global_store_dword v[74:75], v42, off offset:256 sc1
	global_store_dword v[76:77], v41, off offset:256 sc1
	global_store_dword v[80:81], v40, off offset:256 sc1
	global_store_dword v[86:87], v39, off offset:256 sc1
	global_store_dword v[90:91], v38, off offset:256 sc1
	global_store_dword v[92:93], v37, off offset:256 sc1
	global_store_dword v[94:95], v36, off offset:256 sc1
	global_store_dword v[96:97], v35, off offset:256 sc1
	global_store_dword v[98:99], v34, off offset:256 sc1
	global_store_dword v[100:101], v33, off offset:256 sc1
	global_store_dword v[104:105], v114, off offset:256 sc1
	v_lshl_add_u64 v[24:25], s[64:65], 0, v[20:21]
	v_lshl_add_u64 v[18:19], v[18:19], 1, s[8:9]
	global_load_dword v29, v[104:105], off offset:384
	v_lshl_add_u64 v[22:23], s[60:61], 0, v[20:21]
	global_load_dword v17, v[24:25], off
	global_load_dword v30, v[22:23], off
	global_load_dword v28, v[88:89], off offset:384
	global_load_dword v27, v[84:85], off offset:384
	v_fmac_f32_e32 v106, v114, v114
	global_store_short v[18:19], v26, off sc1
	v_lshl_add_u64 v[18:19], s[62:63], 0, v[20:21]
	global_load_dword v102, v[18:19], off
	v_add_u32_e32 v18, v179, v32
	v_ashrrev_i32_e32 v19, 31, v18
	v_mul_f32_e32 v20, v48, v43
	v_cvt_pk_bf16_f32 v20, v20, s0
	v_lshl_add_u64 v[18:19], v[18:19], 1, s[8:9]
	global_store_short v[18:19], v20, off sc1
	v_add_u32_e32 v18, v71, v32
	v_ashrrev_i32_e32 v19, 31, v18
	v_mul_f32_e32 v20, v48, v42
	v_cvt_pk_bf16_f32 v20, v20, s0
	v_lshl_add_u64 v[18:19], v[18:19], 1, s[8:9]
	global_store_short v[18:19], v20, off sc1
	v_add_u32_e32 v18, v180, v32
	v_ashrrev_i32_e32 v19, 31, v18
	v_mul_f32_e32 v20, v48, v41
	v_cvt_pk_bf16_f32 v20, v20, s0
	v_lshl_add_u64 v[18:19], v[18:19], 1, s[8:9]
	global_store_short v[18:19], v20, off sc1
	v_add_u32_e32 v18, v182, v32
	v_ashrrev_i32_e32 v19, 31, v18
	v_mul_f32_e32 v20, v48, v40
	v_cvt_pk_bf16_f32 v20, v20, s0
	v_lshl_add_u64 v[18:19], v[18:19], 1, s[8:9]
	global_store_short v[18:19], v20, off sc1
	v_add_u32_e32 v18, v185, v32
	v_ashrrev_i32_e32 v19, 31, v18
	v_mul_f32_e32 v20, v48, v39
	v_cvt_pk_bf16_f32 v20, v20, s0
	v_lshl_add_u64 v[18:19], v[18:19], 1, s[8:9]
	global_store_short v[18:19], v20, off sc1
	v_add_u32_e32 v18, v187, v32
	v_ashrrev_i32_e32 v19, 31, v18
	v_mul_f32_e32 v20, v48, v38
	v_cvt_pk_bf16_f32 v20, v20, s0
	v_lshl_add_u64 v[18:19], v[18:19], 1, s[8:9]
	global_store_short v[18:19], v20, off sc1
	v_add_u32_e32 v18, v189, v32
	v_ashrrev_i32_e32 v19, 31, v18
	v_mul_f32_e32 v20, v48, v37
	v_cvt_pk_bf16_f32 v20, v20, s0
	v_lshl_add_u64 v[18:19], v[18:19], 1, s[8:9]
	global_store_short v[18:19], v20, off sc1
	v_add_u32_e32 v18, v190, v32
	v_ashrrev_i32_e32 v19, 31, v18
	v_mul_f32_e32 v20, v48, v36
	v_cvt_pk_bf16_f32 v20, v20, s0
	v_lshl_add_u64 v[18:19], v[18:19], 1, s[8:9]
	global_store_short v[18:19], v20, off sc1
	v_add_u32_e32 v18, v191, v32
	v_ashrrev_i32_e32 v19, 31, v18
	v_mul_f32_e32 v20, v48, v35
	v_cvt_pk_bf16_f32 v20, v20, s0
	v_lshl_add_u64 v[18:19], v[18:19], 1, s[8:9]
	global_store_short v[18:19], v20, off sc1
	v_add_u32_e32 v18, v192, v32
	v_ashrrev_i32_e32 v19, 31, v18
	v_mul_f32_e32 v20, v48, v34
	v_cvt_pk_bf16_f32 v20, v20, s0
	v_lshl_add_u64 v[18:19], v[18:19], 1, s[8:9]
	global_store_short v[18:19], v20, off sc1
	v_add_u32_e32 v18, v193, v32
	v_ashrrev_i32_e32 v19, 31, v18
	v_mul_f32_e32 v20, v48, v33
	v_cvt_pk_bf16_f32 v20, v20, s0
	v_lshl_add_u64 v[18:19], v[18:19], 1, s[8:9]
	global_store_short v[18:19], v20, off sc1
	global_load_dword v20, v[86:87], off offset:384
	v_add_u32_e32 v18, v188, v16
	global_load_dword v26, v[82:83], off offset:384
	global_load_dword v25, v[78:79], off offset:384
	global_load_dword v24, v[72:73], off offset:384
	global_load_dword v23, v[74:75], off offset:384
	global_load_dword v21, v[80:81], off offset:384
	global_load_dword v22, v[76:77], off offset:384
	s_waitcnt vmcnt(23)
	v_add_f32_e32 v17, 1.0, v17
	s_waitcnt vmcnt(22)
	v_mul_f32_e32 v32, v30, v17
	v_ashrrev_i32_e32 v19, 31, v18
	v_lshl_add_u64 v[18:19], v[18:19], 1, s[8:9]
	v_add_u32_e32 v30, v186, v16
	s_waitcnt vmcnt(18)
	v_fmac_f32_e32 v29, v0, v102
	v_mul_f32_e32 v0, v32, v29
	v_cvt_pk_bf16_f32 v0, v0, s0
	global_store_short v[18:19], v0, off sc1
	global_load_dword v19, v[90:91], off offset:384
	v_ashrrev_i32_e32 v31, 31, v30
	global_load_dword v18, v[92:93], off offset:384
	v_fmac_f32_e32 v28, v1, v102
	v_mul_f32_e32 v0, v32, v28
	v_cvt_pk_bf16_f32 v17, v0, s0
	v_lshl_add_u64 v[0:1], v[30:31], 1, s[8:9]
	global_store_short v[0:1], v17, off sc1
	v_add_u32_e32 v0, v184, v16
	v_fmac_f32_e32 v27, v2, v102
	global_load_dword v17, v[94:95], off offset:384
	v_ashrrev_i32_e32 v1, 31, v0
	v_mul_f32_e32 v2, v32, v27
	v_cvt_pk_bf16_f32 v2, v2, s0
	v_lshl_add_u64 v[0:1], v[0:1], 1, s[8:9]
	global_store_short v[0:1], v2, off sc1
	v_add_u32_e32 v0, v183, v16
	global_load_dword v2, v[96:97], off offset:384
	v_ashrrev_i32_e32 v1, 31, v0
	v_lshl_add_u64 v[0:1], v[0:1], 1, s[8:9]
	v_add_u32_e32 v30, v181, v16
	v_ashrrev_i32_e32 v31, 31, v30
	v_lshl_add_u64 v[30:31], v[30:31], 1, s[8:9]
	v_fmac_f32_e32 v106, v29, v29
	global_store_dword v[104:105], v29, off offset:384 sc1
	global_store_dword v[88:89], v28, off offset:384 sc1
	global_store_dword v[84:85], v27, off offset:384 sc1
	s_waitcnt vmcnt(16)
	v_fmac_f32_e32 v20, v9, v102
	global_store_dword v[86:87], v20, off offset:384 sc1
	s_waitcnt vmcnt(16)
	v_fmac_f32_e32 v26, v3, v102
	v_mul_f32_e32 v3, v32, v26
	v_cvt_pk_bf16_f32 v3, v3, s0
	global_store_short v[0:1], v3, off sc1
	global_load_dword v1, v[98:99], off offset:384
	s_waitcnt vmcnt(17)
	v_fmac_f32_e32 v25, v4, v102
	v_mul_f32_e32 v0, v32, v25
	v_cvt_pk_bf16_f32 v0, v0, s0
	global_store_short v[30:31], v0, off sc1
	global_load_dword v0, v[100:101], off offset:384
	v_add_u32_e32 v30, v179, v16
	s_waitcnt vmcnt(18)
	v_fmac_f32_e32 v24, v5, v102
	v_ashrrev_i32_e32 v31, 31, v30
	v_mul_f32_e32 v3, v32, v24
	v_cvt_pk_bf16_f32 v3, v3, s0
	v_lshl_add_u64 v[4:5], v[30:31], 1, s[8:9]
	global_store_short v[4:5], v3, off sc1
	v_add_u32_e32 v4, v71, v16
	s_waitcnt vmcnt(18)
	v_fmac_f32_e32 v23, v6, v102
	v_ashrrev_i32_e32 v5, 31, v4
	v_mul_f32_e32 v3, v32, v23
	v_cvt_pk_bf16_f32 v3, v3, s0
	v_lshl_add_u64 v[4:5], v[4:5], 1, s[8:9]
	global_store_short v[4:5], v3, off sc1
	v_add_u32_e32 v4, v180, v16
	s_waitcnt vmcnt(17)
	v_fmac_f32_e32 v22, v7, v102
	v_ashrrev_i32_e32 v5, 31, v4
	v_mul_f32_e32 v3, v32, v22
	v_cvt_pk_bf16_f32 v3, v3, s0
	v_lshl_add_u64 v[4:5], v[4:5], 1, s[8:9]
	global_store_short v[4:5], v3, off sc1
	v_add_u32_e32 v4, v182, v16
	v_fmac_f32_e32 v21, v8, v102
	v_ashrrev_i32_e32 v5, 31, v4
	v_mul_f32_e32 v3, v32, v21
	v_cvt_pk_bf16_f32 v3, v3, s0
	v_lshl_add_u64 v[4:5], v[4:5], 1, s[8:9]
	global_store_short v[4:5], v3, off sc1
	v_add_u32_e32 v4, v185, v16
	v_ashrrev_i32_e32 v5, 31, v4
	v_mul_f32_e32 v3, v32, v20
	v_cvt_pk_bf16_f32 v3, v3, s0
	v_lshl_add_u64 v[4:5], v[4:5], 1, s[8:9]
	global_store_short v[4:5], v3, off sc1
	v_add_u32_e32 v4, v187, v16
	s_waitcnt vmcnt(18)
	v_fmac_f32_e32 v19, v10, v102
	v_ashrrev_i32_e32 v5, 31, v4
	v_mul_f32_e32 v3, v32, v19
	v_cvt_pk_bf16_f32 v3, v3, s0
	v_lshl_add_u64 v[4:5], v[4:5], 1, s[8:9]
	global_store_short v[4:5], v3, off sc1
	v_add_u32_e32 v4, v189, v16
	s_waitcnt vmcnt(18)
	v_fmac_f32_e32 v18, v11, v102
	v_ashrrev_i32_e32 v5, 31, v4
	v_mul_f32_e32 v3, v32, v18
	v_cvt_pk_bf16_f32 v3, v3, s0
	v_lshl_add_u64 v[4:5], v[4:5], 1, s[8:9]
	global_store_short v[4:5], v3, off sc1
	v_add_u32_e32 v4, v190, v16
	s_waitcnt vmcnt(17)
	v_fmac_f32_e32 v17, v12, v102
	v_ashrrev_i32_e32 v5, 31, v4
	v_mul_f32_e32 v3, v32, v17
	v_cvt_pk_bf16_f32 v3, v3, s0
	v_lshl_add_u64 v[4:5], v[4:5], 1, s[8:9]
	global_store_short v[4:5], v3, off sc1
	v_add_u32_e32 v4, v191, v16
	s_waitcnt vmcnt(16)
	v_fmac_f32_e32 v2, v13, v102
	v_ashrrev_i32_e32 v5, 31, v4
	v_mul_f32_e32 v3, v32, v2
	v_cvt_pk_bf16_f32 v3, v3, s0
	v_lshl_add_u64 v[4:5], v[4:5], 1, s[8:9]
	global_store_short v[4:5], v3, off sc1
	v_add_u32_e32 v4, v192, v16
	v_ashrrev_i32_e32 v5, 31, v4
	v_lshl_add_u64 v[4:5], v[4:5], 1, s[8:9]
	v_xor_b32_e32 v13, 16, v164
	v_add_u32_e32 v10, v193, v16
	v_ashrrev_i32_e32 v11, 31, v10
	v_lshl_add_u64 v[10:11], v[10:11], 1, s[8:9]
	v_ashrrev_i32_e32 v71, 31, v70
	global_store_dword v[82:83], v26, off offset:384 sc1
	global_store_dword v[78:79], v25, off offset:384 sc1
	global_store_dword v[72:73], v24, off offset:384 sc1
	global_store_dword v[74:75], v23, off offset:384 sc1
	s_waitcnt vmcnt(15)
	v_fmac_f32_e32 v1, v14, v102
	v_mul_f32_e32 v3, v32, v1
	v_cvt_pk_bf16_f32 v3, v3, s0
	global_store_short v[4:5], v3, off sc1
	v_and_b32_e32 v4, 64, v164
	v_xor_b32_e32 v3, 1, v164
	v_add_u32_e32 v7, 64, v4
	v_cmp_lt_i32_e32 vcc, v3, v7
	v_xor_b32_e32 v4, 2, v164
	s_waitcnt vmcnt(14)
	v_fmac_f32_e32 v0, v15, v102
	v_cndmask_b32_e32 v3, v164, v3, vcc
	v_lshlrev_b32_e32 v3, 2, v3
	ds_bpermute_b32 v5, v3, v106
	v_cmp_lt_i32_e32 vcc, v4, v7
	v_mul_f32_e32 v12, v32, v0
	v_cvt_pk_bf16_f32 v12, v12, s0
	v_cndmask_b32_e32 v4, v164, v4, vcc
	v_lshlrev_b32_e32 v4, 2, v4
	s_waitcnt lgkmcnt(0)
	v_add_f32_e32 v6, v106, v5
	ds_bpermute_b32 v8, v4, v6
	v_xor_b32_e32 v5, 4, v164
	v_cmp_lt_i32_e32 vcc, v5, v7
	global_store_dword v[76:77], v22, off offset:384 sc1
	global_store_dword v[80:81], v21, off offset:384 sc1
	v_cndmask_b32_e32 v5, v164, v5, vcc
	v_lshlrev_b32_e32 v5, 2, v5
	s_waitcnt lgkmcnt(0)
	v_add_f32_e32 v8, v6, v8
	ds_bpermute_b32 v9, v5, v8
	v_xor_b32_e32 v6, 8, v164
	v_cmp_lt_i32_e32 vcc, v6, v7
	global_store_dword v[90:91], v19, off offset:384 sc1
	global_store_dword v[92:93], v18, off offset:384 sc1
	v_cndmask_b32_e32 v6, v164, v6, vcc
	v_lshlrev_b32_e32 v6, 2, v6
	s_waitcnt lgkmcnt(0)
	v_add_f32_e32 v8, v8, v9
	ds_bpermute_b32 v9, v6, v8
	v_cmp_lt_i32_e32 vcc, v13, v7
	global_store_dword v[94:95], v17, off offset:384 sc1
	global_store_dword v[96:97], v2, off offset:384 sc1
	v_cndmask_b32_e32 v7, v164, v13, vcc
	v_lshlrev_b32_e32 v7, 2, v7
	s_waitcnt lgkmcnt(0)
	v_add_f32_e32 v8, v8, v9
	ds_bpermute_b32 v9, v7, v8
	global_store_dword v[98:99], v1, off offset:384 sc1
	global_store_dword v[100:101], v0, off offset:384 sc1
	global_store_short v[10:11], v12, off sc1
	s_and_saveexec_b64 s[60:61], s[0:1]
	s_cbranch_execz .LBB0_1052
	s_waitcnt lgkmcnt(0)
	v_add_f32_e32 v10, v8, v9
	v_lshl_add_u64 v[8:9], v[70:71], 2, s[58:59]
	global_store_dword v[8:9], v10, off sc1

.LBB0_1122:
	s_add_i32 s58, s67, 0xffffe000
	s_lshr_b32 s58, s58, 12
	s_mulk_i32 s58, 0x1800
	s_addk_i32 s58, 0x1800
	s_cmp_gt_i32 s6, 63
	s_cselect_b32 s62, s58, 0
	s_add_i32 s6, s62, 0x4800
	s_lshl_b64 s[58:59], s[6:7], 2
	s_add_u32 s6, s14, s58
	s_addc_u32 s58, s15, s59
	s_add_u32 s60, s6, 0x5ba5000
	s_addc_u32 s61, s58, 0
	s_add_i32 s6, s62, 0x9000
	s_lshl_b64 s[58:59], s[6:7], 2
	v_mov_b32_e32 v70, s66
	s_add_u32 s6, s14, s58
	ds_read_b64 v[70:71], v70
	s_addc_u32 s69, s15, s59
	s_lshl_b32 s58, s64, 14
	s_add_i32 s58, s58, 0x80000
	s_ashr_i32 s59, s58, 31
	s_lshl_b64 s[58:59], s[58:59], 2
	s_add_u32 s58, s10, s58
	s_waitcnt lgkmcnt(0)
	v_readfirstlane_b32 s63, v70
	s_addc_u32 s59, s11, s59
	v_or_b32_e32 v102, s68, v138
	v_add_u32_e32 v70, s67, v139
	v_readfirstlane_b32 s65, v71
	s_add_u32 s62, s63, 0x2000
	v_ashrrev_i32_e32 v103, 31, v102
	v_lshlrev_b32_e32 v191, 10, v70
	s_addc_u32 s63, s65, 0
	v_lshlrev_b64 v[72:73], 2, v[102:103]
	v_or_b32_e32 v187, 0x400, v191
	v_or_b32_e32 v186, 0x4400, v191
	v_or_b32_e32 v189, 0x4c00, v191
	v_or_b32_e32 v194, 0x6c00, v191
	s_add_u32 s64, s6, 0x5ba1000
	v_lshl_add_u64 v[74:75], s[60:61], 0, v[72:73]
	v_add_u32_e32 v130, v191, v102
	v_add_u32_e32 v132, v187, v102
	v_or_b32_e32 v185, 0x800, v191
	v_or_b32_e32 v184, 0xc00, v191
	v_or_b32_e32 v182, 0x2000, v191
	v_or_b32_e32 v180, 0x2400, v191
	v_or_b32_e32 v71, 0x2800, v191
	v_or_b32_e32 v181, 0x2c00, v191
	v_or_b32_e32 v183, 0x4000, v191
	v_add_u32_e32 v112, v186, v102
	v_or_b32_e32 v188, 0x4800, v191
	v_add_u32_e32 v116, v189, v102
	v_or_b32_e32 v190, 0x6000, v191
	v_or_b32_e32 v192, 0x6400, v191
	v_or_b32_e32 v193, 0x6800, v191
	v_add_u32_e32 v128, v194, v102
	s_addc_u32 s65, s69, 0
	global_load_dword v195, v[74:75], off
	global_load_dword v205, v[74:75], off offset:128
	v_lshl_add_u64 v[74:75], s[62:63], 0, v[72:73]
	v_ashrrev_i32_e32 v133, 31, v132
	v_add_u32_e32 v134, v185, v102
	v_add_u32_e32 v136, v184, v102
	v_add_u32_e32 v126, v182, v102
	v_add_u32_e32 v118, v180, v102
	v_add_u32_e32 v110, v71, v102
	v_add_u32_e32 v106, v181, v102
	v_add_u32_e32 v108, v183, v102
	v_ashrrev_i32_e32 v113, 31, v112
	v_add_u32_e32 v114, v188, v102
	v_ashrrev_i32_e32 v117, 31, v116
	v_add_u32_e32 v120, v190, v102
	v_add_u32_e32 v122, v192, v102
	v_add_u32_e32 v124, v193, v102
	v_ashrrev_i32_e32 v129, 31, v128
	v_ashrrev_i32_e32 v131, 31, v130
	v_lshl_add_u64 v[72:73], s[64:65], 0, v[72:73]
	global_load_dword v196, v[74:75], off
	global_load_dword v204, v[74:75], off offset:128
	global_load_dword v197, v[72:73], off
	global_load_dword v203, v[72:73], off offset:128
	v_lshl_add_u64 v[88:89], v[132:133], 2, s[12:13]
	v_ashrrev_i32_e32 v135, 31, v134
	v_ashrrev_i32_e32 v137, 31, v136
	v_ashrrev_i32_e32 v127, 31, v126
	v_ashrrev_i32_e32 v119, 31, v118
	v_ashrrev_i32_e32 v111, 31, v110
	v_ashrrev_i32_e32 v107, 31, v106
	v_ashrrev_i32_e32 v109, 31, v108
	v_lshl_add_u64 v[86:87], v[112:113], 2, s[12:13]
	v_ashrrev_i32_e32 v115, 31, v114
	v_lshl_add_u64 v[92:93], v[116:117], 2, s[12:13]
	v_ashrrev_i32_e32 v121, 31, v120
	v_ashrrev_i32_e32 v123, 31, v122
	v_ashrrev_i32_e32 v125, 31, v124
	v_lshl_add_u64 v[100:101], v[128:129], 2, s[12:13]
	v_lshl_add_u64 v[104:105], v[130:131], 2, s[12:13]
	v_lshl_add_u64 v[84:85], v[134:135], 2, s[12:13]
	v_lshl_add_u64 v[82:83], v[136:137], 2, s[12:13]
	v_lshl_add_u64 v[78:79], v[126:127], 2, s[12:13]
	v_lshl_add_u64 v[72:73], v[118:119], 2, s[12:13]
	v_lshl_add_u64 v[74:75], v[110:111], 2, s[12:13]
	v_lshl_add_u64 v[76:77], v[106:107], 2, s[12:13]
	v_lshl_add_u64 v[80:81], v[108:109], 2, s[12:13]
	global_load_dword v179, v[88:89], off
	global_load_dword v178, v[84:85], off
	global_load_dword v177, v[82:83], off
	global_load_dword v176, v[78:79], off
	global_load_dword v175, v[72:73], off
	global_load_dword v174, v[74:75], off
	global_load_dword v173, v[76:77], off
	global_load_dword v172, v[80:81], off
	v_lshl_add_u64 v[90:91], v[114:115], 2, s[12:13]
	global_load_dword v171, v[86:87], off
	global_load_dword v169, v[90:91], off
	v_lshl_add_u64 v[94:95], v[120:121], 2, s[12:13]
	v_lshl_add_u64 v[96:97], v[122:123], 2, s[12:13]
	v_lshl_add_u64 v[98:99], v[124:125], 2, s[12:13]
	global_load_dword v170, v[92:93], off
	global_load_dword v168, v[94:95], off
	global_load_dword v167, v[96:97], off
	global_load_dword v166, v[98:99], off
	global_load_dword v103, v[100:101], off
	global_load_dword v198, v[104:105], off
	v_lshl_add_u64 v[110:111], v[110:111], 1, s[8:9]
	v_lshl_add_u64 v[106:107], v[106:107], 1, s[8:9]
	global_load_dword v202, v[104:105], off offset:128
	global_load_dword v206, v[84:85], off offset:128
	global_load_dword v207, v[78:79], off offset:128
	global_load_dword v208, v[72:73], off offset:128
	global_load_dword v209, v[74:75], off offset:128
	global_load_dword v210, v[80:81], off offset:128
	global_load_dword v211, v[76:77], off offset:128
	global_load_dword v212, v[86:87], off offset:128
	global_load_dword v213, v[82:83], off offset:128
	global_load_dword v214, v[90:91], off offset:128
	global_load_dword v215, v[92:93], off offset:128
	global_load_dword v216, v[94:95], off offset:128
	global_load_dword v217, v[96:97], off offset:128
	global_load_dword v218, v[98:99], off offset:128
	global_load_dword v219, v[100:101], off offset:128
	global_load_dword v220, v[88:89], off offset:128
	s_waitcnt vmcnt(0)
	v_add_f32_e32 v197, 1.0, v197
	v_mul_f32_e32 v196, v196, v197
	v_fmac_f32_e32 v179, v49, v195
	v_fmac_f32_e32 v178, v50, v195
	v_fmac_f32_e32 v177, v51, v195
	v_fmac_f32_e32 v176, v52, v195
	v_fmac_f32_e32 v175, v53, v195
	v_fmac_f32_e32 v174, v54, v195
	v_fmac_f32_e32 v173, v55, v195
	v_fmac_f32_e32 v172, v56, v195
	v_fmac_f32_e32 v171, v57, v195
	v_fmac_f32_e32 v169, v58, v195
	v_fmac_f32_e32 v170, v59, v195
	v_fmac_f32_e32 v168, v60, v195
	v_fmac_f32_e32 v167, v61, v195
	v_fmac_f32_e32 v166, v62, v195
	v_fmac_f32_e32 v103, v63, v195
	v_fmac_f32_e32 v198, v48, v195
	v_mul_f32_e32 v48, v196, v198
	v_cvt_pk_bf16_f32 v58, v48, s0
	v_or_b32_e32 v48, 32, v102
	v_ashrrev_i32_e32 v49, 31, v48
	v_lshlrev_b64 v[52:53], 2, v[48:49]
	global_store_dword v[88:89], v179, off sc1
	global_store_dword v[84:85], v178, off sc1
	global_store_dword v[82:83], v177, off sc1
	global_store_dword v[78:79], v176, off sc1
	global_store_dword v[72:73], v175, off sc1
	global_store_dword v[74:75], v174, off sc1
	global_store_dword v[76:77], v173, off sc1
	global_store_dword v[80:81], v172, off sc1
	global_store_dword v[86:87], v171, off sc1
	global_store_dword v[90:91], v169, off sc1
	global_store_dword v[92:93], v170, off sc1
	global_store_dword v[94:95], v168, off sc1
	global_store_dword v[96:97], v167, off sc1
	global_store_dword v[98:99], v166, off sc1
	global_store_dword v[100:101], v103, off sc1
	global_store_dword v[104:105], v198, off sc1
	v_lshl_add_u64 v[50:51], v[130:131], 1, s[8:9]
	v_lshl_add_u64 v[56:57], s[64:65], 0, v[52:53]
	v_mov_b32_e32 v197, v202
	v_lshl_add_u64 v[54:55], s[62:63], 0, v[52:53]
	v_mov_b32_e32 v130, v203
	v_mov_b32_e32 v131, v204
	v_mul_f32_e32 v49, v196, v179
	global_store_short v[50:51], v58, off sc1
	v_lshl_add_u64 v[50:51], s[60:61], 0, v[52:53]
	v_mov_b32_e32 v195, v205
	v_lshl_add_u64 v[50:51], v[132:133], 1, s[8:9]
	v_cvt_pk_bf16_f32 v49, v49, s0
	global_store_short v[50:51], v49, off sc1
	v_mul_f32_e32 v49, v196, v178
	v_lshl_add_u64 v[50:51], v[134:135], 1, s[8:9]
	v_cvt_pk_bf16_f32 v49, v49, s0
	global_store_short v[50:51], v49, off sc1
	v_mul_f32_e32 v49, v196, v177
	v_lshl_add_u64 v[50:51], v[136:137], 1, s[8:9]
	v_cvt_pk_bf16_f32 v49, v49, s0
	global_store_short v[50:51], v49, off sc1
	v_mul_f32_e32 v49, v196, v176
	v_lshl_add_u64 v[50:51], v[126:127], 1, s[8:9]
	v_cvt_pk_bf16_f32 v49, v49, s0
	global_store_short v[50:51], v49, off sc1
	v_mul_f32_e32 v49, v196, v175
	v_lshl_add_u64 v[50:51], v[118:119], 1, s[8:9]
	v_cvt_pk_bf16_f32 v49, v49, s0
	v_mov_b32_e32 v62, v206
	v_mov_b32_e32 v60, v207
	v_mov_b32_e32 v59, v208
	v_mov_b32_e32 v58, v209
	v_mov_b32_e32 v56, v210
	v_mov_b32_e32 v57, v211
	v_mov_b32_e32 v55, v212
	v_mov_b32_e32 v61, v213
	v_mov_b32_e32 v54, v214
	v_mov_b32_e32 v53, v215
	v_mov_b32_e32 v52, v216
	v_mul_f32_e32 v63, v196, v174
	global_store_short v[50:51], v49, off sc1
	v_mov_b32_e32 v51, v217
	v_cvt_pk_bf16_f32 v63, v63, s0
	v_mov_b32_e32 v50, v218
	v_mov_b32_e32 v49, v219
	v_fmac_f32_e32 v197, v32, v195
	global_store_short v[110:111], v63, off sc1
	v_mov_b32_e32 v63, v220
	v_mul_f32_e32 v110, v196, v173
	v_cvt_pk_bf16_f32 v110, v110, s0
	global_store_short v[106:107], v110, off sc1
	v_lshl_add_u64 v[106:107], v[108:109], 1, s[8:9]
	v_mul_f32_e32 v108, v196, v172
	v_cvt_pk_bf16_f32 v108, v108, s0
	global_store_short v[106:107], v108, off sc1
	v_mul_f32_e32 v108, v196, v171
	v_lshl_add_u64 v[106:107], v[112:113], 1, s[8:9]
	v_cvt_pk_bf16_f32 v108, v108, s0
	global_store_short v[106:107], v108, off sc1
	v_mul_f32_e32 v108, v196, v169
	v_lshl_add_u64 v[106:107], v[114:115], 1, s[8:9]
	v_cvt_pk_bf16_f32 v108, v108, s0
	global_store_short v[106:107], v108, off sc1
	v_mul_f32_e32 v108, v196, v170
	v_lshl_add_u64 v[106:107], v[116:117], 1, s[8:9]
	v_cvt_pk_bf16_f32 v108, v108, s0
	global_store_short v[106:107], v108, off sc1
	v_mul_f32_e32 v108, v196, v168
	v_lshl_add_u64 v[106:107], v[120:121], 1, s[8:9]
	v_cvt_pk_bf16_f32 v108, v108, s0
	global_store_short v[106:107], v108, off sc1
	v_mul_f32_e32 v108, v196, v167
	v_lshl_add_u64 v[106:107], v[122:123], 1, s[8:9]
	v_cvt_pk_bf16_f32 v108, v108, s0
	global_store_short v[106:107], v108, off sc1
	v_mul_f32_e32 v108, v196, v166
	v_lshl_add_u64 v[106:107], v[124:125], 1, s[8:9]
	v_cvt_pk_bf16_f32 v108, v108, s0
	global_store_short v[106:107], v108, off sc1
	v_mul_f32_e32 v108, v196, v103
	v_lshl_add_u64 v[106:107], v[128:129], 1, s[8:9]
	v_cvt_pk_bf16_f32 v108, v108, s0
	global_store_short v[106:107], v108, off sc1
	v_add_f32_e32 v106, 1.0, v130
	v_mul_f32_e32 v107, v131, v106
	v_add_u32_e32 v108, v191, v48
	v_ashrrev_i32_e32 v109, 31, v108
	v_mul_f32_e32 v32, v107, v197
	v_fmac_f32_e32 v62, v34, v195
	v_fmac_f32_e32 v61, v35, v195
	v_fmac_f32_e32 v60, v36, v195
	v_fmac_f32_e32 v59, v37, v195
	v_fmac_f32_e32 v58, v38, v195
	v_fmac_f32_e32 v57, v39, v195
	v_fmac_f32_e32 v56, v40, v195
	v_fmac_f32_e32 v55, v41, v195
	v_fmac_f32_e32 v54, v42, v195
	v_fmac_f32_e32 v53, v43, v195
	v_fmac_f32_e32 v52, v44, v195
	v_fmac_f32_e32 v51, v45, v195
	v_fmac_f32_e32 v50, v46, v195
	v_fmac_f32_e32 v49, v47, v195
	global_store_dword v[104:105], v197, off offset:128 sc1
	v_lshl_add_u64 v[108:109], v[108:109], 1, s[8:9]
	v_cvt_pk_bf16_f32 v32, v32, s0
	global_store_dword v[84:85], v62, off offset:128 sc1
	global_store_dword v[82:83], v61, off offset:128 sc1
	global_store_dword v[78:79], v60, off offset:128 sc1
	global_store_dword v[72:73], v59, off offset:128 sc1
	global_store_dword v[74:75], v58, off offset:128 sc1
	global_store_dword v[76:77], v57, off offset:128 sc1
	global_store_dword v[80:81], v56, off offset:128 sc1
	global_store_dword v[86:87], v55, off offset:128 sc1
	global_store_dword v[90:91], v54, off offset:128 sc1
	global_store_dword v[92:93], v53, off offset:128 sc1
	global_store_dword v[94:95], v52, off offset:128 sc1
	global_store_dword v[96:97], v51, off offset:128 sc1
	global_store_dword v[98:99], v50, off offset:128 sc1
	global_store_dword v[100:101], v49, off offset:128 sc1
	global_store_short v[108:109], v32, off sc1
	v_add_u32_e32 v108, v187, v48
	global_load_dword v45, v[88:89], off offset:256
	v_ashrrev_i32_e32 v109, 31, v108
	v_mul_f32_e32 v113, v107, v56
	v_cvt_pk_bf16_f32 v113, v113, s0
	v_mul_f32_e32 v106, v197, v197
	v_fmac_f32_e32 v106, v198, v198
	s_waitcnt vmcnt(26)
	v_fmac_f32_e32 v63, v33, v195
	v_mul_f32_e32 v34, v107, v63
	v_lshl_add_u64 v[32:33], v[108:109], 1, s[8:9]
	v_cvt_pk_bf16_f32 v34, v34, s0
	global_store_short v[32:33], v34, off sc1
	v_add_u32_e32 v32, v185, v48
	v_ashrrev_i32_e32 v33, 31, v32
	v_mul_f32_e32 v34, v107, v62
	v_lshl_add_u64 v[32:33], v[32:33], 1, s[8:9]
	v_cvt_pk_bf16_f32 v34, v34, s0
	global_store_short v[32:33], v34, off sc1
	v_add_u32_e32 v32, v184, v48
	v_ashrrev_i32_e32 v33, 31, v32
	v_mul_f32_e32 v34, v107, v61
	v_lshl_add_u64 v[32:33], v[32:33], 1, s[8:9]
	v_cvt_pk_bf16_f32 v34, v34, s0
	global_store_short v[32:33], v34, off sc1
	v_add_u32_e32 v32, v182, v48
	v_ashrrev_i32_e32 v33, 31, v32
	v_mul_f32_e32 v34, v107, v60
	v_lshl_add_u64 v[32:33], v[32:33], 1, s[8:9]
	v_cvt_pk_bf16_f32 v34, v34, s0
	global_store_short v[32:33], v34, off sc1
	v_add_u32_e32 v32, v180, v48
	v_ashrrev_i32_e32 v33, 31, v32
	v_lshl_add_u64 v[34:35], v[32:33], 1, s[8:9]
	v_mul_f32_e32 v32, v107, v59
	v_cvt_pk_bf16_f32 v42, v32, s0
	v_or_b32_e32 v32, 64, v102
	v_ashrrev_i32_e32 v33, 31, v32
	v_lshlrev_b64 v[36:37], 2, v[32:33]
	global_store_dword v[88:89], v63, off offset:128 sc1
	v_lshl_add_u64 v[40:41], s[64:65], 0, v[36:37]
	v_lshl_add_u64 v[38:39], s[62:63], 0, v[36:37]
	global_load_dword v110, v[40:41], off
	global_load_dword v111, v[38:39], off
	v_mul_f32_e32 v33, v107, v58
	global_store_short v[34:35], v42, off sc1
	v_lshl_add_u64 v[34:35], s[60:61], 0, v[36:37]
	global_load_dword v112, v[34:35], off
	v_add_u32_e32 v34, v71, v48
	v_ashrrev_i32_e32 v35, 31, v34
	v_lshl_add_u64 v[34:35], v[34:35], 1, s[8:9]
	v_cvt_pk_bf16_f32 v33, v33, s0
	global_store_short v[34:35], v33, off sc1
	v_add_u32_e32 v34, v181, v48
	v_ashrrev_i32_e32 v35, 31, v34
	v_mul_f32_e32 v33, v107, v57
	v_lshl_add_u64 v[34:35], v[34:35], 1, s[8:9]
	v_cvt_pk_bf16_f32 v33, v33, s0
	global_load_dword v38, v[90:91], off offset:256
	global_load_dword v37, v[92:93], off offset:256
	global_load_dword v36, v[94:95], off offset:256
	global_load_dword v114, v[104:105], off offset:256
	global_load_dword v47, v[84:85], off offset:256
	global_load_dword v39, v[86:87], off offset:256
	global_load_dword v46, v[82:83], off offset:256
	global_load_dword v44, v[78:79], off offset:256
	global_load_dword v43, v[72:73], off offset:256
	global_load_dword v42, v[74:75], off offset:256
	global_load_dword v40, v[80:81], off offset:256
	global_load_dword v41, v[76:77], off offset:256
	v_add_u32_e32 v108, v183, v48
	global_store_short v[34:35], v33, off sc1
	global_load_dword v35, v[96:97], off offset:256
	v_ashrrev_i32_e32 v109, 31, v108
	global_load_dword v34, v[98:99], off offset:256
	global_load_dword v33, v[100:101], off offset:256
	v_lshl_add_u64 v[108:109], v[108:109], 1, s[8:9]
	global_store_short v[108:109], v113, off sc1
	v_add_u32_e32 v108, v186, v48
	v_ashrrev_i32_e32 v109, 31, v108
	v_mul_f32_e32 v113, v107, v55
	v_lshl_add_u64 v[108:109], v[108:109], 1, s[8:9]
	v_cvt_pk_bf16_f32 v113, v113, s0
	global_store_short v[108:109], v113, off sc1
	v_add_u32_e32 v108, v188, v48
	v_ashrrev_i32_e32 v109, 31, v108
	v_mul_f32_e32 v113, v107, v54
	v_lshl_add_u64 v[108:109], v[108:109], 1, s[8:9]
	v_cvt_pk_bf16_f32 v113, v113, s0
	global_store_short v[108:109], v113, off sc1
	v_add_u32_e32 v108, v189, v48
	v_ashrrev_i32_e32 v109, 31, v108
	v_mul_f32_e32 v113, v107, v53
	v_lshl_add_u64 v[108:109], v[108:109], 1, s[8:9]
	v_cvt_pk_bf16_f32 v113, v113, s0
	global_store_short v[108:109], v113, off sc1
	v_add_u32_e32 v108, v190, v48
	v_ashrrev_i32_e32 v109, 31, v108
	v_mul_f32_e32 v113, v107, v52
	v_lshl_add_u64 v[108:109], v[108:109], 1, s[8:9]
	v_cvt_pk_bf16_f32 v113, v113, s0
	global_store_short v[108:109], v113, off sc1
	v_add_u32_e32 v108, v192, v48
	v_ashrrev_i32_e32 v109, 31, v108
	v_mul_f32_e32 v113, v107, v51
	v_lshl_add_u64 v[108:109], v[108:109], 1, s[8:9]
	v_cvt_pk_bf16_f32 v113, v113, s0
	global_store_short v[108:109], v113, off sc1
	v_add_u32_e32 v108, v193, v48
	v_ashrrev_i32_e32 v109, 31, v108
	v_mul_f32_e32 v113, v107, v50
	v_lshl_add_u64 v[108:109], v[108:109], 1, s[8:9]
	v_cvt_pk_bf16_f32 v113, v113, s0
	global_store_short v[108:109], v113, off sc1
	v_add_u32_e32 v108, v194, v48
	v_ashrrev_i32_e32 v109, 31, v108
	v_mul_f32_e32 v48, v107, v49
	v_lshl_add_u64 v[108:109], v[108:109], 1, s[8:9]
	v_cvt_pk_bf16_f32 v48, v48, s0
	global_store_short v[108:109], v48, off sc1
	v_add_u32_e32 v108, v191, v32
	v_ashrrev_i32_e32 v109, 31, v108
	s_waitcnt vmcnt(28)
	v_add_f32_e32 v48, 1.0, v110
	s_waitcnt vmcnt(27)
	v_mul_f32_e32 v48, v111, v48
	s_waitcnt vmcnt(25)
	v_fmac_f32_e32 v45, v17, v112
	global_store_dword v[88:89], v45, off offset:256 sc1
	s_waitcnt vmcnt(24)
	v_fmac_f32_e32 v38, v26, v112
	s_waitcnt vmcnt(23)
	v_fmac_f32_e32 v37, v27, v112
	s_waitcnt vmcnt(22)
	v_fmac_f32_e32 v36, v28, v112
	s_waitcnt vmcnt(21)
	v_fmac_f32_e32 v114, v16, v112
	s_waitcnt vmcnt(20)
	v_fmac_f32_e32 v47, v18, v112
	v_mul_f32_e32 v18, v48, v114
	v_lshl_add_u64 v[16:17], v[108:109], 1, s[8:9]
	v_cvt_pk_bf16_f32 v18, v18, s0
	global_store_short v[16:17], v18, off sc1
	v_add_u32_e32 v16, v187, v32
	v_ashrrev_i32_e32 v17, 31, v16
	v_mul_f32_e32 v18, v48, v45
	v_lshl_add_u64 v[16:17], v[16:17], 1, s[8:9]
	v_cvt_pk_bf16_f32 v18, v18, s0
	global_store_short v[16:17], v18, off sc1
	v_add_u32_e32 v16, v185, v32
	v_ashrrev_i32_e32 v17, 31, v16
	v_mul_f32_e32 v18, v48, v47
	v_lshl_add_u64 v[16:17], v[16:17], 1, s[8:9]
	v_cvt_pk_bf16_f32 v18, v18, s0
	s_waitcnt vmcnt(20)
	v_fmac_f32_e32 v46, v19, v112
	global_store_short v[16:17], v18, off sc1
	v_add_u32_e32 v16, v184, v32
	v_ashrrev_i32_e32 v17, 31, v16
	v_mul_f32_e32 v18, v48, v46
	v_lshl_add_u64 v[16:17], v[16:17], 1, s[8:9]
	v_cvt_pk_bf16_f32 v18, v18, s0
	global_store_short v[16:17], v18, off sc1
	v_add_u32_e32 v16, v182, v32
	v_ashrrev_i32_e32 v17, 31, v16
	v_lshl_add_u64 v[18:19], v[16:17], 1, s[8:9]
	v_or_b32_e32 v16, 0x60, v102
	v_ashrrev_i32_e32 v17, 31, v16
	s_waitcnt vmcnt(21)
	v_fmac_f32_e32 v44, v20, v112
	s_waitcnt vmcnt(20)
	v_fmac_f32_e32 v43, v21, v112
	s_waitcnt vmcnt(19)
	v_fmac_f32_e32 v42, v22, v112
	s_waitcnt vmcnt(17)
	v_fmac_f32_e32 v41, v23, v112
	v_fmac_f32_e32 v40, v24, v112
	v_fmac_f32_e32 v39, v25, v112
	s_waitcnt vmcnt(15)
	v_fmac_f32_e32 v35, v29, v112
	s_waitcnt vmcnt(14)
	v_fmac_f32_e32 v34, v30, v112
	s_waitcnt vmcnt(13)
	v_fmac_f32_e32 v33, v31, v112
	v_lshlrev_b64 v[20:21], 2, v[16:17]
	global_store_dword v[84:85], v47, off offset:256 sc1
	global_store_dword v[82:83], v46, off offset:256 sc1
	global_store_dword v[78:79], v44, off offset:256 sc1
	global_store_dword v[72:73], v43, off offset:256 sc1
	global_store_dword v[74:75], v42, off offset:256 sc1
	global_store_dword v[76:77], v41, off offset:256 sc1
	global_store_dword v[80:81], v40, off offset:256 sc1
	global_store_dword v[86:87], v39, off offset:256 sc1
	global_store_dword v[90:91], v38, off offset:256 sc1
	global_store_dword v[92:93], v37, off offset:256 sc1
	global_store_dword v[94:95], v36, off offset:256 sc1
	global_store_dword v[96:97], v35, off offset:256 sc1
	global_store_dword v[98:99], v34, off offset:256 sc1
	global_store_dword v[100:101], v33, off offset:256 sc1
	global_store_dword v[104:105], v114, off offset:256 sc1
	v_mul_f32_e32 v26, v48, v44
	v_lshl_add_u64 v[22:23], s[62:63], 0, v[20:21]
	v_lshl_add_u64 v[24:25], s[64:65], 0, v[20:21]
	global_load_dword v29, v[104:105], off offset:384
	global_load_dword v17, v[24:25], off
	global_load_dword v30, v[22:23], off
	v_cvt_pk_bf16_f32 v22, v26, s0
	global_store_short v[18:19], v22, off sc1
	v_lshl_add_u64 v[18:19], s[60:61], 0, v[20:21]
	global_load_dword v102, v[18:19], off
	v_add_u32_e32 v18, v180, v32
	v_ashrrev_i32_e32 v19, 31, v18
	v_mul_f32_e32 v20, v48, v43
	v_lshl_add_u64 v[18:19], v[18:19], 1, s[8:9]
	v_cvt_pk_bf16_f32 v20, v20, s0
	global_store_short v[18:19], v20, off sc1
	v_add_u32_e32 v18, v71, v32
	v_ashrrev_i32_e32 v19, 31, v18
	v_mul_f32_e32 v20, v48, v42
	v_lshl_add_u64 v[18:19], v[18:19], 1, s[8:9]
	v_cvt_pk_bf16_f32 v20, v20, s0
	global_store_short v[18:19], v20, off sc1
	v_add_u32_e32 v18, v181, v32
	v_ashrrev_i32_e32 v19, 31, v18
	v_mul_f32_e32 v20, v48, v41
	v_lshl_add_u64 v[18:19], v[18:19], 1, s[8:9]
	v_cvt_pk_bf16_f32 v20, v20, s0
	global_store_short v[18:19], v20, off sc1
	v_add_u32_e32 v18, v183, v32
	v_ashrrev_i32_e32 v19, 31, v18
	v_mul_f32_e32 v20, v48, v40
	v_lshl_add_u64 v[18:19], v[18:19], 1, s[8:9]
	v_cvt_pk_bf16_f32 v20, v20, s0
	global_store_short v[18:19], v20, off sc1
	v_add_u32_e32 v18, v186, v32
	v_ashrrev_i32_e32 v19, 31, v18
	v_mul_f32_e32 v20, v48, v39
	v_lshl_add_u64 v[18:19], v[18:19], 1, s[8:9]
	v_cvt_pk_bf16_f32 v20, v20, s0
	global_store_short v[18:19], v20, off sc1
	v_add_u32_e32 v18, v188, v32
	v_ashrrev_i32_e32 v19, 31, v18
	v_mul_f32_e32 v20, v48, v38
	v_lshl_add_u64 v[18:19], v[18:19], 1, s[8:9]
	v_cvt_pk_bf16_f32 v20, v20, s0
	global_store_short v[18:19], v20, off sc1
	v_add_u32_e32 v18, v189, v32
	v_ashrrev_i32_e32 v19, 31, v18
	v_mul_f32_e32 v20, v48, v37
	v_lshl_add_u64 v[18:19], v[18:19], 1, s[8:9]
	v_cvt_pk_bf16_f32 v20, v20, s0
	global_store_short v[18:19], v20, off sc1
	v_add_u32_e32 v18, v190, v32
	v_ashrrev_i32_e32 v19, 31, v18
	v_mul_f32_e32 v20, v48, v36
	v_lshl_add_u64 v[18:19], v[18:19], 1, s[8:9]
	v_cvt_pk_bf16_f32 v20, v20, s0
	global_store_short v[18:19], v20, off sc1
	v_add_u32_e32 v18, v192, v32
	v_ashrrev_i32_e32 v19, 31, v18
	v_mul_f32_e32 v20, v48, v35
	v_lshl_add_u64 v[18:19], v[18:19], 1, s[8:9]
	v_cvt_pk_bf16_f32 v20, v20, s0
	global_load_dword v28, v[88:89], off offset:384
	global_load_dword v27, v[84:85], off offset:384
	global_load_dword v25, v[78:79], off offset:384
	global_load_dword v24, v[72:73], off offset:384
	global_load_dword v23, v[74:75], off offset:384
	global_load_dword v21, v[80:81], off offset:384
	global_load_dword v22, v[76:77], off offset:384
	v_fmac_f32_e32 v106, v114, v114
	global_store_short v[18:19], v20, off sc1
	v_add_u32_e32 v18, v193, v32
	v_ashrrev_i32_e32 v19, 31, v18
	v_mul_f32_e32 v20, v48, v34
	v_lshl_add_u64 v[18:19], v[18:19], 1, s[8:9]
	v_cvt_pk_bf16_f32 v20, v20, s0
	global_store_short v[18:19], v20, off sc1
	v_add_u32_e32 v18, v194, v32
	v_ashrrev_i32_e32 v19, 31, v18
	v_mul_f32_e32 v20, v48, v33
	v_lshl_add_u64 v[18:19], v[18:19], 1, s[8:9]
	v_cvt_pk_bf16_f32 v20, v20, s0
	global_store_short v[18:19], v20, off sc1
	global_load_dword v20, v[86:87], off offset:384
	s_waitcnt vmcnt(22)
	v_add_f32_e32 v17, 1.0, v17
	global_load_dword v26, v[82:83], off offset:384
	s_waitcnt vmcnt(22)
	v_mul_f32_e32 v32, v30, v17
	v_add_u32_e32 v18, v191, v16
	s_waitcnt vmcnt(20)
	v_fmac_f32_e32 v29, v0, v102
	v_ashrrev_i32_e32 v19, 31, v18
	v_mul_f32_e32 v0, v32, v29
	v_lshl_add_u64 v[18:19], v[18:19], 1, s[8:9]
	v_cvt_pk_bf16_f32 v0, v0, s0
	global_store_short v[18:19], v0, off sc1
	global_load_dword v19, v[90:91], off offset:384
	v_add_u32_e32 v30, v187, v16
	global_load_dword v18, v[92:93], off offset:384
	v_ashrrev_i32_e32 v31, 31, v30
	v_fmac_f32_e32 v106, v29, v29
	global_store_dword v[104:105], v29, off offset:384 sc1
	s_waitcnt vmcnt(15)
	v_fmac_f32_e32 v28, v1, v102
	v_mul_f32_e32 v17, v32, v28
	v_lshl_add_u64 v[0:1], v[30:31], 1, s[8:9]
	v_cvt_pk_bf16_f32 v17, v17, s0
	global_store_short v[0:1], v17, off sc1
	v_add_u32_e32 v0, v185, v16
	s_waitcnt vmcnt(15)
	v_fmac_f32_e32 v27, v2, v102
	global_load_dword v17, v[94:95], off offset:384
	v_ashrrev_i32_e32 v1, 31, v0
	v_mul_f32_e32 v2, v32, v27
	v_lshl_add_u64 v[0:1], v[0:1], 1, s[8:9]
	v_cvt_pk_bf16_f32 v2, v2, s0
	global_store_short v[0:1], v2, off sc1
	v_add_u32_e32 v0, v184, v16
	global_load_dword v2, v[96:97], off offset:384
	v_ashrrev_i32_e32 v1, 31, v0
	v_lshl_add_u64 v[0:1], v[0:1], 1, s[8:9]
	v_add_u32_e32 v30, v182, v16
	s_waitcnt vmcnt(17)
	v_fmac_f32_e32 v25, v4, v102
	v_ashrrev_i32_e32 v31, 31, v30
	v_lshl_add_u64 v[30:31], v[30:31], 1, s[8:9]
	s_waitcnt vmcnt(16)
	v_fmac_f32_e32 v24, v5, v102
	s_waitcnt vmcnt(15)
	v_fmac_f32_e32 v23, v6, v102
	s_waitcnt vmcnt(8)
	v_fmac_f32_e32 v26, v3, v102
	v_mul_f32_e32 v3, v32, v26
	v_cvt_pk_bf16_f32 v3, v3, s0
	global_store_short v[0:1], v3, off sc1
	global_load_dword v1, v[98:99], off offset:384
	v_mul_f32_e32 v0, v32, v25
	v_cvt_pk_bf16_f32 v0, v0, s0
	global_store_short v[30:31], v0, off sc1
	global_load_dword v0, v[100:101], off offset:384
	v_add_u32_e32 v30, v180, v16
	v_ashrrev_i32_e32 v31, 31, v30
	v_mul_f32_e32 v3, v32, v24
	v_lshl_add_u64 v[4:5], v[30:31], 1, s[8:9]
	v_cvt_pk_bf16_f32 v3, v3, s0
	global_store_short v[4:5], v3, off sc1
	v_add_u32_e32 v4, v71, v16
	v_ashrrev_i32_e32 v5, 31, v4
	v_mul_f32_e32 v3, v32, v23
	v_lshl_add_u64 v[4:5], v[4:5], 1, s[8:9]
	v_cvt_pk_bf16_f32 v3, v3, s0
	global_store_short v[4:5], v3, off sc1
	v_add_u32_e32 v4, v181, v16
	v_fmac_f32_e32 v22, v7, v102
	v_ashrrev_i32_e32 v5, 31, v4
	v_mul_f32_e32 v3, v32, v22
	v_lshl_add_u64 v[4:5], v[4:5], 1, s[8:9]
	v_cvt_pk_bf16_f32 v3, v3, s0
	global_store_short v[4:5], v3, off sc1
	v_add_u32_e32 v4, v183, v16
	v_fmac_f32_e32 v21, v8, v102
	v_ashrrev_i32_e32 v5, 31, v4
	v_mul_f32_e32 v3, v32, v21
	v_lshl_add_u64 v[4:5], v[4:5], 1, s[8:9]
	v_cvt_pk_bf16_f32 v3, v3, s0
	global_store_short v[4:5], v3, off sc1
	v_add_u32_e32 v4, v186, v16
	v_fmac_f32_e32 v20, v9, v102
	v_ashrrev_i32_e32 v5, 31, v4
	v_mul_f32_e32 v3, v32, v20
	v_lshl_add_u64 v[4:5], v[4:5], 1, s[8:9]
	v_cvt_pk_bf16_f32 v3, v3, s0
	global_store_short v[4:5], v3, off sc1
	v_add_u32_e32 v4, v188, v16
	s_waitcnt vmcnt(15)
	v_fmac_f32_e32 v19, v10, v102
	v_ashrrev_i32_e32 v5, 31, v4
	v_mul_f32_e32 v3, v32, v19
	v_lshl_add_u64 v[4:5], v[4:5], 1, s[8:9]
	v_cvt_pk_bf16_f32 v3, v3, s0
	global_store_short v[4:5], v3, off sc1
	v_add_u32_e32 v4, v189, v16
	s_waitcnt vmcnt(15)
	v_fmac_f32_e32 v18, v11, v102
	v_ashrrev_i32_e32 v5, 31, v4
	v_mul_f32_e32 v3, v32, v18
	v_lshl_add_u64 v[4:5], v[4:5], 1, s[8:9]
	v_cvt_pk_bf16_f32 v3, v3, s0
	global_store_short v[4:5], v3, off sc1
	v_add_u32_e32 v4, v190, v16
	v_ashrrev_i32_e32 v5, 31, v4
	v_lshl_add_u64 v[4:5], v[4:5], 1, s[8:9]
	v_ashrrev_i32_e32 v71, 31, v70
	global_store_dword v[88:89], v28, off offset:384 sc1
	global_store_dword v[84:85], v27, off offset:384 sc1
	global_store_dword v[82:83], v26, off offset:384 sc1
	global_store_dword v[78:79], v25, off offset:384 sc1
	s_waitcnt vmcnt(17)
	v_fmac_f32_e32 v17, v12, v102
	v_mul_f32_e32 v3, v32, v17
	v_cvt_pk_bf16_f32 v3, v3, s0
	global_store_short v[4:5], v3, off sc1
	v_add_u32_e32 v4, v192, v16
	v_ashrrev_i32_e32 v5, 31, v4
	v_lshl_add_u64 v[4:5], v[4:5], 1, s[8:9]
	s_waitcnt vmcnt(16)
	v_fmac_f32_e32 v2, v13, v102
	v_mul_f32_e32 v3, v32, v2
	v_cvt_pk_bf16_f32 v3, v3, s0
	global_store_short v[4:5], v3, off sc1
	v_add_u32_e32 v4, v193, v16
	v_ashrrev_i32_e32 v5, 31, v4
	v_lshl_add_u64 v[4:5], v[4:5], 1, s[8:9]
	v_xor_b32_e32 v12, 16, v165
	global_store_dword v[72:73], v24, off offset:384 sc1
	global_store_dword v[74:75], v23, off offset:384 sc1
	global_store_dword v[76:77], v22, off offset:384 sc1
	global_store_dword v[80:81], v21, off offset:384 sc1
	global_store_dword v[86:87], v20, off offset:384 sc1
	s_waitcnt vmcnt(20)
	v_fmac_f32_e32 v1, v14, v102
	v_mul_f32_e32 v3, v32, v1
	v_cvt_pk_bf16_f32 v3, v3, s0
	global_store_short v[4:5], v3, off sc1
	v_add_u32_e32 v4, v194, v16
	v_ashrrev_i32_e32 v5, 31, v4
	v_lshl_add_u64 v[10:11], v[4:5], 1, s[8:9]
	v_and_b32_e32 v4, 64, v165
	v_xor_b32_e32 v3, 1, v165
	v_add_u32_e32 v7, 64, v4
	v_cmp_lt_i32_e32 vcc, v3, v7
	v_xor_b32_e32 v4, 2, v165
	s_waitcnt vmcnt(19)
	v_fmac_f32_e32 v0, v15, v102
	v_cndmask_b32_e32 v3, v165, v3, vcc
	v_lshlrev_b32_e32 v3, 2, v3
	ds_bpermute_b32 v5, v3, v106
	v_cmp_lt_i32_e32 vcc, v4, v7
	global_store_dword v[90:91], v19, off offset:384 sc1
	global_store_dword v[92:93], v18, off offset:384 sc1
	v_cndmask_b32_e32 v4, v165, v4, vcc
	v_lshlrev_b32_e32 v4, 2, v4
	s_waitcnt lgkmcnt(0)
	v_add_f32_e32 v6, v106, v5
	ds_bpermute_b32 v8, v4, v6
	v_xor_b32_e32 v5, 4, v165
	v_cmp_lt_i32_e32 vcc, v5, v7
	global_store_dword v[94:95], v17, off offset:384 sc1
	global_store_dword v[96:97], v2, off offset:384 sc1
	v_cndmask_b32_e32 v5, v165, v5, vcc
	v_lshlrev_b32_e32 v5, 2, v5
	s_waitcnt lgkmcnt(0)
	v_add_f32_e32 v8, v6, v8
	ds_bpermute_b32 v9, v5, v8
	v_xor_b32_e32 v6, 8, v165
	v_cmp_lt_i32_e32 vcc, v6, v7
	global_store_dword v[98:99], v1, off offset:384 sc1
	global_store_dword v[100:101], v0, off offset:384 sc1
	v_cndmask_b32_e32 v6, v165, v6, vcc
	v_lshlrev_b32_e32 v6, 2, v6
	s_waitcnt lgkmcnt(0)
	v_add_f32_e32 v8, v8, v9
	ds_bpermute_b32 v9, v6, v8
	v_cmp_lt_i32_e32 vcc, v12, v7
	s_waitcnt lgkmcnt(0)
	v_add_f32_e32 v8, v8, v9
	v_cndmask_b32_e32 v7, v165, v12, vcc
	v_lshlrev_b32_e32 v7, 2, v7
	ds_bpermute_b32 v9, v7, v8
	v_mul_f32_e32 v12, v32, v0
	v_cvt_pk_bf16_f32 v12, v12, s0
	global_store_short v[10:11], v12, off sc1
	s_and_saveexec_b64 s[60:61], s[0:1]
	s_cbranch_execz .LBB0_1124
	s_waitcnt lgkmcnt(0)
	v_add_f32_e32 v10, v8, v9
	v_lshl_add_u64 v[8:9], v[70:71], 2, s[58:59]
	global_store_dword v[8:9], v10, off sc1

.LBB0_1326:
	s_add_i32 s58, s66, 0xffffe000
	s_lshr_b32 s58, s58, 12
	s_mulk_i32 s58, 0x1800
	v_mov_b32_e32 v70, s70
	s_add_i32 s58, s58, 0xa800
	ds_read_b64 v[70:71], v70
	s_cmp_gt_i32 s6, 63
	s_cselect_b32 s6, s58, 0x9000
	s_lshl_b64 s[58:59], s[6:7], 2
	s_add_u32 s6, s14, s58
	s_addc_u32 s65, s15, s59
	s_waitcnt lgkmcnt(0)
	v_readfirstlane_b32 s58, v70
	v_readfirstlane_b32 s59, v71
	s_add_u32 s60, s58, 0x2000
	s_addc_u32 s61, s59, 0
	s_lshl_b32 s58, s64, 14
	s_add_i32 s58, s58, 0xa0000
	s_ashr_i32 s59, s58, 31
	s_lshl_b64 s[58:59], s[58:59], 2
	s_add_u32 s58, s10, s58
	s_addc_u32 s59, s11, s59
	s_add_u32 s62, s6, 0x5ba2000
	v_or_b32_e32 v102, s68, v138
	v_add_u32_e32 v70, s66, v139
	s_addc_u32 s63, s65, 0
	v_lshlrev_b32_e32 v188, 10, v70
	v_ashrrev_i32_e32 v103, 31, v102
	s_add_u32 s64, s6, 0x5ba4000
	v_lshlrev_b64 v[72:73], 2, v[102:103]
	v_or_b32_e32 v186, 0x400, v188
	v_or_b32_e32 v185, 0x4400, v188
	v_or_b32_e32 v189, 0x4c00, v188
	v_or_b32_e32 v193, 0x6c00, v188
	s_addc_u32 s65, s65, 0
	v_lshl_add_u64 v[74:75], s[62:63], 0, v[72:73]
	v_add_u32_e32 v132, v188, v102
	v_add_u32_e32 v134, v186, v102
	v_or_b32_e32 v184, 0x800, v188
	v_or_b32_e32 v183, 0xc00, v188
	v_or_b32_e32 v181, 0x2000, v188
	v_or_b32_e32 v179, 0x2400, v188
	v_or_b32_e32 v71, 0x2800, v188
	v_or_b32_e32 v180, 0x2c00, v188
	v_or_b32_e32 v182, 0x4000, v188
	v_add_u32_e32 v112, v185, v102
	v_or_b32_e32 v187, 0x4800, v188
	v_add_u32_e32 v118, v189, v102
	v_or_b32_e32 v190, 0x6000, v188
	v_or_b32_e32 v191, 0x6400, v188
	v_or_b32_e32 v192, 0x6800, v188
	v_add_u32_e32 v128, v193, v102
	global_load_dword v194, v[74:75], off
	global_load_dword v205, v[74:75], off offset:128
	v_lshl_add_u64 v[74:75], s[60:61], 0, v[72:73]
	v_lshl_add_u64 v[72:73], s[64:65], 0, v[72:73]
	v_ashrrev_i32_e32 v135, 31, v134
	v_add_u32_e32 v136, v184, v102
	v_add_u32_e32 v130, v183, v102
	v_add_u32_e32 v122, v181, v102
	v_add_u32_e32 v114, v179, v102
	v_add_u32_e32 v106, v71, v102
	v_add_u32_e32 v108, v180, v102
	v_add_u32_e32 v110, v182, v102
	v_ashrrev_i32_e32 v113, 31, v112
	v_add_u32_e32 v116, v187, v102
	v_ashrrev_i32_e32 v119, 31, v118
	v_add_u32_e32 v120, v190, v102
	v_add_u32_e32 v124, v191, v102
	v_add_u32_e32 v126, v192, v102
	v_ashrrev_i32_e32 v129, 31, v128
	v_ashrrev_i32_e32 v133, 31, v132
	global_load_dword v196, v[72:73], off
	global_load_dword v203, v[72:73], off offset:128
	v_lshl_add_u64 v[88:89], v[134:135], 2, s[12:13]
	v_ashrrev_i32_e32 v137, 31, v136
	v_ashrrev_i32_e32 v131, 31, v130
	v_ashrrev_i32_e32 v123, 31, v122
	v_ashrrev_i32_e32 v115, 31, v114
	v_ashrrev_i32_e32 v107, 31, v106
	v_ashrrev_i32_e32 v109, 31, v108
	v_ashrrev_i32_e32 v111, 31, v110
	v_lshl_add_u64 v[86:87], v[112:113], 2, s[12:13]
	v_ashrrev_i32_e32 v117, 31, v116
	v_lshl_add_u64 v[92:93], v[118:119], 2, s[12:13]
	v_ashrrev_i32_e32 v121, 31, v120
	v_ashrrev_i32_e32 v125, 31, v124
	v_ashrrev_i32_e32 v127, 31, v126
	v_lshl_add_u64 v[100:101], v[128:129], 2, s[12:13]
	v_lshl_add_u64 v[104:105], v[132:133], 2, s[12:13]
	global_load_dword v195, v[74:75], off
	global_load_dword v204, v[74:75], off offset:128
	v_lshl_add_u64 v[84:85], v[136:137], 2, s[12:13]
	v_lshl_add_u64 v[82:83], v[130:131], 2, s[12:13]
	v_lshl_add_u64 v[78:79], v[122:123], 2, s[12:13]
	v_lshl_add_u64 v[72:73], v[114:115], 2, s[12:13]
	v_lshl_add_u64 v[74:75], v[106:107], 2, s[12:13]
	v_lshl_add_u64 v[76:77], v[108:109], 2, s[12:13]
	v_lshl_add_u64 v[80:81], v[110:111], 2, s[12:13]
	global_load_dword v178, v[88:89], off
	global_load_dword v177, v[84:85], off
	global_load_dword v176, v[82:83], off
	global_load_dword v175, v[78:79], off
	global_load_dword v174, v[72:73], off
	global_load_dword v173, v[74:75], off
	global_load_dword v172, v[76:77], off
	global_load_dword v171, v[80:81], off
	v_lshl_add_u64 v[90:91], v[116:117], 2, s[12:13]
	global_load_dword v170, v[86:87], off
	global_load_dword v168, v[90:91], off
	v_lshl_add_u64 v[94:95], v[120:121], 2, s[12:13]
	v_lshl_add_u64 v[96:97], v[124:125], 2, s[12:13]
	v_lshl_add_u64 v[98:99], v[126:127], 2, s[12:13]
	global_load_dword v169, v[92:93], off
	global_load_dword v167, v[94:95], off
	global_load_dword v166, v[96:97], off
	global_load_dword v165, v[98:99], off
	global_load_dword v103, v[100:101], off
	global_load_dword v197, v[104:105], off
	v_lshl_add_u64 v[106:107], v[106:107], 1, s[8:9]
	global_load_dword v202, v[104:105], off offset:128
	global_load_dword v206, v[84:85], off offset:128
	global_load_dword v207, v[78:79], off offset:128
	global_load_dword v208, v[72:73], off offset:128
	global_load_dword v209, v[74:75], off offset:128
	global_load_dword v210, v[80:81], off offset:128
	global_load_dword v211, v[76:77], off offset:128
	global_load_dword v212, v[86:87], off offset:128
	global_load_dword v213, v[82:83], off offset:128
	global_load_dword v214, v[90:91], off offset:128
	global_load_dword v215, v[92:93], off offset:128
	global_load_dword v216, v[94:95], off offset:128
	global_load_dword v217, v[96:97], off offset:128
	global_load_dword v218, v[98:99], off offset:128
	global_load_dword v219, v[100:101], off offset:128
	global_load_dword v220, v[88:89], off offset:128
	s_waitcnt vmcnt(0)
	v_add_f32_e32 v196, 1.0, v196
	v_mul_f32_e32 v195, v195, v196
	v_fmac_f32_e32 v178, v49, v194
	v_fmac_f32_e32 v177, v50, v194
	v_fmac_f32_e32 v176, v51, v194
	v_fmac_f32_e32 v175, v52, v194
	v_fmac_f32_e32 v174, v53, v194
	v_fmac_f32_e32 v173, v54, v194
	v_fmac_f32_e32 v172, v55, v194
	v_fmac_f32_e32 v171, v56, v194
	v_fmac_f32_e32 v170, v57, v194
	v_fmac_f32_e32 v168, v58, v194
	v_fmac_f32_e32 v169, v59, v194
	v_fmac_f32_e32 v167, v60, v194
	v_fmac_f32_e32 v166, v61, v194
	v_fmac_f32_e32 v165, v62, v194
	v_fmac_f32_e32 v103, v63, v194
	v_fmac_f32_e32 v197, v48, v194
	v_mul_f32_e32 v48, v195, v197
	v_cvt_pk_bf16_f32 v58, v48, s0
	v_or_b32_e32 v48, 32, v102
	v_ashrrev_i32_e32 v49, 31, v48
	v_lshlrev_b64 v[52:53], 2, v[48:49]
	global_store_dword v[88:89], v178, off sc1
	global_store_dword v[84:85], v177, off sc1
	global_store_dword v[82:83], v176, off sc1
	global_store_dword v[78:79], v175, off sc1
	global_store_dword v[72:73], v174, off sc1
	global_store_dword v[74:75], v173, off sc1
	global_store_dword v[76:77], v172, off sc1
	global_store_dword v[80:81], v171, off sc1
	global_store_dword v[86:87], v170, off sc1
	global_store_dword v[90:91], v168, off sc1
	global_store_dword v[92:93], v169, off sc1
	global_store_dword v[94:95], v167, off sc1
	global_store_dword v[96:97], v166, off sc1
	global_store_dword v[98:99], v165, off sc1
	global_store_dword v[100:101], v103, off sc1
	global_store_dword v[104:105], v197, off sc1
	v_lshl_add_u64 v[50:51], v[132:133], 1, s[8:9]
	v_lshl_add_u64 v[56:57], s[64:65], 0, v[52:53]
	v_mov_b32_e32 v196, v202
	v_lshl_add_u64 v[54:55], s[60:61], 0, v[52:53]
	v_mov_b32_e32 v132, v203
	v_mov_b32_e32 v133, v204
	v_mul_f32_e32 v49, v195, v178
	global_store_short v[50:51], v58, off sc1
	v_lshl_add_u64 v[50:51], s[62:63], 0, v[52:53]
	v_mov_b32_e32 v194, v205
	v_cvt_pk_bf16_f32 v49, v49, s0
	v_lshl_add_u64 v[50:51], v[134:135], 1, s[8:9]
	global_store_short v[50:51], v49, off sc1
	v_mul_f32_e32 v49, v195, v177
	v_cvt_pk_bf16_f32 v49, v49, s0
	v_lshl_add_u64 v[50:51], v[136:137], 1, s[8:9]
	global_store_short v[50:51], v49, off sc1
	v_mul_f32_e32 v49, v195, v176
	v_cvt_pk_bf16_f32 v49, v49, s0
	v_lshl_add_u64 v[50:51], v[130:131], 1, s[8:9]
	global_store_short v[50:51], v49, off sc1
	v_mul_f32_e32 v49, v195, v175
	v_cvt_pk_bf16_f32 v49, v49, s0
	v_lshl_add_u64 v[50:51], v[122:123], 1, s[8:9]
	global_store_short v[50:51], v49, off sc1
	v_mul_f32_e32 v49, v195, v174
	v_cvt_pk_bf16_f32 v49, v49, s0
	v_lshl_add_u64 v[50:51], v[114:115], 1, s[8:9]
	global_store_short v[50:51], v49, off sc1
	v_mul_f32_e32 v49, v195, v173
	v_mov_b32_e32 v62, v206
	v_mov_b32_e32 v60, v207
	v_mov_b32_e32 v59, v208
	v_mov_b32_e32 v58, v209
	v_mov_b32_e32 v56, v210
	v_mov_b32_e32 v57, v211
	v_mov_b32_e32 v55, v212
	v_mov_b32_e32 v61, v213
	v_mov_b32_e32 v54, v214
	v_mov_b32_e32 v53, v215
	v_mov_b32_e32 v52, v216
	v_mov_b32_e32 v51, v217
	v_mov_b32_e32 v50, v218
	v_cvt_pk_bf16_f32 v63, v49, s0
	v_mov_b32_e32 v49, v219
	v_fmac_f32_e32 v196, v32, v194
	global_store_short v[106:107], v63, off sc1
	v_mov_b32_e32 v63, v220
	v_mul_f32_e32 v106, v195, v172
	v_cvt_pk_bf16_f32 v114, v106, s0
	v_lshl_add_u64 v[106:107], v[108:109], 1, s[8:9]
	global_store_short v[106:107], v114, off sc1
	v_mul_f32_e32 v106, v195, v171
	v_cvt_pk_bf16_f32 v108, v106, s0
	v_lshl_add_u64 v[106:107], v[110:111], 1, s[8:9]
	global_store_short v[106:107], v108, off sc1
	v_mul_f32_e32 v106, v195, v170
	v_cvt_pk_bf16_f32 v108, v106, s0
	v_lshl_add_u64 v[106:107], v[112:113], 1, s[8:9]
	global_store_short v[106:107], v108, off sc1
	v_mul_f32_e32 v106, v195, v168
	v_cvt_pk_bf16_f32 v108, v106, s0
	v_lshl_add_u64 v[106:107], v[116:117], 1, s[8:9]
	global_store_short v[106:107], v108, off sc1
	v_mul_f32_e32 v106, v195, v169
	v_cvt_pk_bf16_f32 v108, v106, s0
	v_lshl_add_u64 v[106:107], v[118:119], 1, s[8:9]
	global_store_short v[106:107], v108, off sc1
	v_mul_f32_e32 v106, v195, v167
	v_cvt_pk_bf16_f32 v108, v106, s0
	v_lshl_add_u64 v[106:107], v[120:121], 1, s[8:9]
	global_store_short v[106:107], v108, off sc1
	v_mul_f32_e32 v106, v195, v166
	v_cvt_pk_bf16_f32 v108, v106, s0
	v_lshl_add_u64 v[106:107], v[124:125], 1, s[8:9]
	global_store_short v[106:107], v108, off sc1
	v_mul_f32_e32 v106, v195, v165
	v_cvt_pk_bf16_f32 v108, v106, s0
	v_lshl_add_u64 v[106:107], v[126:127], 1, s[8:9]
	global_store_short v[106:107], v108, off sc1
	v_mul_f32_e32 v106, v195, v103
	v_cvt_pk_bf16_f32 v108, v106, s0
	v_lshl_add_u64 v[106:107], v[128:129], 1, s[8:9]
	global_store_short v[106:107], v108, off sc1
	v_add_f32_e32 v106, 1.0, v132
	v_mul_f32_e32 v110, v133, v106
	v_add_u32_e32 v106, v188, v48
	v_fmac_f32_e32 v62, v34, v194
	v_fmac_f32_e32 v61, v35, v194
	v_fmac_f32_e32 v60, v36, v194
	v_fmac_f32_e32 v59, v37, v194
	v_fmac_f32_e32 v58, v38, v194
	v_fmac_f32_e32 v57, v39, v194
	v_fmac_f32_e32 v56, v40, v194
	v_fmac_f32_e32 v55, v41, v194
	v_fmac_f32_e32 v54, v42, v194
	v_fmac_f32_e32 v53, v43, v194
	v_fmac_f32_e32 v52, v44, v194
	v_fmac_f32_e32 v51, v45, v194
	v_fmac_f32_e32 v50, v46, v194
	v_fmac_f32_e32 v49, v47, v194
	v_ashrrev_i32_e32 v107, 31, v106
	global_store_dword v[104:105], v196, off offset:128 sc1
	v_mul_f32_e32 v32, v110, v196
	global_store_dword v[84:85], v62, off offset:128 sc1
	global_store_dword v[82:83], v61, off offset:128 sc1
	global_store_dword v[78:79], v60, off offset:128 sc1
	global_store_dword v[72:73], v59, off offset:128 sc1
	global_store_dword v[74:75], v58, off offset:128 sc1
	global_store_dword v[76:77], v57, off offset:128 sc1
	global_store_dword v[80:81], v56, off offset:128 sc1
	global_store_dword v[86:87], v55, off offset:128 sc1
	global_store_dword v[90:91], v54, off offset:128 sc1
	global_store_dword v[92:93], v53, off offset:128 sc1
	global_store_dword v[94:95], v52, off offset:128 sc1
	global_store_dword v[96:97], v51, off offset:128 sc1
	global_store_dword v[98:99], v50, off offset:128 sc1
	global_store_dword v[100:101], v49, off offset:128 sc1
	v_cvt_pk_bf16_f32 v32, v32, s0
	v_lshl_add_u64 v[106:107], v[106:107], 1, s[8:9]
	v_add_u32_e32 v108, v186, v48
	global_load_dword v45, v[88:89], off offset:256
	v_ashrrev_i32_e32 v109, 31, v108
	global_store_short v[106:107], v32, off sc1
	v_mul_f32_e32 v113, v110, v56
	v_cvt_pk_bf16_f32 v113, v113, s0
	v_mul_f32_e32 v106, v196, v196
	s_waitcnt vmcnt(26)
	v_fmac_f32_e32 v63, v33, v194
	v_mul_f32_e32 v32, v110, v63
	v_cvt_pk_bf16_f32 v34, v32, s0
	v_lshl_add_u64 v[32:33], v[108:109], 1, s[8:9]
	global_store_short v[32:33], v34, off sc1
	v_add_u32_e32 v32, v184, v48
	v_ashrrev_i32_e32 v33, 31, v32
	v_mul_f32_e32 v34, v110, v62
	v_cvt_pk_bf16_f32 v34, v34, s0
	v_lshl_add_u64 v[32:33], v[32:33], 1, s[8:9]
	global_store_short v[32:33], v34, off sc1
	v_add_u32_e32 v32, v183, v48
	v_ashrrev_i32_e32 v33, 31, v32
	v_mul_f32_e32 v34, v110, v61
	v_cvt_pk_bf16_f32 v34, v34, s0
	v_lshl_add_u64 v[32:33], v[32:33], 1, s[8:9]
	global_store_short v[32:33], v34, off sc1
	v_add_u32_e32 v32, v181, v48
	v_ashrrev_i32_e32 v33, 31, v32
	v_mul_f32_e32 v34, v110, v60
	v_cvt_pk_bf16_f32 v34, v34, s0
	v_lshl_add_u64 v[32:33], v[32:33], 1, s[8:9]
	global_store_short v[32:33], v34, off sc1
	v_add_u32_e32 v32, v179, v48
	v_ashrrev_i32_e32 v33, 31, v32
	v_mul_f32_e32 v34, v110, v59
	v_cvt_pk_bf16_f32 v42, v34, s0
	v_lshl_add_u64 v[34:35], v[32:33], 1, s[8:9]
	v_or_b32_e32 v32, 64, v102
	v_ashrrev_i32_e32 v33, 31, v32
	v_lshlrev_b64 v[36:37], 2, v[32:33]
	global_store_dword v[88:89], v63, off offset:128 sc1
	v_lshl_add_u64 v[40:41], s[64:65], 0, v[36:37]
	v_lshl_add_u64 v[38:39], s[60:61], 0, v[36:37]
	global_load_dword v107, v[40:41], off
	global_load_dword v111, v[38:39], off
	v_mul_f32_e32 v33, v110, v58
	global_store_short v[34:35], v42, off sc1
	v_lshl_add_u64 v[34:35], s[62:63], 0, v[36:37]
	global_load_dword v112, v[34:35], off
	v_add_u32_e32 v34, v71, v48
	v_ashrrev_i32_e32 v35, 31, v34
	v_cvt_pk_bf16_f32 v33, v33, s0
	v_lshl_add_u64 v[34:35], v[34:35], 1, s[8:9]
	global_store_short v[34:35], v33, off sc1
	v_add_u32_e32 v34, v180, v48
	v_ashrrev_i32_e32 v35, 31, v34
	v_mul_f32_e32 v33, v110, v57
	v_cvt_pk_bf16_f32 v33, v33, s0
	v_lshl_add_u64 v[34:35], v[34:35], 1, s[8:9]
	global_load_dword v38, v[90:91], off offset:256
	global_load_dword v37, v[92:93], off offset:256
	global_load_dword v36, v[94:95], off offset:256
	global_load_dword v114, v[104:105], off offset:256
	global_load_dword v47, v[84:85], off offset:256
	global_load_dword v39, v[86:87], off offset:256
	global_load_dword v46, v[82:83], off offset:256
	global_load_dword v44, v[78:79], off offset:256
	global_load_dword v43, v[72:73], off offset:256
	global_load_dword v42, v[74:75], off offset:256
	global_load_dword v40, v[80:81], off offset:256
	global_load_dword v41, v[76:77], off offset:256
	v_add_u32_e32 v108, v182, v48
	global_store_short v[34:35], v33, off sc1
	global_load_dword v35, v[96:97], off offset:256
	v_ashrrev_i32_e32 v109, 31, v108
	global_load_dword v34, v[98:99], off offset:256
	global_load_dword v33, v[100:101], off offset:256
	v_lshl_add_u64 v[108:109], v[108:109], 1, s[8:9]
	global_store_short v[108:109], v113, off sc1
	v_add_u32_e32 v108, v185, v48
	v_ashrrev_i32_e32 v109, 31, v108
	v_mul_f32_e32 v113, v110, v55
	v_cvt_pk_bf16_f32 v113, v113, s0
	v_lshl_add_u64 v[108:109], v[108:109], 1, s[8:9]
	global_store_short v[108:109], v113, off sc1
	v_add_u32_e32 v108, v187, v48
	v_ashrrev_i32_e32 v109, 31, v108
	v_mul_f32_e32 v113, v110, v54
	v_cvt_pk_bf16_f32 v113, v113, s0
	v_lshl_add_u64 v[108:109], v[108:109], 1, s[8:9]
	global_store_short v[108:109], v113, off sc1
	v_add_u32_e32 v108, v189, v48
	v_ashrrev_i32_e32 v109, 31, v108
	v_mul_f32_e32 v113, v110, v53
	v_cvt_pk_bf16_f32 v113, v113, s0
	v_lshl_add_u64 v[108:109], v[108:109], 1, s[8:9]
	global_store_short v[108:109], v113, off sc1
	v_add_u32_e32 v108, v190, v48
	v_ashrrev_i32_e32 v109, 31, v108
	v_mul_f32_e32 v113, v110, v52
	v_cvt_pk_bf16_f32 v113, v113, s0
	v_lshl_add_u64 v[108:109], v[108:109], 1, s[8:9]
	global_store_short v[108:109], v113, off sc1
	v_add_u32_e32 v108, v191, v48
	v_ashrrev_i32_e32 v109, 31, v108
	v_mul_f32_e32 v113, v110, v51
	v_cvt_pk_bf16_f32 v113, v113, s0
	v_lshl_add_u64 v[108:109], v[108:109], 1, s[8:9]
	global_store_short v[108:109], v113, off sc1
	v_add_u32_e32 v108, v192, v48
	v_ashrrev_i32_e32 v109, 31, v108
	v_mul_f32_e32 v113, v110, v50
	v_cvt_pk_bf16_f32 v113, v113, s0
	v_lshl_add_u64 v[108:109], v[108:109], 1, s[8:9]
	global_store_short v[108:109], v113, off sc1
	v_add_u32_e32 v108, v193, v48
	v_ashrrev_i32_e32 v109, 31, v108
	v_mul_f32_e32 v48, v110, v49
	v_cvt_pk_bf16_f32 v48, v48, s0
	v_lshl_add_u64 v[108:109], v[108:109], 1, s[8:9]
	global_store_short v[108:109], v48, off sc1
	v_add_u32_e32 v108, v188, v32
	v_ashrrev_i32_e32 v109, 31, v108
	s_waitcnt vmcnt(28)
	v_add_f32_e32 v48, 1.0, v107
	s_waitcnt vmcnt(27)
	v_mul_f32_e32 v48, v111, v48
	v_fmac_f32_e32 v106, v197, v197
	s_waitcnt vmcnt(25)
	v_fmac_f32_e32 v45, v17, v112
	global_store_dword v[88:89], v45, off offset:256 sc1
	s_waitcnt vmcnt(24)
	v_fmac_f32_e32 v38, v26, v112
	s_waitcnt vmcnt(23)
	v_fmac_f32_e32 v37, v27, v112
	s_waitcnt vmcnt(22)
	v_fmac_f32_e32 v36, v28, v112
	s_waitcnt vmcnt(21)
	v_fmac_f32_e32 v114, v16, v112
	v_mul_f32_e32 v16, v48, v114
	s_waitcnt vmcnt(20)
	v_fmac_f32_e32 v47, v18, v112
	v_cvt_pk_bf16_f32 v18, v16, s0
	v_lshl_add_u64 v[16:17], v[108:109], 1, s[8:9]
	global_store_short v[16:17], v18, off sc1
	v_add_u32_e32 v16, v186, v32
	v_ashrrev_i32_e32 v17, 31, v16
	v_mul_f32_e32 v18, v48, v45
	v_cvt_pk_bf16_f32 v18, v18, s0
	v_lshl_add_u64 v[16:17], v[16:17], 1, s[8:9]
	global_store_short v[16:17], v18, off sc1
	v_add_u32_e32 v16, v184, v32
	v_ashrrev_i32_e32 v17, 31, v16
	v_mul_f32_e32 v18, v48, v47
	v_cvt_pk_bf16_f32 v18, v18, s0
	v_lshl_add_u64 v[16:17], v[16:17], 1, s[8:9]
	s_waitcnt vmcnt(20)
	v_fmac_f32_e32 v46, v19, v112
	global_store_short v[16:17], v18, off sc1
	v_add_u32_e32 v16, v183, v32
	v_ashrrev_i32_e32 v17, 31, v16
	v_mul_f32_e32 v18, v48, v46
	s_waitcnt vmcnt(20)
	v_fmac_f32_e32 v44, v20, v112
	v_cvt_pk_bf16_f32 v18, v18, s0
	v_lshl_add_u64 v[16:17], v[16:17], 1, s[8:9]
	global_store_short v[16:17], v18, off sc1
	v_mul_f32_e32 v16, v48, v44
	v_cvt_pk_bf16_f32 v26, v16, s0
	v_or_b32_e32 v16, 0x60, v102
	v_add_u32_e32 v18, v181, v32
	v_ashrrev_i32_e32 v17, 31, v16
	s_waitcnt vmcnt(20)
	v_fmac_f32_e32 v43, v21, v112
	s_waitcnt vmcnt(19)
	v_fmac_f32_e32 v42, v22, v112
	s_waitcnt vmcnt(17)
	v_fmac_f32_e32 v41, v23, v112
	v_fmac_f32_e32 v40, v24, v112
	v_fmac_f32_e32 v39, v25, v112
	s_waitcnt vmcnt(15)
	v_fmac_f32_e32 v35, v29, v112
	s_waitcnt vmcnt(14)
	v_fmac_f32_e32 v34, v30, v112
	s_waitcnt vmcnt(13)
	v_fmac_f32_e32 v33, v31, v112
	v_ashrrev_i32_e32 v19, 31, v18
	v_lshlrev_b64 v[20:21], 2, v[16:17]
	global_store_dword v[84:85], v47, off offset:256 sc1
	global_store_dword v[82:83], v46, off offset:256 sc1
	global_store_dword v[78:79], v44, off offset:256 sc1
	global_store_dword v[72:73], v43, off offset:256 sc1
	global_store_dword v[74:75], v42, off offset:256 sc1
	global_store_dword v[76:77], v41, off offset:256 sc1
	global_store_dword v[80:81], v40, off offset:256 sc1
	global_store_dword v[86:87], v39, off offset:256 sc1
	global_store_dword v[90:91], v38, off offset:256 sc1
	global_store_dword v[92:93], v37, off offset:256 sc1
	global_store_dword v[94:95], v36, off offset:256 sc1
	global_store_dword v[96:97], v35, off offset:256 sc1
	global_store_dword v[98:99], v34, off offset:256 sc1
	global_store_dword v[100:101], v33, off offset:256 sc1
	global_store_dword v[104:105], v114, off offset:256 sc1
	v_lshl_add_u64 v[24:25], s[64:65], 0, v[20:21]
	v_lshl_add_u64 v[18:19], v[18:19], 1, s[8:9]
	global_load_dword v29, v[104:105], off offset:384
	v_lshl_add_u64 v[22:23], s[60:61], 0, v[20:21]
	global_load_dword v17, v[24:25], off
	global_load_dword v30, v[22:23], off
	global_load_dword v28, v[88:89], off offset:384
	global_load_dword v27, v[84:85], off offset:384
	v_fmac_f32_e32 v106, v114, v114
	global_store_short v[18:19], v26, off sc1
	v_lshl_add_u64 v[18:19], s[62:63], 0, v[20:21]
	global_load_dword v102, v[18:19], off
	v_add_u32_e32 v18, v179, v32
	v_ashrrev_i32_e32 v19, 31, v18
	v_mul_f32_e32 v20, v48, v43
	v_cvt_pk_bf16_f32 v20, v20, s0
	v_lshl_add_u64 v[18:19], v[18:19], 1, s[8:9]
	global_store_short v[18:19], v20, off sc1
	v_add_u32_e32 v18, v71, v32
	v_ashrrev_i32_e32 v19, 31, v18
	v_mul_f32_e32 v20, v48, v42
	v_cvt_pk_bf16_f32 v20, v20, s0
	v_lshl_add_u64 v[18:19], v[18:19], 1, s[8:9]
	global_store_short v[18:19], v20, off sc1
	v_add_u32_e32 v18, v180, v32
	v_ashrrev_i32_e32 v19, 31, v18
	v_mul_f32_e32 v20, v48, v41
	v_cvt_pk_bf16_f32 v20, v20, s0
	v_lshl_add_u64 v[18:19], v[18:19], 1, s[8:9]
	global_store_short v[18:19], v20, off sc1
	v_add_u32_e32 v18, v182, v32
	v_ashrrev_i32_e32 v19, 31, v18
	v_mul_f32_e32 v20, v48, v40
	v_cvt_pk_bf16_f32 v20, v20, s0
	v_lshl_add_u64 v[18:19], v[18:19], 1, s[8:9]
	global_store_short v[18:19], v20, off sc1
	v_add_u32_e32 v18, v185, v32
	v_ashrrev_i32_e32 v19, 31, v18
	v_mul_f32_e32 v20, v48, v39
	v_cvt_pk_bf16_f32 v20, v20, s0
	v_lshl_add_u64 v[18:19], v[18:19], 1, s[8:9]
	global_store_short v[18:19], v20, off sc1
	v_add_u32_e32 v18, v187, v32
	v_ashrrev_i32_e32 v19, 31, v18
	v_mul_f32_e32 v20, v48, v38
	v_cvt_pk_bf16_f32 v20, v20, s0
	v_lshl_add_u64 v[18:19], v[18:19], 1, s[8:9]
	global_store_short v[18:19], v20, off sc1
	v_add_u32_e32 v18, v189, v32
	v_ashrrev_i32_e32 v19, 31, v18
	v_mul_f32_e32 v20, v48, v37
	v_cvt_pk_bf16_f32 v20, v20, s0
	v_lshl_add_u64 v[18:19], v[18:19], 1, s[8:9]
	global_store_short v[18:19], v20, off sc1
	v_add_u32_e32 v18, v190, v32
	v_ashrrev_i32_e32 v19, 31, v18
	v_mul_f32_e32 v20, v48, v36
	v_cvt_pk_bf16_f32 v20, v20, s0
	v_lshl_add_u64 v[18:19], v[18:19], 1, s[8:9]
	global_store_short v[18:19], v20, off sc1
	v_add_u32_e32 v18, v191, v32
	v_ashrrev_i32_e32 v19, 31, v18
	v_mul_f32_e32 v20, v48, v35
	v_cvt_pk_bf16_f32 v20, v20, s0
	v_lshl_add_u64 v[18:19], v[18:19], 1, s[8:9]
	global_store_short v[18:19], v20, off sc1
	v_add_u32_e32 v18, v192, v32
	v_ashrrev_i32_e32 v19, 31, v18
	v_mul_f32_e32 v20, v48, v34
	v_cvt_pk_bf16_f32 v20, v20, s0
	v_lshl_add_u64 v[18:19], v[18:19], 1, s[8:9]
	global_store_short v[18:19], v20, off sc1
	v_add_u32_e32 v18, v193, v32
	v_ashrrev_i32_e32 v19, 31, v18
	v_mul_f32_e32 v20, v48, v33
	v_cvt_pk_bf16_f32 v20, v20, s0
	v_lshl_add_u64 v[18:19], v[18:19], 1, s[8:9]
	global_store_short v[18:19], v20, off sc1
	global_load_dword v20, v[86:87], off offset:384
	v_add_u32_e32 v18, v188, v16
	global_load_dword v26, v[82:83], off offset:384
	global_load_dword v25, v[78:79], off offset:384
	global_load_dword v24, v[72:73], off offset:384
	global_load_dword v23, v[74:75], off offset:384
	global_load_dword v21, v[80:81], off offset:384
	global_load_dword v22, v[76:77], off offset:384
	s_waitcnt vmcnt(23)
	v_add_f32_e32 v17, 1.0, v17
	s_waitcnt vmcnt(22)
	v_mul_f32_e32 v32, v30, v17
	v_ashrrev_i32_e32 v19, 31, v18
	v_lshl_add_u64 v[18:19], v[18:19], 1, s[8:9]
	v_add_u32_e32 v30, v186, v16
	s_waitcnt vmcnt(18)
	v_fmac_f32_e32 v29, v0, v102
	v_mul_f32_e32 v0, v32, v29
	v_cvt_pk_bf16_f32 v0, v0, s0
	global_store_short v[18:19], v0, off sc1
	global_load_dword v19, v[90:91], off offset:384
	v_ashrrev_i32_e32 v31, 31, v30
	global_load_dword v18, v[92:93], off offset:384
	v_fmac_f32_e32 v28, v1, v102
	v_mul_f32_e32 v0, v32, v28
	v_cvt_pk_bf16_f32 v17, v0, s0
	v_lshl_add_u64 v[0:1], v[30:31], 1, s[8:9]
	global_store_short v[0:1], v17, off sc1
	v_add_u32_e32 v0, v184, v16
	v_fmac_f32_e32 v27, v2, v102
	global_load_dword v17, v[94:95], off offset:384
	v_ashrrev_i32_e32 v1, 31, v0
	v_mul_f32_e32 v2, v32, v27
	v_cvt_pk_bf16_f32 v2, v2, s0
	v_lshl_add_u64 v[0:1], v[0:1], 1, s[8:9]
	global_store_short v[0:1], v2, off sc1
	v_add_u32_e32 v0, v183, v16
	global_load_dword v2, v[96:97], off offset:384
	v_ashrrev_i32_e32 v1, 31, v0
	v_lshl_add_u64 v[0:1], v[0:1], 1, s[8:9]
	v_add_u32_e32 v30, v181, v16
	v_ashrrev_i32_e32 v31, 31, v30
	v_lshl_add_u64 v[30:31], v[30:31], 1, s[8:9]
	v_fmac_f32_e32 v106, v29, v29
	global_store_dword v[104:105], v29, off offset:384 sc1
	global_store_dword v[88:89], v28, off offset:384 sc1
	global_store_dword v[84:85], v27, off offset:384 sc1
	s_waitcnt vmcnt(16)
	v_fmac_f32_e32 v20, v9, v102
	global_store_dword v[86:87], v20, off offset:384 sc1
	s_waitcnt vmcnt(16)
	v_fmac_f32_e32 v26, v3, v102
	v_mul_f32_e32 v3, v32, v26
	v_cvt_pk_bf16_f32 v3, v3, s0
	global_store_short v[0:1], v3, off sc1
	global_load_dword v1, v[98:99], off offset:384
	s_waitcnt vmcnt(17)
	v_fmac_f32_e32 v25, v4, v102
	v_mul_f32_e32 v0, v32, v25
	v_cvt_pk_bf16_f32 v0, v0, s0
	global_store_short v[30:31], v0, off sc1
	global_load_dword v0, v[100:101], off offset:384
	v_add_u32_e32 v30, v179, v16
	s_waitcnt vmcnt(18)
	v_fmac_f32_e32 v24, v5, v102
	v_ashrrev_i32_e32 v31, 31, v30
	v_mul_f32_e32 v3, v32, v24
	v_cvt_pk_bf16_f32 v3, v3, s0
	v_lshl_add_u64 v[4:5], v[30:31], 1, s[8:9]
	global_store_short v[4:5], v3, off sc1
	v_add_u32_e32 v4, v71, v16
	s_waitcnt vmcnt(18)
	v_fmac_f32_e32 v23, v6, v102
	v_ashrrev_i32_e32 v5, 31, v4
	v_mul_f32_e32 v3, v32, v23
	v_cvt_pk_bf16_f32 v3, v3, s0
	v_lshl_add_u64 v[4:5], v[4:5], 1, s[8:9]
	global_store_short v[4:5], v3, off sc1
	v_add_u32_e32 v4, v180, v16
	s_waitcnt vmcnt(17)
	v_fmac_f32_e32 v22, v7, v102
	v_ashrrev_i32_e32 v5, 31, v4
	v_mul_f32_e32 v3, v32, v22
	v_cvt_pk_bf16_f32 v3, v3, s0
	v_lshl_add_u64 v[4:5], v[4:5], 1, s[8:9]
	global_store_short v[4:5], v3, off sc1
	v_add_u32_e32 v4, v182, v16
	v_fmac_f32_e32 v21, v8, v102
	v_ashrrev_i32_e32 v5, 31, v4
	v_mul_f32_e32 v3, v32, v21
	v_cvt_pk_bf16_f32 v3, v3, s0
	v_lshl_add_u64 v[4:5], v[4:5], 1, s[8:9]
	global_store_short v[4:5], v3, off sc1
	v_add_u32_e32 v4, v185, v16
	v_ashrrev_i32_e32 v5, 31, v4
	v_mul_f32_e32 v3, v32, v20
	v_cvt_pk_bf16_f32 v3, v3, s0
	v_lshl_add_u64 v[4:5], v[4:5], 1, s[8:9]
	global_store_short v[4:5], v3, off sc1
	v_add_u32_e32 v4, v187, v16
	s_waitcnt vmcnt(18)
	v_fmac_f32_e32 v19, v10, v102
	v_ashrrev_i32_e32 v5, 31, v4
	v_mul_f32_e32 v3, v32, v19
	v_cvt_pk_bf16_f32 v3, v3, s0
	v_lshl_add_u64 v[4:5], v[4:5], 1, s[8:9]
	global_store_short v[4:5], v3, off sc1
	v_add_u32_e32 v4, v189, v16
	s_waitcnt vmcnt(18)
	v_fmac_f32_e32 v18, v11, v102
	v_ashrrev_i32_e32 v5, 31, v4
	v_mul_f32_e32 v3, v32, v18
	v_cvt_pk_bf16_f32 v3, v3, s0
	v_lshl_add_u64 v[4:5], v[4:5], 1, s[8:9]
	global_store_short v[4:5], v3, off sc1
	v_add_u32_e32 v4, v190, v16
	s_waitcnt vmcnt(17)
	v_fmac_f32_e32 v17, v12, v102
	v_ashrrev_i32_e32 v5, 31, v4
	v_mul_f32_e32 v3, v32, v17
	v_cvt_pk_bf16_f32 v3, v3, s0
	v_lshl_add_u64 v[4:5], v[4:5], 1, s[8:9]
	global_store_short v[4:5], v3, off sc1
	v_add_u32_e32 v4, v191, v16
	s_waitcnt vmcnt(16)
	v_fmac_f32_e32 v2, v13, v102
	v_ashrrev_i32_e32 v5, 31, v4
	v_mul_f32_e32 v3, v32, v2
	v_cvt_pk_bf16_f32 v3, v3, s0
	v_lshl_add_u64 v[4:5], v[4:5], 1, s[8:9]
	global_store_short v[4:5], v3, off sc1
	v_add_u32_e32 v4, v192, v16
	v_ashrrev_i32_e32 v5, 31, v4
	v_lshl_add_u64 v[4:5], v[4:5], 1, s[8:9]
	v_xor_b32_e32 v13, 16, v164
	v_add_u32_e32 v10, v193, v16
	v_ashrrev_i32_e32 v11, 31, v10
	v_lshl_add_u64 v[10:11], v[10:11], 1, s[8:9]
	v_ashrrev_i32_e32 v71, 31, v70
	global_store_dword v[82:83], v26, off offset:384 sc1
	global_store_dword v[78:79], v25, off offset:384 sc1
	global_store_dword v[72:73], v24, off offset:384 sc1
	global_store_dword v[74:75], v23, off offset:384 sc1
	s_waitcnt vmcnt(15)
	v_fmac_f32_e32 v1, v14, v102
	v_mul_f32_e32 v3, v32, v1
	v_cvt_pk_bf16_f32 v3, v3, s0
	global_store_short v[4:5], v3, off sc1
	v_and_b32_e32 v4, 64, v164
	v_xor_b32_e32 v3, 1, v164
	v_add_u32_e32 v7, 64, v4
	v_cmp_lt_i32_e32 vcc, v3, v7
	v_xor_b32_e32 v4, 2, v164
	s_waitcnt vmcnt(14)
	v_fmac_f32_e32 v0, v15, v102
	v_cndmask_b32_e32 v3, v164, v3, vcc
	v_lshlrev_b32_e32 v3, 2, v3
	ds_bpermute_b32 v5, v3, v106
	v_cmp_lt_i32_e32 vcc, v4, v7
	v_mul_f32_e32 v12, v32, v0
	v_cvt_pk_bf16_f32 v12, v12, s0
	v_cndmask_b32_e32 v4, v164, v4, vcc
	v_lshlrev_b32_e32 v4, 2, v4
	s_waitcnt lgkmcnt(0)
	v_add_f32_e32 v6, v106, v5
	ds_bpermute_b32 v8, v4, v6
	v_xor_b32_e32 v5, 4, v164
	v_cmp_lt_i32_e32 vcc, v5, v7
	global_store_dword v[76:77], v22, off offset:384 sc1
	global_store_dword v[80:81], v21, off offset:384 sc1
	v_cndmask_b32_e32 v5, v164, v5, vcc
	v_lshlrev_b32_e32 v5, 2, v5
	s_waitcnt lgkmcnt(0)
	v_add_f32_e32 v8, v6, v8
	ds_bpermute_b32 v9, v5, v8
	v_xor_b32_e32 v6, 8, v164
	v_cmp_lt_i32_e32 vcc, v6, v7
	global_store_dword v[90:91], v19, off offset:384 sc1
	global_store_dword v[92:93], v18, off offset:384 sc1
	v_cndmask_b32_e32 v6, v164, v6, vcc
	v_lshlrev_b32_e32 v6, 2, v6
	s_waitcnt lgkmcnt(0)
	v_add_f32_e32 v8, v8, v9
	ds_bpermute_b32 v9, v6, v8
	v_cmp_lt_i32_e32 vcc, v13, v7
	global_store_dword v[94:95], v17, off offset:384 sc1
	global_store_dword v[96:97], v2, off offset:384 sc1
	v_cndmask_b32_e32 v7, v164, v13, vcc
	v_lshlrev_b32_e32 v7, 2, v7
	s_waitcnt lgkmcnt(0)
	v_add_f32_e32 v8, v8, v9
	ds_bpermute_b32 v9, v7, v8
	global_store_dword v[98:99], v1, off offset:384 sc1
	global_store_dword v[100:101], v0, off offset:384 sc1
	global_store_short v[10:11], v12, off sc1
	s_and_saveexec_b64 s[60:61], s[0:1]
	s_cbranch_execz .LBB0_1328
	s_waitcnt lgkmcnt(0)
	v_add_f32_e32 v10, v8, v9
	v_lshl_add_u64 v[8:9], v[70:71], 2, s[58:59]
	global_store_dword v[8:9], v10, off sc1

.LBB0_1398:
	s_add_i32 s58, s67, 0xffffe000
	s_lshr_b32 s58, s58, 12
	s_mulk_i32 s58, 0x1800
	s_addk_i32 s58, 0x1800
	s_cmp_gt_i32 s6, 63
	s_cselect_b32 s62, s58, 0
	s_add_i32 s6, s62, 0x9000
	s_lshl_b64 s[58:59], s[6:7], 2
	s_add_u32 s6, s14, s58
	s_addc_u32 s58, s15, s59
	s_add_u32 s60, s6, 0x5ba5000
	s_addc_u32 s61, s58, 0
	s_add_i32 s6, s62, 0xd800
	s_lshl_b64 s[58:59], s[6:7], 2
	v_mov_b32_e32 v70, s66
	s_add_u32 s6, s14, s58
	ds_read_b64 v[70:71], v70
	s_addc_u32 s69, s15, s59
	s_lshl_b32 s58, s64, 14
	s_add_i32 s58, s58, 0xc0000
	s_ashr_i32 s59, s58, 31
	s_lshl_b64 s[58:59], s[58:59], 2
	s_add_u32 s58, s10, s58
	s_waitcnt lgkmcnt(0)
	v_readfirstlane_b32 s63, v70
	s_addc_u32 s59, s11, s59
	v_or_b32_e32 v102, s68, v138
	v_add_u32_e32 v70, s67, v139
	v_readfirstlane_b32 s65, v71
	s_add_u32 s62, s63, 0x3000
	v_ashrrev_i32_e32 v103, 31, v102
	v_lshlrev_b32_e32 v191, 10, v70
	s_addc_u32 s63, s65, 0
	v_lshlrev_b64 v[72:73], 2, v[102:103]
	v_or_b32_e32 v187, 0x400, v191
	v_or_b32_e32 v186, 0x4400, v191
	v_or_b32_e32 v189, 0x4c00, v191
	v_or_b32_e32 v194, 0x6c00, v191
	s_add_u32 s64, s6, 0x5ba1000
	v_lshl_add_u64 v[74:75], s[60:61], 0, v[72:73]
	v_add_u32_e32 v130, v191, v102
	v_add_u32_e32 v132, v187, v102
	v_or_b32_e32 v185, 0x800, v191
	v_or_b32_e32 v184, 0xc00, v191
	v_or_b32_e32 v182, 0x2000, v191
	v_or_b32_e32 v180, 0x2400, v191
	v_or_b32_e32 v71, 0x2800, v191
	v_or_b32_e32 v181, 0x2c00, v191
	v_or_b32_e32 v183, 0x4000, v191
	v_add_u32_e32 v112, v186, v102
	v_or_b32_e32 v188, 0x4800, v191
	v_add_u32_e32 v116, v189, v102
	v_or_b32_e32 v190, 0x6000, v191
	v_or_b32_e32 v192, 0x6400, v191
	v_or_b32_e32 v193, 0x6800, v191
	v_add_u32_e32 v128, v194, v102
	s_addc_u32 s65, s69, 0
	global_load_dword v195, v[74:75], off
	global_load_dword v205, v[74:75], off offset:128
	v_lshl_add_u64 v[74:75], s[62:63], 0, v[72:73]
	v_ashrrev_i32_e32 v133, 31, v132
	v_add_u32_e32 v134, v185, v102
	v_add_u32_e32 v136, v184, v102
	v_add_u32_e32 v126, v182, v102
	v_add_u32_e32 v118, v180, v102
	v_add_u32_e32 v110, v71, v102
	v_add_u32_e32 v106, v181, v102
	v_add_u32_e32 v108, v183, v102
	v_ashrrev_i32_e32 v113, 31, v112
	v_add_u32_e32 v114, v188, v102
	v_ashrrev_i32_e32 v117, 31, v116
	v_add_u32_e32 v120, v190, v102
	v_add_u32_e32 v122, v192, v102
	v_add_u32_e32 v124, v193, v102
	v_ashrrev_i32_e32 v129, 31, v128
	v_ashrrev_i32_e32 v131, 31, v130
	v_lshl_add_u64 v[72:73], s[64:65], 0, v[72:73]
	global_load_dword v196, v[74:75], off
	global_load_dword v204, v[74:75], off offset:128
	global_load_dword v197, v[72:73], off
	global_load_dword v203, v[72:73], off offset:128
	v_lshl_add_u64 v[88:89], v[132:133], 2, s[12:13]
	v_ashrrev_i32_e32 v135, 31, v134
	v_ashrrev_i32_e32 v137, 31, v136
	v_ashrrev_i32_e32 v127, 31, v126
	v_ashrrev_i32_e32 v119, 31, v118
	v_ashrrev_i32_e32 v111, 31, v110
	v_ashrrev_i32_e32 v107, 31, v106
	v_ashrrev_i32_e32 v109, 31, v108
	v_lshl_add_u64 v[86:87], v[112:113], 2, s[12:13]
	v_ashrrev_i32_e32 v115, 31, v114
	v_lshl_add_u64 v[92:93], v[116:117], 2, s[12:13]
	v_ashrrev_i32_e32 v121, 31, v120
	v_ashrrev_i32_e32 v123, 31, v122
	v_ashrrev_i32_e32 v125, 31, v124
	v_lshl_add_u64 v[100:101], v[128:129], 2, s[12:13]
	v_lshl_add_u64 v[104:105], v[130:131], 2, s[12:13]
	v_lshl_add_u64 v[84:85], v[134:135], 2, s[12:13]
	v_lshl_add_u64 v[82:83], v[136:137], 2, s[12:13]
	v_lshl_add_u64 v[78:79], v[126:127], 2, s[12:13]
	v_lshl_add_u64 v[72:73], v[118:119], 2, s[12:13]
	v_lshl_add_u64 v[74:75], v[110:111], 2, s[12:13]
	v_lshl_add_u64 v[76:77], v[106:107], 2, s[12:13]
	v_lshl_add_u64 v[80:81], v[108:109], 2, s[12:13]
	global_load_dword v179, v[88:89], off
	global_load_dword v178, v[84:85], off
	global_load_dword v177, v[82:83], off
	global_load_dword v176, v[78:79], off
	global_load_dword v175, v[72:73], off
	global_load_dword v174, v[74:75], off
	global_load_dword v173, v[76:77], off
	global_load_dword v172, v[80:81], off
	v_lshl_add_u64 v[90:91], v[114:115], 2, s[12:13]
	global_load_dword v171, v[86:87], off
	global_load_dword v169, v[90:91], off
	v_lshl_add_u64 v[94:95], v[120:121], 2, s[12:13]
	v_lshl_add_u64 v[96:97], v[122:123], 2, s[12:13]
	v_lshl_add_u64 v[98:99], v[124:125], 2, s[12:13]
	global_load_dword v170, v[92:93], off
	global_load_dword v168, v[94:95], off
	global_load_dword v167, v[96:97], off
	global_load_dword v166, v[98:99], off
	global_load_dword v103, v[100:101], off
	global_load_dword v198, v[104:105], off
	v_lshl_add_u64 v[110:111], v[110:111], 1, s[8:9]
	v_lshl_add_u64 v[106:107], v[106:107], 1, s[8:9]
	global_load_dword v202, v[104:105], off offset:128
	global_load_dword v206, v[84:85], off offset:128
	global_load_dword v207, v[78:79], off offset:128
	global_load_dword v208, v[72:73], off offset:128
	global_load_dword v209, v[74:75], off offset:128
	global_load_dword v210, v[80:81], off offset:128
	global_load_dword v211, v[76:77], off offset:128
	global_load_dword v212, v[86:87], off offset:128
	global_load_dword v213, v[82:83], off offset:128
	global_load_dword v214, v[90:91], off offset:128
	global_load_dword v215, v[92:93], off offset:128
	global_load_dword v216, v[94:95], off offset:128
	global_load_dword v217, v[96:97], off offset:128
	global_load_dword v218, v[98:99], off offset:128
	global_load_dword v219, v[100:101], off offset:128
	global_load_dword v220, v[88:89], off offset:128
	s_waitcnt vmcnt(0)
	v_add_f32_e32 v197, 1.0, v197
	v_mul_f32_e32 v196, v196, v197
	v_fmac_f32_e32 v179, v49, v195
	v_fmac_f32_e32 v178, v50, v195
	v_fmac_f32_e32 v177, v51, v195
	v_fmac_f32_e32 v176, v52, v195
	v_fmac_f32_e32 v175, v53, v195
	v_fmac_f32_e32 v174, v54, v195
	v_fmac_f32_e32 v173, v55, v195
	v_fmac_f32_e32 v172, v56, v195
	v_fmac_f32_e32 v171, v57, v195
	v_fmac_f32_e32 v169, v58, v195
	v_fmac_f32_e32 v170, v59, v195
	v_fmac_f32_e32 v168, v60, v195
	v_fmac_f32_e32 v167, v61, v195
	v_fmac_f32_e32 v166, v62, v195
	v_fmac_f32_e32 v103, v63, v195
	v_fmac_f32_e32 v198, v48, v195
	v_mul_f32_e32 v48, v196, v198
	v_cvt_pk_bf16_f32 v58, v48, s0
	v_or_b32_e32 v48, 32, v102
	v_ashrrev_i32_e32 v49, 31, v48
	v_lshlrev_b64 v[52:53], 2, v[48:49]
	global_store_dword v[88:89], v179, off sc1
	global_store_dword v[84:85], v178, off sc1
	global_store_dword v[82:83], v177, off sc1
	global_store_dword v[78:79], v176, off sc1
	global_store_dword v[72:73], v175, off sc1
	global_store_dword v[74:75], v174, off sc1
	global_store_dword v[76:77], v173, off sc1
	global_store_dword v[80:81], v172, off sc1
	global_store_dword v[86:87], v171, off sc1
	global_store_dword v[90:91], v169, off sc1
	global_store_dword v[92:93], v170, off sc1
	global_store_dword v[94:95], v168, off sc1
	global_store_dword v[96:97], v167, off sc1
	global_store_dword v[98:99], v166, off sc1
	global_store_dword v[100:101], v103, off sc1
	global_store_dword v[104:105], v198, off sc1
	v_lshl_add_u64 v[50:51], v[130:131], 1, s[8:9]
	v_lshl_add_u64 v[56:57], s[64:65], 0, v[52:53]
	v_mov_b32_e32 v197, v202
	v_lshl_add_u64 v[54:55], s[62:63], 0, v[52:53]
	v_mov_b32_e32 v130, v203
	v_mov_b32_e32 v131, v204
	v_mul_f32_e32 v49, v196, v179
	global_store_short v[50:51], v58, off sc1
	v_lshl_add_u64 v[50:51], s[60:61], 0, v[52:53]
	v_mov_b32_e32 v195, v205
	v_lshl_add_u64 v[50:51], v[132:133], 1, s[8:9]
	v_cvt_pk_bf16_f32 v49, v49, s0
	global_store_short v[50:51], v49, off sc1
	v_mul_f32_e32 v49, v196, v178
	v_lshl_add_u64 v[50:51], v[134:135], 1, s[8:9]
	v_cvt_pk_bf16_f32 v49, v49, s0
	global_store_short v[50:51], v49, off sc1
	v_mul_f32_e32 v49, v196, v177
	v_lshl_add_u64 v[50:51], v[136:137], 1, s[8:9]
	v_cvt_pk_bf16_f32 v49, v49, s0
	global_store_short v[50:51], v49, off sc1
	v_mul_f32_e32 v49, v196, v176
	v_lshl_add_u64 v[50:51], v[126:127], 1, s[8:9]
	v_cvt_pk_bf16_f32 v49, v49, s0
	global_store_short v[50:51], v49, off sc1
	v_mul_f32_e32 v49, v196, v175
	v_lshl_add_u64 v[50:51], v[118:119], 1, s[8:9]
	v_cvt_pk_bf16_f32 v49, v49, s0
	v_mov_b32_e32 v62, v206
	v_mov_b32_e32 v60, v207
	v_mov_b32_e32 v59, v208
	v_mov_b32_e32 v58, v209
	v_mov_b32_e32 v56, v210
	v_mov_b32_e32 v57, v211
	v_mov_b32_e32 v55, v212
	v_mov_b32_e32 v61, v213
	v_mov_b32_e32 v54, v214
	v_mov_b32_e32 v53, v215
	v_mov_b32_e32 v52, v216
	v_mul_f32_e32 v63, v196, v174
	global_store_short v[50:51], v49, off sc1
	v_mov_b32_e32 v51, v217
	v_cvt_pk_bf16_f32 v63, v63, s0
	v_mov_b32_e32 v50, v218
	v_mov_b32_e32 v49, v219
	v_fmac_f32_e32 v197, v32, v195
	global_store_short v[110:111], v63, off sc1
	v_mov_b32_e32 v63, v220
	v_mul_f32_e32 v110, v196, v173
	v_cvt_pk_bf16_f32 v110, v110, s0
	global_store_short v[106:107], v110, off sc1
	v_lshl_add_u64 v[106:107], v[108:109], 1, s[8:9]
	v_mul_f32_e32 v108, v196, v172
	v_cvt_pk_bf16_f32 v108, v108, s0
	global_store_short v[106:107], v108, off sc1
	v_mul_f32_e32 v108, v196, v171
	v_lshl_add_u64 v[106:107], v[112:113], 1, s[8:9]
	v_cvt_pk_bf16_f32 v108, v108, s0
	global_store_short v[106:107], v108, off sc1
	v_mul_f32_e32 v108, v196, v169
	v_lshl_add_u64 v[106:107], v[114:115], 1, s[8:9]
	v_cvt_pk_bf16_f32 v108, v108, s0
	global_store_short v[106:107], v108, off sc1
	v_mul_f32_e32 v108, v196, v170
	v_lshl_add_u64 v[106:107], v[116:117], 1, s[8:9]
	v_cvt_pk_bf16_f32 v108, v108, s0
	global_store_short v[106:107], v108, off sc1
	v_mul_f32_e32 v108, v196, v168
	v_lshl_add_u64 v[106:107], v[120:121], 1, s[8:9]
	v_cvt_pk_bf16_f32 v108, v108, s0
	global_store_short v[106:107], v108, off sc1
	v_mul_f32_e32 v108, v196, v167
	v_lshl_add_u64 v[106:107], v[122:123], 1, s[8:9]
	v_cvt_pk_bf16_f32 v108, v108, s0
	global_store_short v[106:107], v108, off sc1
	v_mul_f32_e32 v108, v196, v166
	v_lshl_add_u64 v[106:107], v[124:125], 1, s[8:9]
	v_cvt_pk_bf16_f32 v108, v108, s0
	global_store_short v[106:107], v108, off sc1
	v_mul_f32_e32 v108, v196, v103
	v_lshl_add_u64 v[106:107], v[128:129], 1, s[8:9]
	v_cvt_pk_bf16_f32 v108, v108, s0
	global_store_short v[106:107], v108, off sc1
	v_add_f32_e32 v106, 1.0, v130
	v_mul_f32_e32 v107, v131, v106
	v_add_u32_e32 v108, v191, v48
	v_ashrrev_i32_e32 v109, 31, v108
	v_mul_f32_e32 v32, v107, v197
	v_fmac_f32_e32 v62, v34, v195
	v_fmac_f32_e32 v61, v35, v195
	v_fmac_f32_e32 v60, v36, v195
	v_fmac_f32_e32 v59, v37, v195
	v_fmac_f32_e32 v58, v38, v195
	v_fmac_f32_e32 v57, v39, v195
	v_fmac_f32_e32 v56, v40, v195
	v_fmac_f32_e32 v55, v41, v195
	v_fmac_f32_e32 v54, v42, v195
	v_fmac_f32_e32 v53, v43, v195
	v_fmac_f32_e32 v52, v44, v195
	v_fmac_f32_e32 v51, v45, v195
	v_fmac_f32_e32 v50, v46, v195
	v_fmac_f32_e32 v49, v47, v195
	global_store_dword v[104:105], v197, off offset:128 sc1
	v_lshl_add_u64 v[108:109], v[108:109], 1, s[8:9]
	v_cvt_pk_bf16_f32 v32, v32, s0
	global_store_dword v[84:85], v62, off offset:128 sc1
	global_store_dword v[82:83], v61, off offset:128 sc1
	global_store_dword v[78:79], v60, off offset:128 sc1
	global_store_dword v[72:73], v59, off offset:128 sc1
	global_store_dword v[74:75], v58, off offset:128 sc1
	global_store_dword v[76:77], v57, off offset:128 sc1
	global_store_dword v[80:81], v56, off offset:128 sc1
	global_store_dword v[86:87], v55, off offset:128 sc1
	global_store_dword v[90:91], v54, off offset:128 sc1
	global_store_dword v[92:93], v53, off offset:128 sc1
	global_store_dword v[94:95], v52, off offset:128 sc1
	global_store_dword v[96:97], v51, off offset:128 sc1
	global_store_dword v[98:99], v50, off offset:128 sc1
	global_store_dword v[100:101], v49, off offset:128 sc1
	global_store_short v[108:109], v32, off sc1
	v_add_u32_e32 v108, v187, v48
	global_load_dword v45, v[88:89], off offset:256
	v_ashrrev_i32_e32 v109, 31, v108
	v_mul_f32_e32 v113, v107, v56
	v_cvt_pk_bf16_f32 v113, v113, s0
	v_mul_f32_e32 v106, v197, v197
	v_fmac_f32_e32 v106, v198, v198
	s_waitcnt vmcnt(26)
	v_fmac_f32_e32 v63, v33, v195
	v_mul_f32_e32 v34, v107, v63
	v_lshl_add_u64 v[32:33], v[108:109], 1, s[8:9]
	v_cvt_pk_bf16_f32 v34, v34, s0
	global_store_short v[32:33], v34, off sc1
	v_add_u32_e32 v32, v185, v48
	v_ashrrev_i32_e32 v33, 31, v32
	v_mul_f32_e32 v34, v107, v62
	v_lshl_add_u64 v[32:33], v[32:33], 1, s[8:9]
	v_cvt_pk_bf16_f32 v34, v34, s0
	global_store_short v[32:33], v34, off sc1
	v_add_u32_e32 v32, v184, v48
	v_ashrrev_i32_e32 v33, 31, v32
	v_mul_f32_e32 v34, v107, v61
	v_lshl_add_u64 v[32:33], v[32:33], 1, s[8:9]
	v_cvt_pk_bf16_f32 v34, v34, s0
	global_store_short v[32:33], v34, off sc1
	v_add_u32_e32 v32, v182, v48
	v_ashrrev_i32_e32 v33, 31, v32
	v_mul_f32_e32 v34, v107, v60
	v_lshl_add_u64 v[32:33], v[32:33], 1, s[8:9]
	v_cvt_pk_bf16_f32 v34, v34, s0
	global_store_short v[32:33], v34, off sc1
	v_add_u32_e32 v32, v180, v48
	v_ashrrev_i32_e32 v33, 31, v32
	v_lshl_add_u64 v[34:35], v[32:33], 1, s[8:9]
	v_mul_f32_e32 v32, v107, v59
	v_cvt_pk_bf16_f32 v42, v32, s0
	v_or_b32_e32 v32, 64, v102
	v_ashrrev_i32_e32 v33, 31, v32
	v_lshlrev_b64 v[36:37], 2, v[32:33]
	global_store_dword v[88:89], v63, off offset:128 sc1
	v_lshl_add_u64 v[40:41], s[64:65], 0, v[36:37]
	v_lshl_add_u64 v[38:39], s[62:63], 0, v[36:37]
	global_load_dword v110, v[40:41], off
	global_load_dword v111, v[38:39], off
	v_mul_f32_e32 v33, v107, v58
	global_store_short v[34:35], v42, off sc1
	v_lshl_add_u64 v[34:35], s[60:61], 0, v[36:37]
	global_load_dword v112, v[34:35], off
	v_add_u32_e32 v34, v71, v48
	v_ashrrev_i32_e32 v35, 31, v34
	v_lshl_add_u64 v[34:35], v[34:35], 1, s[8:9]
	v_cvt_pk_bf16_f32 v33, v33, s0
	global_store_short v[34:35], v33, off sc1
	v_add_u32_e32 v34, v181, v48
	v_ashrrev_i32_e32 v35, 31, v34
	v_mul_f32_e32 v33, v107, v57
	v_lshl_add_u64 v[34:35], v[34:35], 1, s[8:9]
	v_cvt_pk_bf16_f32 v33, v33, s0
	global_load_dword v38, v[90:91], off offset:256
	global_load_dword v37, v[92:93], off offset:256
	global_load_dword v36, v[94:95], off offset:256
	global_load_dword v114, v[104:105], off offset:256
	global_load_dword v47, v[84:85], off offset:256
	global_load_dword v39, v[86:87], off offset:256
	global_load_dword v46, v[82:83], off offset:256
	global_load_dword v44, v[78:79], off offset:256
	global_load_dword v43, v[72:73], off offset:256
	global_load_dword v42, v[74:75], off offset:256
	global_load_dword v40, v[80:81], off offset:256
	global_load_dword v41, v[76:77], off offset:256
	v_add_u32_e32 v108, v183, v48
	global_store_short v[34:35], v33, off sc1
	global_load_dword v35, v[96:97], off offset:256
	v_ashrrev_i32_e32 v109, 31, v108
	global_load_dword v34, v[98:99], off offset:256
	global_load_dword v33, v[100:101], off offset:256
	v_lshl_add_u64 v[108:109], v[108:109], 1, s[8:9]
	global_store_short v[108:109], v113, off sc1
	v_add_u32_e32 v108, v186, v48
	v_ashrrev_i32_e32 v109, 31, v108
	v_mul_f32_e32 v113, v107, v55
	v_lshl_add_u64 v[108:109], v[108:109], 1, s[8:9]
	v_cvt_pk_bf16_f32 v113, v113, s0
	global_store_short v[108:109], v113, off sc1
	v_add_u32_e32 v108, v188, v48
	v_ashrrev_i32_e32 v109, 31, v108
	v_mul_f32_e32 v113, v107, v54
	v_lshl_add_u64 v[108:109], v[108:109], 1, s[8:9]
	v_cvt_pk_bf16_f32 v113, v113, s0
	global_store_short v[108:109], v113, off sc1
	v_add_u32_e32 v108, v189, v48
	v_ashrrev_i32_e32 v109, 31, v108
	v_mul_f32_e32 v113, v107, v53
	v_lshl_add_u64 v[108:109], v[108:109], 1, s[8:9]
	v_cvt_pk_bf16_f32 v113, v113, s0
	global_store_short v[108:109], v113, off sc1
	v_add_u32_e32 v108, v190, v48
	v_ashrrev_i32_e32 v109, 31, v108
	v_mul_f32_e32 v113, v107, v52
	v_lshl_add_u64 v[108:109], v[108:109], 1, s[8:9]
	v_cvt_pk_bf16_f32 v113, v113, s0
	global_store_short v[108:109], v113, off sc1
	v_add_u32_e32 v108, v192, v48
	v_ashrrev_i32_e32 v109, 31, v108
	v_mul_f32_e32 v113, v107, v51
	v_lshl_add_u64 v[108:109], v[108:109], 1, s[8:9]
	v_cvt_pk_bf16_f32 v113, v113, s0
	global_store_short v[108:109], v113, off sc1
	v_add_u32_e32 v108, v193, v48
	v_ashrrev_i32_e32 v109, 31, v108
	v_mul_f32_e32 v113, v107, v50
	v_lshl_add_u64 v[108:109], v[108:109], 1, s[8:9]
	v_cvt_pk_bf16_f32 v113, v113, s0
	global_store_short v[108:109], v113, off sc1
	v_add_u32_e32 v108, v194, v48
	v_ashrrev_i32_e32 v109, 31, v108
	v_mul_f32_e32 v48, v107, v49
	v_lshl_add_u64 v[108:109], v[108:109], 1, s[8:9]
	v_cvt_pk_bf16_f32 v48, v48, s0
	global_store_short v[108:109], v48, off sc1
	v_add_u32_e32 v108, v191, v32
	v_ashrrev_i32_e32 v109, 31, v108
	s_waitcnt vmcnt(28)
	v_add_f32_e32 v48, 1.0, v110
	s_waitcnt vmcnt(27)
	v_mul_f32_e32 v48, v111, v48
	s_waitcnt vmcnt(25)
	v_fmac_f32_e32 v45, v17, v112
	global_store_dword v[88:89], v45, off offset:256 sc1
	s_waitcnt vmcnt(24)
	v_fmac_f32_e32 v38, v26, v112
	s_waitcnt vmcnt(23)
	v_fmac_f32_e32 v37, v27, v112
	s_waitcnt vmcnt(22)
	v_fmac_f32_e32 v36, v28, v112
	s_waitcnt vmcnt(21)
	v_fmac_f32_e32 v114, v16, v112
	s_waitcnt vmcnt(20)
	v_fmac_f32_e32 v47, v18, v112
	v_mul_f32_e32 v18, v48, v114
	v_lshl_add_u64 v[16:17], v[108:109], 1, s[8:9]
	v_cvt_pk_bf16_f32 v18, v18, s0
	global_store_short v[16:17], v18, off sc1
	v_add_u32_e32 v16, v187, v32
	v_ashrrev_i32_e32 v17, 31, v16
	v_mul_f32_e32 v18, v48, v45
	v_lshl_add_u64 v[16:17], v[16:17], 1, s[8:9]
	v_cvt_pk_bf16_f32 v18, v18, s0
	global_store_short v[16:17], v18, off sc1
	v_add_u32_e32 v16, v185, v32
	v_ashrrev_i32_e32 v17, 31, v16
	v_mul_f32_e32 v18, v48, v47
	v_lshl_add_u64 v[16:17], v[16:17], 1, s[8:9]
	v_cvt_pk_bf16_f32 v18, v18, s0
	s_waitcnt vmcnt(20)
	v_fmac_f32_e32 v46, v19, v112
	global_store_short v[16:17], v18, off sc1
	v_add_u32_e32 v16, v184, v32
	v_ashrrev_i32_e32 v17, 31, v16
	v_mul_f32_e32 v18, v48, v46
	v_lshl_add_u64 v[16:17], v[16:17], 1, s[8:9]
	v_cvt_pk_bf16_f32 v18, v18, s0
	global_store_short v[16:17], v18, off sc1
	v_add_u32_e32 v16, v182, v32
	v_ashrrev_i32_e32 v17, 31, v16
	v_lshl_add_u64 v[18:19], v[16:17], 1, s[8:9]
	v_or_b32_e32 v16, 0x60, v102
	v_ashrrev_i32_e32 v17, 31, v16
	s_waitcnt vmcnt(21)
	v_fmac_f32_e32 v44, v20, v112
	s_waitcnt vmcnt(20)
	v_fmac_f32_e32 v43, v21, v112
	s_waitcnt vmcnt(19)
	v_fmac_f32_e32 v42, v22, v112
	s_waitcnt vmcnt(17)
	v_fmac_f32_e32 v41, v23, v112
	v_fmac_f32_e32 v40, v24, v112
	v_fmac_f32_e32 v39, v25, v112
	s_waitcnt vmcnt(15)
	v_fmac_f32_e32 v35, v29, v112
	s_waitcnt vmcnt(14)
	v_fmac_f32_e32 v34, v30, v112
	s_waitcnt vmcnt(13)
	v_fmac_f32_e32 v33, v31, v112
	v_lshlrev_b64 v[20:21], 2, v[16:17]
	global_store_dword v[84:85], v47, off offset:256 sc1
	global_store_dword v[82:83], v46, off offset:256 sc1
	global_store_dword v[78:79], v44, off offset:256 sc1
	global_store_dword v[72:73], v43, off offset:256 sc1
	global_store_dword v[74:75], v42, off offset:256 sc1
	global_store_dword v[76:77], v41, off offset:256 sc1
	global_store_dword v[80:81], v40, off offset:256 sc1
	global_store_dword v[86:87], v39, off offset:256 sc1
	global_store_dword v[90:91], v38, off offset:256 sc1
	global_store_dword v[92:93], v37, off offset:256 sc1
	global_store_dword v[94:95], v36, off offset:256 sc1
	global_store_dword v[96:97], v35, off offset:256 sc1
	global_store_dword v[98:99], v34, off offset:256 sc1
	global_store_dword v[100:101], v33, off offset:256 sc1
	global_store_dword v[104:105], v114, off offset:256 sc1
	v_mul_f32_e32 v26, v48, v44
	v_lshl_add_u64 v[22:23], s[62:63], 0, v[20:21]
	v_lshl_add_u64 v[24:25], s[64:65], 0, v[20:21]
	global_load_dword v29, v[104:105], off offset:384
	global_load_dword v17, v[24:25], off
	global_load_dword v30, v[22:23], off
	v_cvt_pk_bf16_f32 v22, v26, s0
	global_store_short v[18:19], v22, off sc1
	v_lshl_add_u64 v[18:19], s[60:61], 0, v[20:21]
	global_load_dword v102, v[18:19], off
	v_add_u32_e32 v18, v180, v32
	v_ashrrev_i32_e32 v19, 31, v18
	v_mul_f32_e32 v20, v48, v43
	v_lshl_add_u64 v[18:19], v[18:19], 1, s[8:9]
	v_cvt_pk_bf16_f32 v20, v20, s0
	global_store_short v[18:19], v20, off sc1
	v_add_u32_e32 v18, v71, v32
	v_ashrrev_i32_e32 v19, 31, v18
	v_mul_f32_e32 v20, v48, v42
	v_lshl_add_u64 v[18:19], v[18:19], 1, s[8:9]
	v_cvt_pk_bf16_f32 v20, v20, s0
	global_store_short v[18:19], v20, off sc1
	v_add_u32_e32 v18, v181, v32
	v_ashrrev_i32_e32 v19, 31, v18
	v_mul_f32_e32 v20, v48, v41
	v_lshl_add_u64 v[18:19], v[18:19], 1, s[8:9]
	v_cvt_pk_bf16_f32 v20, v20, s0
	global_store_short v[18:19], v20, off sc1
	v_add_u32_e32 v18, v183, v32
	v_ashrrev_i32_e32 v19, 31, v18
	v_mul_f32_e32 v20, v48, v40
	v_lshl_add_u64 v[18:19], v[18:19], 1, s[8:9]
	v_cvt_pk_bf16_f32 v20, v20, s0
	global_store_short v[18:19], v20, off sc1
	v_add_u32_e32 v18, v186, v32
	v_ashrrev_i32_e32 v19, 31, v18
	v_mul_f32_e32 v20, v48, v39
	v_lshl_add_u64 v[18:19], v[18:19], 1, s[8:9]
	v_cvt_pk_bf16_f32 v20, v20, s0
	global_store_short v[18:19], v20, off sc1
	v_add_u32_e32 v18, v188, v32
	v_ashrrev_i32_e32 v19, 31, v18
	v_mul_f32_e32 v20, v48, v38
	v_lshl_add_u64 v[18:19], v[18:19], 1, s[8:9]
	v_cvt_pk_bf16_f32 v20, v20, s0
	global_store_short v[18:19], v20, off sc1
	v_add_u32_e32 v18, v189, v32
	v_ashrrev_i32_e32 v19, 31, v18
	v_mul_f32_e32 v20, v48, v37
	v_lshl_add_u64 v[18:19], v[18:19], 1, s[8:9]
	v_cvt_pk_bf16_f32 v20, v20, s0
	global_store_short v[18:19], v20, off sc1
	v_add_u32_e32 v18, v190, v32
	v_ashrrev_i32_e32 v19, 31, v18
	v_mul_f32_e32 v20, v48, v36
	v_lshl_add_u64 v[18:19], v[18:19], 1, s[8:9]
	v_cvt_pk_bf16_f32 v20, v20, s0
	global_store_short v[18:19], v20, off sc1
	v_add_u32_e32 v18, v192, v32
	v_ashrrev_i32_e32 v19, 31, v18
	v_mul_f32_e32 v20, v48, v35
	v_lshl_add_u64 v[18:19], v[18:19], 1, s[8:9]
	v_cvt_pk_bf16_f32 v20, v20, s0
	global_load_dword v28, v[88:89], off offset:384
	global_load_dword v27, v[84:85], off offset:384
	global_load_dword v25, v[78:79], off offset:384
	global_load_dword v24, v[72:73], off offset:384
	global_load_dword v23, v[74:75], off offset:384
	global_load_dword v21, v[80:81], off offset:384
	global_load_dword v22, v[76:77], off offset:384
	v_fmac_f32_e32 v106, v114, v114
	global_store_short v[18:19], v20, off sc1
	v_add_u32_e32 v18, v193, v32
	v_ashrrev_i32_e32 v19, 31, v18
	v_mul_f32_e32 v20, v48, v34
	v_lshl_add_u64 v[18:19], v[18:19], 1, s[8:9]
	v_cvt_pk_bf16_f32 v20, v20, s0
	global_store_short v[18:19], v20, off sc1
	v_add_u32_e32 v18, v194, v32
	v_ashrrev_i32_e32 v19, 31, v18
	v_mul_f32_e32 v20, v48, v33
	v_lshl_add_u64 v[18:19], v[18:19], 1, s[8:9]
	v_cvt_pk_bf16_f32 v20, v20, s0
	global_store_short v[18:19], v20, off sc1
	global_load_dword v20, v[86:87], off offset:384
	s_waitcnt vmcnt(22)
	v_add_f32_e32 v17, 1.0, v17
	global_load_dword v26, v[82:83], off offset:384
	s_waitcnt vmcnt(22)
	v_mul_f32_e32 v32, v30, v17
	v_add_u32_e32 v18, v191, v16
	s_waitcnt vmcnt(20)
	v_fmac_f32_e32 v29, v0, v102
	v_ashrrev_i32_e32 v19, 31, v18
	v_mul_f32_e32 v0, v32, v29
	v_lshl_add_u64 v[18:19], v[18:19], 1, s[8:9]
	v_cvt_pk_bf16_f32 v0, v0, s0
	global_store_short v[18:19], v0, off sc1
	global_load_dword v19, v[90:91], off offset:384
	v_add_u32_e32 v30, v187, v16
	global_load_dword v18, v[92:93], off offset:384
	v_ashrrev_i32_e32 v31, 31, v30
	v_fmac_f32_e32 v106, v29, v29
	global_store_dword v[104:105], v29, off offset:384 sc1
	s_waitcnt vmcnt(15)
	v_fmac_f32_e32 v28, v1, v102
	v_mul_f32_e32 v17, v32, v28
	v_lshl_add_u64 v[0:1], v[30:31], 1, s[8:9]
	v_cvt_pk_bf16_f32 v17, v17, s0
	global_store_short v[0:1], v17, off sc1
	v_add_u32_e32 v0, v185, v16
	s_waitcnt vmcnt(15)
	v_fmac_f32_e32 v27, v2, v102
	global_load_dword v17, v[94:95], off offset:384
	v_ashrrev_i32_e32 v1, 31, v0
	v_mul_f32_e32 v2, v32, v27
	v_lshl_add_u64 v[0:1], v[0:1], 1, s[8:9]
	v_cvt_pk_bf16_f32 v2, v2, s0
	global_store_short v[0:1], v2, off sc1
	v_add_u32_e32 v0, v184, v16
	global_load_dword v2, v[96:97], off offset:384
	v_ashrrev_i32_e32 v1, 31, v0
	v_lshl_add_u64 v[0:1], v[0:1], 1, s[8:9]
	v_add_u32_e32 v30, v182, v16
	s_waitcnt vmcnt(17)
	v_fmac_f32_e32 v25, v4, v102
	v_ashrrev_i32_e32 v31, 31, v30
	v_lshl_add_u64 v[30:31], v[30:31], 1, s[8:9]
	s_waitcnt vmcnt(16)
	v_fmac_f32_e32 v24, v5, v102
	s_waitcnt vmcnt(15)
	v_fmac_f32_e32 v23, v6, v102
	s_waitcnt vmcnt(8)
	v_fmac_f32_e32 v26, v3, v102
	v_mul_f32_e32 v3, v32, v26
	v_cvt_pk_bf16_f32 v3, v3, s0
	global_store_short v[0:1], v3, off sc1
	global_load_dword v1, v[98:99], off offset:384
	v_mul_f32_e32 v0, v32, v25
	v_cvt_pk_bf16_f32 v0, v0, s0
	global_store_short v[30:31], v0, off sc1
	global_load_dword v0, v[100:101], off offset:384
	v_add_u32_e32 v30, v180, v16
	v_ashrrev_i32_e32 v31, 31, v30
	v_mul_f32_e32 v3, v32, v24
	v_lshl_add_u64 v[4:5], v[30:31], 1, s[8:9]
	v_cvt_pk_bf16_f32 v3, v3, s0
	global_store_short v[4:5], v3, off sc1
	v_add_u32_e32 v4, v71, v16
	v_ashrrev_i32_e32 v5, 31, v4
	v_mul_f32_e32 v3, v32, v23
	v_lshl_add_u64 v[4:5], v[4:5], 1, s[8:9]
	v_cvt_pk_bf16_f32 v3, v3, s0
	global_store_short v[4:5], v3, off sc1
	v_add_u32_e32 v4, v181, v16
	v_fmac_f32_e32 v22, v7, v102
	v_ashrrev_i32_e32 v5, 31, v4
	v_mul_f32_e32 v3, v32, v22
	v_lshl_add_u64 v[4:5], v[4:5], 1, s[8:9]
	v_cvt_pk_bf16_f32 v3, v3, s0
	global_store_short v[4:5], v3, off sc1
	v_add_u32_e32 v4, v183, v16
	v_fmac_f32_e32 v21, v8, v102
	v_ashrrev_i32_e32 v5, 31, v4
	v_mul_f32_e32 v3, v32, v21
	v_lshl_add_u64 v[4:5], v[4:5], 1, s[8:9]
	v_cvt_pk_bf16_f32 v3, v3, s0
	global_store_short v[4:5], v3, off sc1
	v_add_u32_e32 v4, v186, v16
	v_fmac_f32_e32 v20, v9, v102
	v_ashrrev_i32_e32 v5, 31, v4
	v_mul_f32_e32 v3, v32, v20
	v_lshl_add_u64 v[4:5], v[4:5], 1, s[8:9]
	v_cvt_pk_bf16_f32 v3, v3, s0
	global_store_short v[4:5], v3, off sc1
	v_add_u32_e32 v4, v188, v16
	s_waitcnt vmcnt(15)
	v_fmac_f32_e32 v19, v10, v102
	v_ashrrev_i32_e32 v5, 31, v4
	v_mul_f32_e32 v3, v32, v19
	v_lshl_add_u64 v[4:5], v[4:5], 1, s[8:9]
	v_cvt_pk_bf16_f32 v3, v3, s0
	global_store_short v[4:5], v3, off sc1
	v_add_u32_e32 v4, v189, v16
	s_waitcnt vmcnt(15)
	v_fmac_f32_e32 v18, v11, v102
	v_ashrrev_i32_e32 v5, 31, v4
	v_mul_f32_e32 v3, v32, v18
	v_lshl_add_u64 v[4:5], v[4:5], 1, s[8:9]
	v_cvt_pk_bf16_f32 v3, v3, s0
	global_store_short v[4:5], v3, off sc1
	v_add_u32_e32 v4, v190, v16
	v_ashrrev_i32_e32 v5, 31, v4
	v_lshl_add_u64 v[4:5], v[4:5], 1, s[8:9]
	v_ashrrev_i32_e32 v71, 31, v70
	global_store_dword v[88:89], v28, off offset:384 sc1
	global_store_dword v[84:85], v27, off offset:384 sc1
	global_store_dword v[82:83], v26, off offset:384 sc1
	global_store_dword v[78:79], v25, off offset:384 sc1
	s_waitcnt vmcnt(17)
	v_fmac_f32_e32 v17, v12, v102
	v_mul_f32_e32 v3, v32, v17
	v_cvt_pk_bf16_f32 v3, v3, s0
	global_store_short v[4:5], v3, off sc1
	v_add_u32_e32 v4, v192, v16
	v_ashrrev_i32_e32 v5, 31, v4
	v_lshl_add_u64 v[4:5], v[4:5], 1, s[8:9]
	s_waitcnt vmcnt(16)
	v_fmac_f32_e32 v2, v13, v102
	v_mul_f32_e32 v3, v32, v2
	v_cvt_pk_bf16_f32 v3, v3, s0
	global_store_short v[4:5], v3, off sc1
	v_add_u32_e32 v4, v193, v16
	v_ashrrev_i32_e32 v5, 31, v4
	v_lshl_add_u64 v[4:5], v[4:5], 1, s[8:9]
	v_xor_b32_e32 v12, 16, v165
	global_store_dword v[72:73], v24, off offset:384 sc1
	global_store_dword v[74:75], v23, off offset:384 sc1
	global_store_dword v[76:77], v22, off offset:384 sc1
	global_store_dword v[80:81], v21, off offset:384 sc1
	global_store_dword v[86:87], v20, off offset:384 sc1
	s_waitcnt vmcnt(20)
	v_fmac_f32_e32 v1, v14, v102
	v_mul_f32_e32 v3, v32, v1
	v_cvt_pk_bf16_f32 v3, v3, s0
	global_store_short v[4:5], v3, off sc1
	v_add_u32_e32 v4, v194, v16
	v_ashrrev_i32_e32 v5, 31, v4
	v_lshl_add_u64 v[10:11], v[4:5], 1, s[8:9]
	v_and_b32_e32 v4, 64, v165
	v_xor_b32_e32 v3, 1, v165
	v_add_u32_e32 v7, 64, v4
	v_cmp_lt_i32_e32 vcc, v3, v7
	v_xor_b32_e32 v4, 2, v165
	s_waitcnt vmcnt(19)
	v_fmac_f32_e32 v0, v15, v102
	v_cndmask_b32_e32 v3, v165, v3, vcc
	v_lshlrev_b32_e32 v3, 2, v3
	ds_bpermute_b32 v5, v3, v106
	v_cmp_lt_i32_e32 vcc, v4, v7
	global_store_dword v[90:91], v19, off offset:384 sc1
	global_store_dword v[92:93], v18, off offset:384 sc1
	v_cndmask_b32_e32 v4, v165, v4, vcc
	v_lshlrev_b32_e32 v4, 2, v4
	s_waitcnt lgkmcnt(0)
	v_add_f32_e32 v6, v106, v5
	ds_bpermute_b32 v8, v4, v6
	v_xor_b32_e32 v5, 4, v165
	v_cmp_lt_i32_e32 vcc, v5, v7
	global_store_dword v[94:95], v17, off offset:384 sc1
	global_store_dword v[96:97], v2, off offset:384 sc1
	v_cndmask_b32_e32 v5, v165, v5, vcc
	v_lshlrev_b32_e32 v5, 2, v5
	s_waitcnt lgkmcnt(0)
	v_add_f32_e32 v8, v6, v8
	ds_bpermute_b32 v9, v5, v8
	v_xor_b32_e32 v6, 8, v165
	v_cmp_lt_i32_e32 vcc, v6, v7
	global_store_dword v[98:99], v1, off offset:384 sc1
	global_store_dword v[100:101], v0, off offset:384 sc1
	v_cndmask_b32_e32 v6, v165, v6, vcc
	v_lshlrev_b32_e32 v6, 2, v6
	s_waitcnt lgkmcnt(0)
	v_add_f32_e32 v8, v8, v9
	ds_bpermute_b32 v9, v6, v8
	v_cmp_lt_i32_e32 vcc, v12, v7
	s_waitcnt lgkmcnt(0)
	v_add_f32_e32 v8, v8, v9
	v_cndmask_b32_e32 v7, v165, v12, vcc
	v_lshlrev_b32_e32 v7, 2, v7
	ds_bpermute_b32 v9, v7, v8
	v_mul_f32_e32 v12, v32, v0
	v_cvt_pk_bf16_f32 v12, v12, s0
	global_store_short v[10:11], v12, off sc1
	s_and_saveexec_b64 s[60:61], s[0:1]
	s_cbranch_execz .LBB0_1400
	s_waitcnt lgkmcnt(0)
	v_add_f32_e32 v10, v8, v9
	v_lshl_add_u64 v[8:9], v[70:71], 2, s[58:59]
	global_store_dword v[8:9], v10, off sc1

.LBB0_1569:
	s_add_i32 s58, s66, 0xffffe000
	s_lshr_b32 s58, s58, 12
	s_mulk_i32 s58, 0x1800
	v_mov_b32_e32 v70, s70
	s_add_i32 s58, s58, 0xf000
	ds_read_b64 v[70:71], v70
	s_cmp_gt_i32 s6, 63
	s_cselect_b32 s6, s58, 0xd800
	s_lshl_b64 s[58:59], s[6:7], 2
	s_add_u32 s6, s14, s58
	s_addc_u32 s65, s15, s59
	s_waitcnt lgkmcnt(0)
	v_readfirstlane_b32 s58, v70
	v_readfirstlane_b32 s59, v71
	s_add_u32 s60, s58, 0x3000
	s_addc_u32 s61, s59, 0
	s_lshl_b32 s58, s64, 14
	s_add_i32 s58, s58, 0xe0000
	s_ashr_i32 s59, s58, 31
	s_lshl_b64 s[58:59], s[58:59], 2
	s_add_u32 s58, s10, s58
	s_addc_u32 s59, s11, s59
	s_add_u32 s62, s6, 0x5ba2000
	v_or_b32_e32 v102, s68, v138
	v_add_u32_e32 v70, s66, v139
	s_addc_u32 s63, s65, 0
	v_lshlrev_b32_e32 v188, 10, v70
	v_ashrrev_i32_e32 v103, 31, v102
	s_add_u32 s64, s6, 0x5ba4000
	v_lshlrev_b64 v[72:73], 2, v[102:103]
	v_or_b32_e32 v186, 0x400, v188
	v_or_b32_e32 v185, 0x4400, v188
	v_or_b32_e32 v189, 0x4c00, v188
	v_or_b32_e32 v193, 0x6c00, v188
	s_addc_u32 s65, s65, 0
	v_lshl_add_u64 v[74:75], s[62:63], 0, v[72:73]
	v_add_u32_e32 v132, v188, v102
	v_add_u32_e32 v134, v186, v102
	v_or_b32_e32 v184, 0x800, v188
	v_or_b32_e32 v183, 0xc00, v188
	v_or_b32_e32 v181, 0x2000, v188
	v_or_b32_e32 v179, 0x2400, v188
	v_or_b32_e32 v71, 0x2800, v188
	v_or_b32_e32 v180, 0x2c00, v188
	v_or_b32_e32 v182, 0x4000, v188
	v_add_u32_e32 v112, v185, v102
	v_or_b32_e32 v187, 0x4800, v188
	v_add_u32_e32 v118, v189, v102
	v_or_b32_e32 v190, 0x6000, v188
	v_or_b32_e32 v191, 0x6400, v188
	v_or_b32_e32 v192, 0x6800, v188
	v_add_u32_e32 v128, v193, v102
	global_load_dword v194, v[74:75], off
	global_load_dword v205, v[74:75], off offset:128
	v_lshl_add_u64 v[74:75], s[60:61], 0, v[72:73]
	v_lshl_add_u64 v[72:73], s[64:65], 0, v[72:73]
	v_ashrrev_i32_e32 v135, 31, v134
	v_add_u32_e32 v136, v184, v102
	v_add_u32_e32 v130, v183, v102
	v_add_u32_e32 v122, v181, v102
	v_add_u32_e32 v114, v179, v102
	v_add_u32_e32 v106, v71, v102
	v_add_u32_e32 v108, v180, v102
	v_add_u32_e32 v110, v182, v102
	v_ashrrev_i32_e32 v113, 31, v112
	v_add_u32_e32 v116, v187, v102
	v_ashrrev_i32_e32 v119, 31, v118
	v_add_u32_e32 v120, v190, v102
	v_add_u32_e32 v124, v191, v102
	v_add_u32_e32 v126, v192, v102
	v_ashrrev_i32_e32 v129, 31, v128
	v_ashrrev_i32_e32 v133, 31, v132
	global_load_dword v196, v[72:73], off
	global_load_dword v203, v[72:73], off offset:128
	v_lshl_add_u64 v[88:89], v[134:135], 2, s[12:13]
	v_ashrrev_i32_e32 v137, 31, v136
	v_ashrrev_i32_e32 v131, 31, v130
	v_ashrrev_i32_e32 v123, 31, v122
	v_ashrrev_i32_e32 v115, 31, v114
	v_ashrrev_i32_e32 v107, 31, v106
	v_ashrrev_i32_e32 v109, 31, v108
	v_ashrrev_i32_e32 v111, 31, v110
	v_lshl_add_u64 v[86:87], v[112:113], 2, s[12:13]
	v_ashrrev_i32_e32 v117, 31, v116
	v_lshl_add_u64 v[92:93], v[118:119], 2, s[12:13]
	v_ashrrev_i32_e32 v121, 31, v120
	v_ashrrev_i32_e32 v125, 31, v124
	v_ashrrev_i32_e32 v127, 31, v126
	v_lshl_add_u64 v[100:101], v[128:129], 2, s[12:13]
	v_lshl_add_u64 v[104:105], v[132:133], 2, s[12:13]
	global_load_dword v195, v[74:75], off
	global_load_dword v204, v[74:75], off offset:128
	v_lshl_add_u64 v[84:85], v[136:137], 2, s[12:13]
	v_lshl_add_u64 v[82:83], v[130:131], 2, s[12:13]
	v_lshl_add_u64 v[78:79], v[122:123], 2, s[12:13]
	v_lshl_add_u64 v[72:73], v[114:115], 2, s[12:13]
	v_lshl_add_u64 v[74:75], v[106:107], 2, s[12:13]
	v_lshl_add_u64 v[76:77], v[108:109], 2, s[12:13]
	v_lshl_add_u64 v[80:81], v[110:111], 2, s[12:13]
	global_load_dword v178, v[88:89], off
	global_load_dword v177, v[84:85], off
	global_load_dword v176, v[82:83], off
	global_load_dword v175, v[78:79], off
	global_load_dword v174, v[72:73], off
	global_load_dword v173, v[74:75], off
	global_load_dword v172, v[76:77], off
	global_load_dword v171, v[80:81], off
	v_lshl_add_u64 v[90:91], v[116:117], 2, s[12:13]
	global_load_dword v170, v[86:87], off
	global_load_dword v168, v[90:91], off
	v_lshl_add_u64 v[94:95], v[120:121], 2, s[12:13]
	v_lshl_add_u64 v[96:97], v[124:125], 2, s[12:13]
	v_lshl_add_u64 v[98:99], v[126:127], 2, s[12:13]
	global_load_dword v169, v[92:93], off
	global_load_dword v167, v[94:95], off
	global_load_dword v166, v[96:97], off
	global_load_dword v165, v[98:99], off
	global_load_dword v103, v[100:101], off
	global_load_dword v197, v[104:105], off
	v_lshl_add_u64 v[106:107], v[106:107], 1, s[8:9]
	global_load_dword v202, v[104:105], off offset:128
	global_load_dword v206, v[84:85], off offset:128
	global_load_dword v207, v[78:79], off offset:128
	global_load_dword v208, v[72:73], off offset:128
	global_load_dword v209, v[74:75], off offset:128
	global_load_dword v210, v[80:81], off offset:128
	global_load_dword v211, v[76:77], off offset:128
	global_load_dword v212, v[86:87], off offset:128
	global_load_dword v213, v[82:83], off offset:128
	global_load_dword v214, v[90:91], off offset:128
	global_load_dword v215, v[92:93], off offset:128
	global_load_dword v216, v[94:95], off offset:128
	global_load_dword v217, v[96:97], off offset:128
	global_load_dword v218, v[98:99], off offset:128
	global_load_dword v219, v[100:101], off offset:128
	global_load_dword v220, v[88:89], off offset:128
	s_waitcnt vmcnt(0)
	v_add_f32_e32 v196, 1.0, v196
	v_mul_f32_e32 v195, v195, v196
	v_fmac_f32_e32 v178, v49, v194
	v_fmac_f32_e32 v177, v50, v194
	v_fmac_f32_e32 v176, v51, v194
	v_fmac_f32_e32 v175, v52, v194
	v_fmac_f32_e32 v174, v53, v194
	v_fmac_f32_e32 v173, v54, v194
	v_fmac_f32_e32 v172, v55, v194
	v_fmac_f32_e32 v171, v56, v194
	v_fmac_f32_e32 v170, v57, v194
	v_fmac_f32_e32 v168, v58, v194
	v_fmac_f32_e32 v169, v59, v194
	v_fmac_f32_e32 v167, v60, v194
	v_fmac_f32_e32 v166, v61, v194
	v_fmac_f32_e32 v165, v62, v194
	v_fmac_f32_e32 v103, v63, v194
	v_fmac_f32_e32 v197, v48, v194
	v_mul_f32_e32 v48, v195, v197
	v_cvt_pk_bf16_f32 v58, v48, s0
	v_or_b32_e32 v48, 32, v102
	v_ashrrev_i32_e32 v49, 31, v48
	v_lshlrev_b64 v[52:53], 2, v[48:49]
	global_store_dword v[88:89], v178, off sc1
	global_store_dword v[84:85], v177, off sc1
	global_store_dword v[82:83], v176, off sc1
	global_store_dword v[78:79], v175, off sc1
	global_store_dword v[72:73], v174, off sc1
	global_store_dword v[74:75], v173, off sc1
	global_store_dword v[76:77], v172, off sc1
	global_store_dword v[80:81], v171, off sc1
	global_store_dword v[86:87], v170, off sc1
	global_store_dword v[90:91], v168, off sc1
	global_store_dword v[92:93], v169, off sc1
	global_store_dword v[94:95], v167, off sc1
	global_store_dword v[96:97], v166, off sc1
	global_store_dword v[98:99], v165, off sc1
	global_store_dword v[100:101], v103, off sc1
	global_store_dword v[104:105], v197, off sc1
	v_lshl_add_u64 v[50:51], v[132:133], 1, s[8:9]
	v_lshl_add_u64 v[56:57], s[64:65], 0, v[52:53]
	v_mov_b32_e32 v196, v202
	v_lshl_add_u64 v[54:55], s[60:61], 0, v[52:53]
	v_mov_b32_e32 v132, v203
	v_mov_b32_e32 v133, v204
	v_mul_f32_e32 v49, v195, v178
	global_store_short v[50:51], v58, off sc1
	v_lshl_add_u64 v[50:51], s[62:63], 0, v[52:53]
	v_mov_b32_e32 v194, v205
	v_cvt_pk_bf16_f32 v49, v49, s0
	v_lshl_add_u64 v[50:51], v[134:135], 1, s[8:9]
	global_store_short v[50:51], v49, off sc1
	v_mul_f32_e32 v49, v195, v177
	v_cvt_pk_bf16_f32 v49, v49, s0
	v_lshl_add_u64 v[50:51], v[136:137], 1, s[8:9]
	global_store_short v[50:51], v49, off sc1
	v_mul_f32_e32 v49, v195, v176
	v_cvt_pk_bf16_f32 v49, v49, s0
	v_lshl_add_u64 v[50:51], v[130:131], 1, s[8:9]
	global_store_short v[50:51], v49, off sc1
	v_mul_f32_e32 v49, v195, v175
	v_cvt_pk_bf16_f32 v49, v49, s0
	v_lshl_add_u64 v[50:51], v[122:123], 1, s[8:9]
	global_store_short v[50:51], v49, off sc1
	v_mul_f32_e32 v49, v195, v174
	v_cvt_pk_bf16_f32 v49, v49, s0
	v_lshl_add_u64 v[50:51], v[114:115], 1, s[8:9]
	global_store_short v[50:51], v49, off sc1
	v_mul_f32_e32 v49, v195, v173
	v_mov_b32_e32 v62, v206
	v_mov_b32_e32 v60, v207
	v_mov_b32_e32 v59, v208
	v_mov_b32_e32 v58, v209
	v_mov_b32_e32 v56, v210
	v_mov_b32_e32 v57, v211
	v_mov_b32_e32 v55, v212
	v_mov_b32_e32 v61, v213
	v_mov_b32_e32 v54, v214
	v_mov_b32_e32 v53, v215
	v_mov_b32_e32 v52, v216
	v_mov_b32_e32 v51, v217
	v_mov_b32_e32 v50, v218
	v_cvt_pk_bf16_f32 v63, v49, s0
	v_mov_b32_e32 v49, v219
	v_fmac_f32_e32 v196, v32, v194
	global_store_short v[106:107], v63, off sc1
	v_mov_b32_e32 v63, v220
	v_mul_f32_e32 v106, v195, v172
	v_cvt_pk_bf16_f32 v114, v106, s0
	v_lshl_add_u64 v[106:107], v[108:109], 1, s[8:9]
	global_store_short v[106:107], v114, off sc1
	v_mul_f32_e32 v106, v195, v171
	v_cvt_pk_bf16_f32 v108, v106, s0
	v_lshl_add_u64 v[106:107], v[110:111], 1, s[8:9]
	global_store_short v[106:107], v108, off sc1
	v_mul_f32_e32 v106, v195, v170
	v_cvt_pk_bf16_f32 v108, v106, s0
	v_lshl_add_u64 v[106:107], v[112:113], 1, s[8:9]
	global_store_short v[106:107], v108, off sc1
	v_mul_f32_e32 v106, v195, v168
	v_cvt_pk_bf16_f32 v108, v106, s0
	v_lshl_add_u64 v[106:107], v[116:117], 1, s[8:9]
	global_store_short v[106:107], v108, off sc1
	v_mul_f32_e32 v106, v195, v169
	v_cvt_pk_bf16_f32 v108, v106, s0
	v_lshl_add_u64 v[106:107], v[118:119], 1, s[8:9]
	global_store_short v[106:107], v108, off sc1
	v_mul_f32_e32 v106, v195, v167
	v_cvt_pk_bf16_f32 v108, v106, s0
	v_lshl_add_u64 v[106:107], v[120:121], 1, s[8:9]
	global_store_short v[106:107], v108, off sc1
	v_mul_f32_e32 v106, v195, v166
	v_cvt_pk_bf16_f32 v108, v106, s0
	v_lshl_add_u64 v[106:107], v[124:125], 1, s[8:9]
	global_store_short v[106:107], v108, off sc1
	v_mul_f32_e32 v106, v195, v165
	v_cvt_pk_bf16_f32 v108, v106, s0
	v_lshl_add_u64 v[106:107], v[126:127], 1, s[8:9]
	global_store_short v[106:107], v108, off sc1
	v_mul_f32_e32 v106, v195, v103
	v_cvt_pk_bf16_f32 v108, v106, s0
	v_lshl_add_u64 v[106:107], v[128:129], 1, s[8:9]
	global_store_short v[106:107], v108, off sc1
	v_add_f32_e32 v106, 1.0, v132
	v_mul_f32_e32 v110, v133, v106
	v_add_u32_e32 v106, v188, v48
	v_fmac_f32_e32 v62, v34, v194
	v_fmac_f32_e32 v61, v35, v194
	v_fmac_f32_e32 v60, v36, v194
	v_fmac_f32_e32 v59, v37, v194
	v_fmac_f32_e32 v58, v38, v194
	v_fmac_f32_e32 v57, v39, v194
	v_fmac_f32_e32 v56, v40, v194
	v_fmac_f32_e32 v55, v41, v194
	v_fmac_f32_e32 v54, v42, v194
	v_fmac_f32_e32 v53, v43, v194
	v_fmac_f32_e32 v52, v44, v194
	v_fmac_f32_e32 v51, v45, v194
	v_fmac_f32_e32 v50, v46, v194
	v_fmac_f32_e32 v49, v47, v194
	v_ashrrev_i32_e32 v107, 31, v106
	global_store_dword v[104:105], v196, off offset:128 sc1
	v_mul_f32_e32 v32, v110, v196
	global_store_dword v[84:85], v62, off offset:128 sc1
	global_store_dword v[82:83], v61, off offset:128 sc1
	global_store_dword v[78:79], v60, off offset:128 sc1
	global_store_dword v[72:73], v59, off offset:128 sc1
	global_store_dword v[74:75], v58, off offset:128 sc1
	global_store_dword v[76:77], v57, off offset:128 sc1
	global_store_dword v[80:81], v56, off offset:128 sc1
	global_store_dword v[86:87], v55, off offset:128 sc1
	global_store_dword v[90:91], v54, off offset:128 sc1
	global_store_dword v[92:93], v53, off offset:128 sc1
	global_store_dword v[94:95], v52, off offset:128 sc1
	global_store_dword v[96:97], v51, off offset:128 sc1
	global_store_dword v[98:99], v50, off offset:128 sc1
	global_store_dword v[100:101], v49, off offset:128 sc1
	v_cvt_pk_bf16_f32 v32, v32, s0
	v_lshl_add_u64 v[106:107], v[106:107], 1, s[8:9]
	v_add_u32_e32 v108, v186, v48
	global_load_dword v45, v[88:89], off offset:256
	v_ashrrev_i32_e32 v109, 31, v108
	global_store_short v[106:107], v32, off sc1
	v_mul_f32_e32 v113, v110, v56
	v_cvt_pk_bf16_f32 v113, v113, s0
	v_mul_f32_e32 v106, v196, v196
	s_waitcnt vmcnt(26)
	v_fmac_f32_e32 v63, v33, v194
	v_mul_f32_e32 v32, v110, v63
	v_cvt_pk_bf16_f32 v34, v32, s0
	v_lshl_add_u64 v[32:33], v[108:109], 1, s[8:9]
	global_store_short v[32:33], v34, off sc1
	v_add_u32_e32 v32, v184, v48
	v_ashrrev_i32_e32 v33, 31, v32
	v_mul_f32_e32 v34, v110, v62
	v_cvt_pk_bf16_f32 v34, v34, s0
	v_lshl_add_u64 v[32:33], v[32:33], 1, s[8:9]
	global_store_short v[32:33], v34, off sc1
	v_add_u32_e32 v32, v183, v48
	v_ashrrev_i32_e32 v33, 31, v32
	v_mul_f32_e32 v34, v110, v61
	v_cvt_pk_bf16_f32 v34, v34, s0
	v_lshl_add_u64 v[32:33], v[32:33], 1, s[8:9]
	global_store_short v[32:33], v34, off sc1
	v_add_u32_e32 v32, v181, v48
	v_ashrrev_i32_e32 v33, 31, v32
	v_mul_f32_e32 v34, v110, v60
	v_cvt_pk_bf16_f32 v34, v34, s0
	v_lshl_add_u64 v[32:33], v[32:33], 1, s[8:9]
	global_store_short v[32:33], v34, off sc1
	v_add_u32_e32 v32, v179, v48
	v_ashrrev_i32_e32 v33, 31, v32
	v_mul_f32_e32 v34, v110, v59
	v_cvt_pk_bf16_f32 v42, v34, s0
	v_lshl_add_u64 v[34:35], v[32:33], 1, s[8:9]
	v_or_b32_e32 v32, 64, v102
	v_ashrrev_i32_e32 v33, 31, v32
	v_lshlrev_b64 v[36:37], 2, v[32:33]
	global_store_dword v[88:89], v63, off offset:128 sc1
	v_lshl_add_u64 v[40:41], s[64:65], 0, v[36:37]
	v_lshl_add_u64 v[38:39], s[60:61], 0, v[36:37]
	global_load_dword v107, v[40:41], off
	global_load_dword v111, v[38:39], off
	v_mul_f32_e32 v33, v110, v58
	global_store_short v[34:35], v42, off sc1
	v_lshl_add_u64 v[34:35], s[62:63], 0, v[36:37]
	global_load_dword v112, v[34:35], off
	v_add_u32_e32 v34, v71, v48
	v_ashrrev_i32_e32 v35, 31, v34
	v_cvt_pk_bf16_f32 v33, v33, s0
	v_lshl_add_u64 v[34:35], v[34:35], 1, s[8:9]
	global_store_short v[34:35], v33, off sc1
	v_add_u32_e32 v34, v180, v48
	v_ashrrev_i32_e32 v35, 31, v34
	v_mul_f32_e32 v33, v110, v57
	v_cvt_pk_bf16_f32 v33, v33, s0
	v_lshl_add_u64 v[34:35], v[34:35], 1, s[8:9]
	global_load_dword v38, v[90:91], off offset:256
	global_load_dword v37, v[92:93], off offset:256
	global_load_dword v36, v[94:95], off offset:256
	global_load_dword v114, v[104:105], off offset:256
	global_load_dword v47, v[84:85], off offset:256
	global_load_dword v39, v[86:87], off offset:256
	global_load_dword v46, v[82:83], off offset:256
	global_load_dword v44, v[78:79], off offset:256
	global_load_dword v43, v[72:73], off offset:256
	global_load_dword v42, v[74:75], off offset:256
	global_load_dword v40, v[80:81], off offset:256
	global_load_dword v41, v[76:77], off offset:256
	v_add_u32_e32 v108, v182, v48
	global_store_short v[34:35], v33, off sc1
	global_load_dword v35, v[96:97], off offset:256
	v_ashrrev_i32_e32 v109, 31, v108
	global_load_dword v34, v[98:99], off offset:256
	global_load_dword v33, v[100:101], off offset:256
	v_lshl_add_u64 v[108:109], v[108:109], 1, s[8:9]
	global_store_short v[108:109], v113, off sc1
	v_add_u32_e32 v108, v185, v48
	v_ashrrev_i32_e32 v109, 31, v108
	v_mul_f32_e32 v113, v110, v55
	v_cvt_pk_bf16_f32 v113, v113, s0
	v_lshl_add_u64 v[108:109], v[108:109], 1, s[8:9]
	global_store_short v[108:109], v113, off sc1
	v_add_u32_e32 v108, v187, v48
	v_ashrrev_i32_e32 v109, 31, v108
	v_mul_f32_e32 v113, v110, v54
	v_cvt_pk_bf16_f32 v113, v113, s0
	v_lshl_add_u64 v[108:109], v[108:109], 1, s[8:9]
	global_store_short v[108:109], v113, off sc1
	v_add_u32_e32 v108, v189, v48
	v_ashrrev_i32_e32 v109, 31, v108
	v_mul_f32_e32 v113, v110, v53
	v_cvt_pk_bf16_f32 v113, v113, s0
	v_lshl_add_u64 v[108:109], v[108:109], 1, s[8:9]
	global_store_short v[108:109], v113, off sc1
	v_add_u32_e32 v108, v190, v48
	v_ashrrev_i32_e32 v109, 31, v108
	v_mul_f32_e32 v113, v110, v52
	v_cvt_pk_bf16_f32 v113, v113, s0
	v_lshl_add_u64 v[108:109], v[108:109], 1, s[8:9]
	global_store_short v[108:109], v113, off sc1
	v_add_u32_e32 v108, v191, v48
	v_ashrrev_i32_e32 v109, 31, v108
	v_mul_f32_e32 v113, v110, v51
	v_cvt_pk_bf16_f32 v113, v113, s0
	v_lshl_add_u64 v[108:109], v[108:109], 1, s[8:9]
	global_store_short v[108:109], v113, off sc1
	v_add_u32_e32 v108, v192, v48
	v_ashrrev_i32_e32 v109, 31, v108
	v_mul_f32_e32 v113, v110, v50
	v_cvt_pk_bf16_f32 v113, v113, s0
	v_lshl_add_u64 v[108:109], v[108:109], 1, s[8:9]
	global_store_short v[108:109], v113, off sc1
	v_add_u32_e32 v108, v193, v48
	v_ashrrev_i32_e32 v109, 31, v108
	v_mul_f32_e32 v48, v110, v49
	v_cvt_pk_bf16_f32 v48, v48, s0
	v_lshl_add_u64 v[108:109], v[108:109], 1, s[8:9]
	global_store_short v[108:109], v48, off sc1
	v_add_u32_e32 v108, v188, v32
	v_ashrrev_i32_e32 v109, 31, v108
	s_waitcnt vmcnt(28)
	v_add_f32_e32 v48, 1.0, v107
	s_waitcnt vmcnt(27)
	v_mul_f32_e32 v48, v111, v48
	v_fmac_f32_e32 v106, v197, v197
	s_waitcnt vmcnt(25)
	v_fmac_f32_e32 v45, v17, v112
	global_store_dword v[88:89], v45, off offset:256 sc1
	s_waitcnt vmcnt(24)
	v_fmac_f32_e32 v38, v26, v112
	s_waitcnt vmcnt(23)
	v_fmac_f32_e32 v37, v27, v112
	s_waitcnt vmcnt(22)
	v_fmac_f32_e32 v36, v28, v112
	s_waitcnt vmcnt(21)
	v_fmac_f32_e32 v114, v16, v112
	v_mul_f32_e32 v16, v48, v114
	s_waitcnt vmcnt(20)
	v_fmac_f32_e32 v47, v18, v112
	v_cvt_pk_bf16_f32 v18, v16, s0
	v_lshl_add_u64 v[16:17], v[108:109], 1, s[8:9]
	global_store_short v[16:17], v18, off sc1
	v_add_u32_e32 v16, v186, v32
	v_ashrrev_i32_e32 v17, 31, v16
	v_mul_f32_e32 v18, v48, v45
	v_cvt_pk_bf16_f32 v18, v18, s0
	v_lshl_add_u64 v[16:17], v[16:17], 1, s[8:9]
	global_store_short v[16:17], v18, off sc1
	v_add_u32_e32 v16, v184, v32
	v_ashrrev_i32_e32 v17, 31, v16
	v_mul_f32_e32 v18, v48, v47
	v_cvt_pk_bf16_f32 v18, v18, s0
	v_lshl_add_u64 v[16:17], v[16:17], 1, s[8:9]
	s_waitcnt vmcnt(20)
	v_fmac_f32_e32 v46, v19, v112
	global_store_short v[16:17], v18, off sc1
	v_add_u32_e32 v16, v183, v32
	v_ashrrev_i32_e32 v17, 31, v16
	v_mul_f32_e32 v18, v48, v46
	s_waitcnt vmcnt(20)
	v_fmac_f32_e32 v44, v20, v112
	v_cvt_pk_bf16_f32 v18, v18, s0
	v_lshl_add_u64 v[16:17], v[16:17], 1, s[8:9]
	global_store_short v[16:17], v18, off sc1
	v_mul_f32_e32 v16, v48, v44
	v_cvt_pk_bf16_f32 v26, v16, s0
	v_or_b32_e32 v16, 0x60, v102
	v_add_u32_e32 v18, v181, v32
	v_ashrrev_i32_e32 v17, 31, v16
	s_waitcnt vmcnt(20)
	v_fmac_f32_e32 v43, v21, v112
	s_waitcnt vmcnt(19)
	v_fmac_f32_e32 v42, v22, v112
	s_waitcnt vmcnt(17)
	v_fmac_f32_e32 v41, v23, v112
	v_fmac_f32_e32 v40, v24, v112
	v_fmac_f32_e32 v39, v25, v112
	s_waitcnt vmcnt(15)
	v_fmac_f32_e32 v35, v29, v112
	s_waitcnt vmcnt(14)
	v_fmac_f32_e32 v34, v30, v112
	s_waitcnt vmcnt(13)
	v_fmac_f32_e32 v33, v31, v112
	v_ashrrev_i32_e32 v19, 31, v18
	v_lshlrev_b64 v[20:21], 2, v[16:17]
	global_store_dword v[84:85], v47, off offset:256 sc1
	global_store_dword v[82:83], v46, off offset:256 sc1
	global_store_dword v[78:79], v44, off offset:256 sc1
	global_store_dword v[72:73], v43, off offset:256 sc1
	global_store_dword v[74:75], v42, off offset:256 sc1
	global_store_dword v[76:77], v41, off offset:256 sc1
	global_store_dword v[80:81], v40, off offset:256 sc1
	global_store_dword v[86:87], v39, off offset:256 sc1
	global_store_dword v[90:91], v38, off offset:256 sc1
	global_store_dword v[92:93], v37, off offset:256 sc1
	global_store_dword v[94:95], v36, off offset:256 sc1
	global_store_dword v[96:97], v35, off offset:256 sc1
	global_store_dword v[98:99], v34, off offset:256 sc1
	global_store_dword v[100:101], v33, off offset:256 sc1
	global_store_dword v[104:105], v114, off offset:256 sc1
	v_lshl_add_u64 v[24:25], s[64:65], 0, v[20:21]
	v_lshl_add_u64 v[18:19], v[18:19], 1, s[8:9]
	global_load_dword v29, v[104:105], off offset:384
	v_lshl_add_u64 v[22:23], s[60:61], 0, v[20:21]
	global_load_dword v17, v[24:25], off
	global_load_dword v30, v[22:23], off
	global_load_dword v28, v[88:89], off offset:384
	global_load_dword v27, v[84:85], off offset:384
	v_fmac_f32_e32 v106, v114, v114
	global_store_short v[18:19], v26, off sc1
	v_lshl_add_u64 v[18:19], s[62:63], 0, v[20:21]
	global_load_dword v102, v[18:19], off
	v_add_u32_e32 v18, v179, v32
	v_ashrrev_i32_e32 v19, 31, v18
	v_mul_f32_e32 v20, v48, v43
	v_cvt_pk_bf16_f32 v20, v20, s0
	v_lshl_add_u64 v[18:19], v[18:19], 1, s[8:9]
	global_store_short v[18:19], v20, off sc1
	v_add_u32_e32 v18, v71, v32
	v_ashrrev_i32_e32 v19, 31, v18
	v_mul_f32_e32 v20, v48, v42
	v_cvt_pk_bf16_f32 v20, v20, s0
	v_lshl_add_u64 v[18:19], v[18:19], 1, s[8:9]
	global_store_short v[18:19], v20, off sc1
	v_add_u32_e32 v18, v180, v32
	v_ashrrev_i32_e32 v19, 31, v18
	v_mul_f32_e32 v20, v48, v41
	v_cvt_pk_bf16_f32 v20, v20, s0
	v_lshl_add_u64 v[18:19], v[18:19], 1, s[8:9]
	global_store_short v[18:19], v20, off sc1
	v_add_u32_e32 v18, v182, v32
	v_ashrrev_i32_e32 v19, 31, v18
	v_mul_f32_e32 v20, v48, v40
	v_cvt_pk_bf16_f32 v20, v20, s0
	v_lshl_add_u64 v[18:19], v[18:19], 1, s[8:9]
	global_store_short v[18:19], v20, off sc1
	v_add_u32_e32 v18, v185, v32
	v_ashrrev_i32_e32 v19, 31, v18
	v_mul_f32_e32 v20, v48, v39
	v_cvt_pk_bf16_f32 v20, v20, s0
	v_lshl_add_u64 v[18:19], v[18:19], 1, s[8:9]
	global_store_short v[18:19], v20, off sc1
	v_add_u32_e32 v18, v187, v32
	v_ashrrev_i32_e32 v19, 31, v18
	v_mul_f32_e32 v20, v48, v38
	v_cvt_pk_bf16_f32 v20, v20, s0
	v_lshl_add_u64 v[18:19], v[18:19], 1, s[8:9]
	global_store_short v[18:19], v20, off sc1
	v_add_u32_e32 v18, v189, v32
	v_ashrrev_i32_e32 v19, 31, v18
	v_mul_f32_e32 v20, v48, v37
	v_cvt_pk_bf16_f32 v20, v20, s0
	v_lshl_add_u64 v[18:19], v[18:19], 1, s[8:9]
	global_store_short v[18:19], v20, off sc1
	v_add_u32_e32 v18, v190, v32
	v_ashrrev_i32_e32 v19, 31, v18
	v_mul_f32_e32 v20, v48, v36
	v_cvt_pk_bf16_f32 v20, v20, s0
	v_lshl_add_u64 v[18:19], v[18:19], 1, s[8:9]
	global_store_short v[18:19], v20, off sc1
	v_add_u32_e32 v18, v191, v32
	v_ashrrev_i32_e32 v19, 31, v18
	v_mul_f32_e32 v20, v48, v35
	v_cvt_pk_bf16_f32 v20, v20, s0
	v_lshl_add_u64 v[18:19], v[18:19], 1, s[8:9]
	global_store_short v[18:19], v20, off sc1
	v_add_u32_e32 v18, v192, v32
	v_ashrrev_i32_e32 v19, 31, v18
	v_mul_f32_e32 v20, v48, v34
	v_cvt_pk_bf16_f32 v20, v20, s0
	v_lshl_add_u64 v[18:19], v[18:19], 1, s[8:9]
	global_store_short v[18:19], v20, off sc1
	v_add_u32_e32 v18, v193, v32
	v_ashrrev_i32_e32 v19, 31, v18
	v_mul_f32_e32 v20, v48, v33
	v_cvt_pk_bf16_f32 v20, v20, s0
	v_lshl_add_u64 v[18:19], v[18:19], 1, s[8:9]
	global_store_short v[18:19], v20, off sc1
	global_load_dword v20, v[86:87], off offset:384
	v_add_u32_e32 v18, v188, v16
	global_load_dword v26, v[82:83], off offset:384
	global_load_dword v25, v[78:79], off offset:384
	global_load_dword v24, v[72:73], off offset:384
	global_load_dword v23, v[74:75], off offset:384
	global_load_dword v21, v[80:81], off offset:384
	global_load_dword v22, v[76:77], off offset:384
	s_waitcnt vmcnt(23)
	v_add_f32_e32 v17, 1.0, v17
	s_waitcnt vmcnt(22)
	v_mul_f32_e32 v32, v30, v17
	v_ashrrev_i32_e32 v19, 31, v18
	v_lshl_add_u64 v[18:19], v[18:19], 1, s[8:9]
	v_add_u32_e32 v30, v186, v16
	s_waitcnt vmcnt(18)
	v_fmac_f32_e32 v29, v0, v102
	v_mul_f32_e32 v0, v32, v29
	v_cvt_pk_bf16_f32 v0, v0, s0
	global_store_short v[18:19], v0, off sc1
	global_load_dword v19, v[90:91], off offset:384
	v_ashrrev_i32_e32 v31, 31, v30
	global_load_dword v18, v[92:93], off offset:384
	v_fmac_f32_e32 v28, v1, v102
	v_mul_f32_e32 v0, v32, v28
	v_cvt_pk_bf16_f32 v17, v0, s0
	v_lshl_add_u64 v[0:1], v[30:31], 1, s[8:9]
	global_store_short v[0:1], v17, off sc1
	v_add_u32_e32 v0, v184, v16
	v_fmac_f32_e32 v27, v2, v102
	global_load_dword v17, v[94:95], off offset:384
	v_ashrrev_i32_e32 v1, 31, v0
	v_mul_f32_e32 v2, v32, v27
	v_cvt_pk_bf16_f32 v2, v2, s0
	v_lshl_add_u64 v[0:1], v[0:1], 1, s[8:9]
	global_store_short v[0:1], v2, off sc1
	v_add_u32_e32 v0, v183, v16
	global_load_dword v2, v[96:97], off offset:384
	v_ashrrev_i32_e32 v1, 31, v0
	v_lshl_add_u64 v[0:1], v[0:1], 1, s[8:9]
	v_add_u32_e32 v30, v181, v16
	v_ashrrev_i32_e32 v31, 31, v30
	v_lshl_add_u64 v[30:31], v[30:31], 1, s[8:9]
	v_fmac_f32_e32 v106, v29, v29
	global_store_dword v[104:105], v29, off offset:384 sc1
	global_store_dword v[88:89], v28, off offset:384 sc1
	global_store_dword v[84:85], v27, off offset:384 sc1
	s_waitcnt vmcnt(16)
	v_fmac_f32_e32 v20, v9, v102
	global_store_dword v[86:87], v20, off offset:384 sc1
	s_waitcnt vmcnt(16)
	v_fmac_f32_e32 v26, v3, v102
	v_mul_f32_e32 v3, v32, v26
	v_cvt_pk_bf16_f32 v3, v3, s0
	global_store_short v[0:1], v3, off sc1
	global_load_dword v1, v[98:99], off offset:384
	s_waitcnt vmcnt(17)
	v_fmac_f32_e32 v25, v4, v102
	v_mul_f32_e32 v0, v32, v25
	v_cvt_pk_bf16_f32 v0, v0, s0
	global_store_short v[30:31], v0, off sc1
	global_load_dword v0, v[100:101], off offset:384
	v_add_u32_e32 v30, v179, v16
	s_waitcnt vmcnt(18)
	v_fmac_f32_e32 v24, v5, v102
	v_ashrrev_i32_e32 v31, 31, v30
	v_mul_f32_e32 v3, v32, v24
	v_cvt_pk_bf16_f32 v3, v3, s0
	v_lshl_add_u64 v[4:5], v[30:31], 1, s[8:9]
	global_store_short v[4:5], v3, off sc1
	v_add_u32_e32 v4, v71, v16
	s_waitcnt vmcnt(18)
	v_fmac_f32_e32 v23, v6, v102
	v_ashrrev_i32_e32 v5, 31, v4
	v_mul_f32_e32 v3, v32, v23
	v_cvt_pk_bf16_f32 v3, v3, s0
	v_lshl_add_u64 v[4:5], v[4:5], 1, s[8:9]
	global_store_short v[4:5], v3, off sc1
	v_add_u32_e32 v4, v180, v16
	s_waitcnt vmcnt(17)
	v_fmac_f32_e32 v22, v7, v102
	v_ashrrev_i32_e32 v5, 31, v4
	v_mul_f32_e32 v3, v32, v22
	v_cvt_pk_bf16_f32 v3, v3, s0
	v_lshl_add_u64 v[4:5], v[4:5], 1, s[8:9]
	global_store_short v[4:5], v3, off sc1
	v_add_u32_e32 v4, v182, v16
	v_fmac_f32_e32 v21, v8, v102
	v_ashrrev_i32_e32 v5, 31, v4
	v_mul_f32_e32 v3, v32, v21
	v_cvt_pk_bf16_f32 v3, v3, s0
	v_lshl_add_u64 v[4:5], v[4:5], 1, s[8:9]
	global_store_short v[4:5], v3, off sc1
	v_add_u32_e32 v4, v185, v16
	v_ashrrev_i32_e32 v5, 31, v4
	v_mul_f32_e32 v3, v32, v20
	v_cvt_pk_bf16_f32 v3, v3, s0
	v_lshl_add_u64 v[4:5], v[4:5], 1, s[8:9]
	global_store_short v[4:5], v3, off sc1
	v_add_u32_e32 v4, v187, v16
	s_waitcnt vmcnt(18)
	v_fmac_f32_e32 v19, v10, v102
	v_ashrrev_i32_e32 v5, 31, v4
	v_mul_f32_e32 v3, v32, v19
	v_cvt_pk_bf16_f32 v3, v3, s0
	v_lshl_add_u64 v[4:5], v[4:5], 1, s[8:9]
	global_store_short v[4:5], v3, off sc1
	v_add_u32_e32 v4, v189, v16
	s_waitcnt vmcnt(18)
	v_fmac_f32_e32 v18, v11, v102
	v_ashrrev_i32_e32 v5, 31, v4
	v_mul_f32_e32 v3, v32, v18
	v_cvt_pk_bf16_f32 v3, v3, s0
	v_lshl_add_u64 v[4:5], v[4:5], 1, s[8:9]
	global_store_short v[4:5], v3, off sc1
	v_add_u32_e32 v4, v190, v16
	s_waitcnt vmcnt(17)
	v_fmac_f32_e32 v17, v12, v102
	v_ashrrev_i32_e32 v5, 31, v4
	v_mul_f32_e32 v3, v32, v17
	v_cvt_pk_bf16_f32 v3, v3, s0
	v_lshl_add_u64 v[4:5], v[4:5], 1, s[8:9]
	global_store_short v[4:5], v3, off sc1
	v_add_u32_e32 v4, v191, v16
	s_waitcnt vmcnt(16)
	v_fmac_f32_e32 v2, v13, v102
	v_ashrrev_i32_e32 v5, 31, v4
	v_mul_f32_e32 v3, v32, v2
	v_cvt_pk_bf16_f32 v3, v3, s0
	v_lshl_add_u64 v[4:5], v[4:5], 1, s[8:9]
	global_store_short v[4:5], v3, off sc1
	v_add_u32_e32 v4, v192, v16
	v_ashrrev_i32_e32 v5, 31, v4
	v_lshl_add_u64 v[4:5], v[4:5], 1, s[8:9]
	v_xor_b32_e32 v13, 16, v164
	v_add_u32_e32 v10, v193, v16
	v_ashrrev_i32_e32 v11, 31, v10
	v_lshl_add_u64 v[10:11], v[10:11], 1, s[8:9]
	v_ashrrev_i32_e32 v71, 31, v70
	global_store_dword v[82:83], v26, off offset:384 sc1
	global_store_dword v[78:79], v25, off offset:384 sc1
	global_store_dword v[72:73], v24, off offset:384 sc1
	global_store_dword v[74:75], v23, off offset:384 sc1
	s_waitcnt vmcnt(15)
	v_fmac_f32_e32 v1, v14, v102
	v_mul_f32_e32 v3, v32, v1
	v_cvt_pk_bf16_f32 v3, v3, s0
	global_store_short v[4:5], v3, off sc1
	v_and_b32_e32 v4, 64, v164
	v_xor_b32_e32 v3, 1, v164
	v_add_u32_e32 v7, 64, v4
	v_cmp_lt_i32_e32 vcc, v3, v7
	v_xor_b32_e32 v4, 2, v164
	s_waitcnt vmcnt(14)
	v_fmac_f32_e32 v0, v15, v102
	v_cndmask_b32_e32 v3, v164, v3, vcc
	v_lshlrev_b32_e32 v3, 2, v3
	ds_bpermute_b32 v5, v3, v106
	v_cmp_lt_i32_e32 vcc, v4, v7
	v_mul_f32_e32 v12, v32, v0
	v_cvt_pk_bf16_f32 v12, v12, s0
	v_cndmask_b32_e32 v4, v164, v4, vcc
	v_lshlrev_b32_e32 v4, 2, v4
	s_waitcnt lgkmcnt(0)
	v_add_f32_e32 v6, v106, v5
	ds_bpermute_b32 v8, v4, v6
	v_xor_b32_e32 v5, 4, v164
	v_cmp_lt_i32_e32 vcc, v5, v7
	global_store_dword v[76:77], v22, off offset:384 sc1
	global_store_dword v[80:81], v21, off offset:384 sc1
	v_cndmask_b32_e32 v5, v164, v5, vcc
	v_lshlrev_b32_e32 v5, 2, v5
	s_waitcnt lgkmcnt(0)
	v_add_f32_e32 v8, v6, v8
	ds_bpermute_b32 v9, v5, v8
	v_xor_b32_e32 v6, 8, v164
	v_cmp_lt_i32_e32 vcc, v6, v7
	global_store_dword v[90:91], v19, off offset:384 sc1
	global_store_dword v[92:93], v18, off offset:384 sc1
	v_cndmask_b32_e32 v6, v164, v6, vcc
	v_lshlrev_b32_e32 v6, 2, v6
	s_waitcnt lgkmcnt(0)
	v_add_f32_e32 v8, v8, v9
	ds_bpermute_b32 v9, v6, v8
	v_cmp_lt_i32_e32 vcc, v13, v7
	global_store_dword v[94:95], v17, off offset:384 sc1
	global_store_dword v[96:97], v2, off offset:384 sc1
	v_cndmask_b32_e32 v7, v164, v13, vcc
	v_lshlrev_b32_e32 v7, 2, v7
	s_waitcnt lgkmcnt(0)
	v_add_f32_e32 v8, v8, v9
	ds_bpermute_b32 v9, v7, v8
	global_store_dword v[98:99], v1, off offset:384 sc1
	global_store_dword v[100:101], v0, off offset:384 sc1
	global_store_short v[10:11], v12, off sc1
	s_and_saveexec_b64 s[60:61], s[0:1]
	s_cbranch_execz .LBB0_1571
	s_waitcnt lgkmcnt(0)
	v_add_f32_e32 v10, v8, v9
	v_lshl_add_u64 v[8:9], v[70:71], 2, s[58:59]
	global_store_dword v[8:9], v10, off sc1
